# EpiGates: hoist xc loads above the two preceding av/uv stores (11 sites), vmcnt(2) instead of vmcnt(0)
# speedup vs baseline: 1.0154x; 1.0154x over previous
;   DI bf16_t* xc() const { return (bf16_t*)(ws + OFF_Q1); }
;   DI float* cf() const { return (float*)(ws + OFF_CF); }
; DI float bflo(unsigned u) { return __uint_as_float(u << 16); }
; DI float bfhi(unsigned u) { return __uint_as_float(u & 0xffff0000u); }
;   DI void operator()(const f32x16 (&acc)[2][4], int mbase, int nbase, int l32, int g) const {
;     ...
;     for (int j = 0; j < 4; ++j) {
;       const int ch = ch0 + 8 * j + 4 * g;
;       const f32x4 bx = *(const f32x4*)(p->gx_b + ch), ba = *(const f32x4*)(p->ga_b + ch), cf = *(const f32x4*)(p->cf() + ch);
; #pragma unroll
;       for (int mb = 0; mb < 4; ++mb) {
;         const size_t tok = mbase + 32 * mb + l32;
;         const u32x2 xr = *(const u32x2*)(p->xc() + tok * 1024 + ch);
;         const float xv[4] = {bflo(xr.x), bfhi(xr.x), bflo(xr.y), bfhi(xr.y)};
;         f32x4 av, uv;
; #pragma unroll
;         for (int i = 0; i < 4; ++i) {
;           const float gi = __builtin_amdgcn_rcpf(1.f + __expf(-(acc[0][mb][4 * j + i] + bx[i])));
;           const float gr = __builtin_amdgcn_rcpf(1.f + __expf(-(acc[1][mb][4 * j + i] + ba[i])));
;           const float la = cf[i] * gr;
;           const float x2 = 2.f * la;
;           const float ser = -x2 * (1.f + x2 * (0.5f + x2 * (0.16666667f + x2 * (0.041666668f + x2 * 0.0083333333f))));
;           const float m2 = (x2 > -0.3f) ? ser : (1.f - __expf(x2));
;           av[i] = __expf(la);
;           uv[i] = sqrtf(fmaxf(m2, 0.f)) * gi * xv[i];
.LBB0_312:
	s_lshr_b32 s1, s46, 1
	s_and_b32 s1, s1, 0x60
	v_lshrrev_b32_e32 v160, 3, v186
	v_and_or_b32 v160, v160, 4, s1
	v_or_b32_e32 v172, s0, v160
	v_ashrrev_i32_e32 v173, 31, v172
	v_readlane_b32 s48, v252, 4
	v_lshlrev_b64 v[180:181], 2, v[172:173]
	v_readlane_b32 s50, v252, 6
	v_readlane_b32 s51, v252, 7
	s_ashr_i32 s0, s46, 1
	s_and_b32 s0, s0, 0xffffff80
	v_lshl_add_u64 v[174:175], s[50:51], 0, v[180:181]
	global_load_dwordx4 v[164:167], v[174:175], off
	s_add_i32 s0, s0, s33
	v_and_or_b32 v182, v186, 31, s0
	v_lshl_add_u64 v[168:169], s[10:11], 0, v[180:181]
	v_ashrrev_i32_e32 v183, 31, v182
	global_load_dwordx4 v[168:171], v[168:169], off
	v_lshlrev_b64 v[178:179], 11, v[182:183]
	v_lshl_add_u64 v[178:179], s[8:9], 0, v[178:179]
	v_lshl_add_u64 v[176:177], s[82:83], 0, v[180:181]
	v_lshl_add_u64 v[178:179], v[172:173], 1, v[178:179]
	global_load_dwordx4 v[160:163], v[176:177], off
	global_load_dwordx2 v[186:187], v[178:179], off
	v_readlane_b32 s49, v252, 5
	v_readlane_b32 s52, v252, 8
	v_readlane_b32 s53, v252, 9
	v_readlane_b32 s54, v252, 10
	v_readlane_b32 s55, v252, 11
	v_readlane_b32 s56, v252, 12
	v_readlane_b32 s57, v252, 13
	v_readlane_b32 s58, v252, 14
	v_readlane_b32 s59, v252, 15
	v_readlane_b32 s60, v252, 16
	v_readlane_b32 s61, v252, 17
	v_readlane_b32 s62, v252, 18
	v_readlane_b32 s63, v252, 19
	s_waitcnt vmcnt(3)
	v_add_f32_e32 v112, v112, v164
	v_mul_f32_e32 v112, 0xbfb8aa3b, v112
	v_exp_f32_e32 v112, v112
	s_nop 0
	v_add_f32_e32 v112, 1.0, v112
	v_rcp_f32_e32 v112, v112
	s_waitcnt vmcnt(2)
	v_mul_f32_e32 v112, v168, v112
	v_add_f32_e32 v190, v112, v112
	v_cmp_nlt_f32_e32 vcc, s43, v190
	s_and_saveexec_b64 s[0:1], vcc
	s_xor_b64 s[0:1], exec, s[0:1]
	v_mul_f32_e32 v184, 0x3fb8aa3b, v190
	v_exp_f32_e32 v184, v184
	s_nop 0
	v_sub_f32_e32 v184, 1.0, v184
	s_andn2_saveexec_b64 s[0:1], s[0:1]
	v_fmamk_f32 v184, v190, 0x3c088888, v188
	v_fmaak_f32 v184, v190, v184, 0x3e2aaaab
	v_fma_f32 v184, v190, v184, 0.5
	v_fma_f32 v184, v190, v184, 1.0
	v_mul_f32_e64 v184, v184, -v190
	s_or_b64 exec, exec, s[0:1]
	v_add_f32_e32 v113, v113, v165
	v_mul_f32_e32 v113, 0xbfb8aa3b, v113
	v_exp_f32_e32 v113, v113
	s_nop 0
	v_add_f32_e32 v113, 1.0, v113
	v_rcp_f32_e32 v113, v113
	s_nop 0
	v_mul_f32_e32 v113, v169, v113
	v_add_f32_e32 v191, v113, v113
	v_cmp_nlt_f32_e32 vcc, s43, v191
	s_and_saveexec_b64 s[0:1], vcc
	s_xor_b64 s[0:1], exec, s[0:1]
	v_mul_f32_e32 v190, 0x3fb8aa3b, v191
	v_exp_f32_e32 v190, v190
	s_nop 0
	v_sub_f32_e32 v190, 1.0, v190
	s_andn2_saveexec_b64 s[0:1], s[0:1]
	v_fmamk_f32 v190, v191, 0x3c088888, v188
	v_fmaak_f32 v190, v191, v190, 0x3e2aaaab
	v_fma_f32 v190, v191, v190, 0.5
	v_fma_f32 v190, v191, v190, 1.0
	v_mul_f32_e64 v190, v190, -v191
	s_or_b64 exec, exec, s[0:1]
	v_add_f32_e32 v114, v114, v166
	v_mul_f32_e32 v114, 0xbfb8aa3b, v114
	v_exp_f32_e32 v114, v114
	s_nop 0
	v_add_f32_e32 v114, 1.0, v114
	v_rcp_f32_e32 v114, v114
	s_nop 0
	v_mul_f32_e32 v114, v170, v114
	v_add_f32_e32 v192, v114, v114
	v_cmp_nlt_f32_e32 vcc, s43, v192
	s_and_saveexec_b64 s[0:1], vcc
	s_xor_b64 s[0:1], exec, s[0:1]
	v_mul_f32_e32 v191, 0x3fb8aa3b, v192
	v_exp_f32_e32 v191, v191
	s_nop 0
	v_sub_f32_e32 v191, 1.0, v191
	s_andn2_saveexec_b64 s[0:1], s[0:1]
	v_fmamk_f32 v191, v192, 0x3c088888, v188
	v_fmaak_f32 v191, v192, v191, 0x3e2aaaab
	v_fma_f32 v191, v192, v191, 0.5
	v_fma_f32 v191, v192, v191, 1.0
	v_mul_f32_e64 v191, v191, -v192
	s_or_b64 exec, exec, s[0:1]
	v_add_f32_e32 v115, v115, v167
	v_mul_f32_e32 v115, 0xbfb8aa3b, v115
	v_exp_f32_e32 v115, v115
	s_nop 0
	v_add_f32_e32 v115, 1.0, v115
	v_rcp_f32_e32 v115, v115
	s_nop 0
	v_mul_f32_e32 v115, v171, v115
	v_add_f32_e32 v193, v115, v115
	v_cmp_nlt_f32_e32 vcc, s43, v193
	s_and_saveexec_b64 s[0:1], vcc
	s_xor_b64 s[0:1], exec, s[0:1]
	v_mul_f32_e32 v192, 0x3fb8aa3b, v193
	v_exp_f32_e32 v192, v192
	s_nop 0
	v_sub_f32_e32 v192, 1.0, v192
	s_andn2_saveexec_b64 s[0:1], s[0:1]
	v_fmamk_f32 v192, v193, 0x3c088888, v188
	v_fmaak_f32 v192, v193, v192, 0x3e2aaaab
	v_fma_f32 v192, v193, v192, 0.5
	v_fma_f32 v192, v193, v192, 1.0
	v_mul_f32_e64 v192, v192, -v193
	s_or_b64 exec, exec, s[0:1]
	v_max_f32_e32 v184, v184, v184
	v_max_f32_e32 v184, 0, v184
	v_mul_f32_e32 v193, 0x4f800000, v184
	v_cmp_gt_f32_e32 vcc, s44, v184
	s_waitcnt vmcnt(1)
	v_add_f32_e32 v96, v96, v160
	v_mul_f32_e32 v96, 0xbfb8aa3b, v96
	v_cndmask_b32_e32 v184, v184, v193, vcc
	v_sqrt_f32_e32 v193, v184
	v_exp_f32_e32 v96, v96
	v_add_f32_e32 v97, v97, v161
	v_mul_f32_e32 v97, 0xbfb8aa3b, v97
	v_add_u32_e32 v194, -1, v193
	v_fma_f32 v195, -v194, v193, v184
	v_cmp_ge_f32_e64 s[0:1], 0, v195
	v_add_u32_e32 v195, 1, v193
	v_add_f32_e32 v96, 1.0, v96
	v_cndmask_b32_e64 v194, v193, v194, s[0:1]
	v_fma_f32 v193, -v195, v193, v184
	v_cmp_lt_f32_e64 s[0:1], 0, v193
	v_rcp_f32_e32 v96, v96
	v_exp_f32_e32 v97, v97
	v_cndmask_b32_e64 v193, v194, v195, s[0:1]
	v_mul_f32_e32 v194, 0x37800000, v193
	v_cndmask_b32_e32 v193, v193, v194, vcc
	v_cmp_class_f32_e32 vcc, v184, v189
	v_lshlrev_b64 v[198:199], 10, v[182:183]
	s_waitcnt vmcnt(0)
;   DI bf16_t* xc() const { return (bf16_t*)(ws + OFF_Q1); }
;   DI float* cf() const { return (float*)(ws + OFF_CF); }
; DI float bflo(unsigned u) { return __uint_as_float(u << 16); }
; DI float bfhi(unsigned u) { return __uint_as_float(u & 0xffff0000u); }
;   DI void operator()(const f32x16 (&acc)[2][4], int mbase, int nbase, int l32, int g) const {
;     ...
;         const size_t tok = mbase + 32 * mb + l32;
;         const u32x2 xr = *(const u32x2*)(p->xc() + tok * 1024 + ch);
;         const float xv[4] = {bflo(xr.x), bfhi(xr.x), bflo(xr.y), bfhi(xr.y)};
;         f32x4 av, uv;
; #pragma unroll
;         for (int i = 0; i < 4; ++i) {
;           const float gi = __builtin_amdgcn_rcpf(1.f + __expf(-(acc[0][mb][4 * j + i] + bx[i])));
;           const float gr = __builtin_amdgcn_rcpf(1.f + __expf(-(acc[1][mb][4 * j + i] + ba[i])));
;           const float la = cf[i] * gr;
;           const float x2 = 2.f * la;
;           const float ser = -x2 * (1.f + x2 * (0.5f + x2 * (0.16666667f + x2 * (0.041666668f + x2 * 0.0083333333f))));
;           const float m2 = (x2 > -0.3f) ? ser : (1.f - __expf(x2));
;           av[i] = __expf(la);
;           uv[i] = sqrtf(fmaxf(m2, 0.f)) * gi * xv[i];
;         }
;         *(f32x4*)(p->av() + tok * 1024 + ch) = av;
;         *(f32x4*)(p->uv() + tok * 1024 + ch) = uv;
;       }
	v_lshlrev_b32_e32 v183, 16, v186
	v_cndmask_b32_e32 v184, v193, v184, vcc
	v_mul_f32_e32 v96, v96, v184
	v_mul_f32_e32 v194, v96, v183
	v_add_f32_e32 v96, 1.0, v97
	v_max_f32_e32 v97, v190, v190
	v_max_f32_e32 v97, 0, v97
	v_mul_f32_e32 v183, 0x4f800000, v97
	v_cmp_gt_f32_e32 vcc, s44, v97
	v_and_b32_e32 v184, 0xffff0000, v186
	v_rcp_f32_e32 v96, v96
	v_cndmask_b32_e32 v97, v97, v183, vcc
	v_sqrt_f32_e32 v183, v97
	v_add_f32_e32 v98, v98, v162
	v_mul_f32_e32 v98, 0xbfb8aa3b, v98
	v_exp_f32_e32 v98, v98
	v_add_u32_e32 v186, -1, v183
	v_fma_f32 v190, -v186, v183, v97
	v_cmp_ge_f32_e64 s[0:1], 0, v190
	v_add_u32_e32 v190, 1, v183
	v_add_f32_e32 v99, v99, v163
	v_cndmask_b32_e64 v186, v183, v186, s[0:1]
	v_fma_f32 v183, -v190, v183, v97
	v_cmp_lt_f32_e64 s[0:1], 0, v183
	v_mul_f32_e32 v99, 0xbfb8aa3b, v99
	v_exp_f32_e32 v99, v99
	v_cndmask_b32_e64 v183, v186, v190, s[0:1]
	v_mul_f32_e32 v186, 0x37800000, v183
	v_cndmask_b32_e32 v183, v183, v186, vcc
	v_cmp_class_f32_e32 vcc, v97, v189
	v_mul_f32_e32 v112, 0x3fb8aa3b, v112
	v_mul_f32_e32 v113, 0x3fb8aa3b, v113
	v_cndmask_b32_e32 v97, v183, v97, vcc
	v_mul_f32_e32 v96, v96, v97
	v_max_f32_e32 v97, v191, v191
	v_max_f32_e32 v97, 0, v97
	v_mul_f32_e32 v195, v96, v184
	v_add_f32_e32 v96, 1.0, v98
	v_mul_f32_e32 v98, 0x4f800000, v97
	v_cmp_gt_f32_e32 vcc, s44, v97
	v_rcp_f32_e32 v96, v96
	v_lshlrev_b32_e32 v183, 16, v187
	v_cndmask_b32_e32 v97, v97, v98, vcc
	v_sqrt_f32_e32 v98, v97
	v_mul_f32_e32 v114, 0x3fb8aa3b, v114
	v_mul_f32_e32 v115, 0x3fb8aa3b, v115
	v_exp_f32_e32 v112, v112
	v_add_u32_e32 v184, -1, v98
	v_fma_f32 v186, -v184, v98, v97
	v_cmp_ge_f32_e64 s[0:1], 0, v186
	v_add_u32_e32 v186, 1, v98
	v_exp_f32_e32 v113, v113
	v_cndmask_b32_e64 v184, v98, v184, s[0:1]
	v_fma_f32 v98, -v186, v98, v97
	v_cmp_lt_f32_e64 s[0:1], 0, v98
	v_exp_f32_e32 v114, v114
	v_exp_f32_e32 v115, v115
	v_cndmask_b32_e64 v98, v184, v186, s[0:1]
	v_mul_f32_e32 v184, 0x37800000, v98
	v_cndmask_b32_e32 v98, v98, v184, vcc
	v_cmp_class_f32_e32 vcc, v97, v189
	v_or_b32_e32 v186, 32, v182
	v_add_f32_e32 v80, v80, v164
	v_cndmask_b32_e32 v97, v98, v97, vcc
	v_mul_f32_e32 v96, v96, v97
	v_max_f32_e32 v97, v192, v192
	v_max_f32_e32 v97, 0, v97
	v_mul_f32_e32 v98, 0x4f800000, v97
	v_cmp_gt_f32_e32 vcc, s44, v97
	v_mul_f32_e32 v196, v96, v183
	v_add_f32_e32 v96, 1.0, v99
	v_cndmask_b32_e32 v97, v97, v98, vcc
	v_sqrt_f32_e32 v98, v97
	v_rcp_f32_e32 v96, v96
	v_and_b32_e32 v99, 0xffff0000, v187
	v_ashrrev_i32_e32 v187, 31, v186
	v_add_u32_e32 v183, -1, v98
	v_fma_f32 v184, -v183, v98, v97
	v_cmp_ge_f32_e64 s[0:1], 0, v184
	v_add_u32_e32 v184, 1, v98
	v_mul_f32_e32 v80, 0xbfb8aa3b, v80
	v_cndmask_b32_e64 v183, v98, v183, s[0:1]
	v_fma_f32 v98, -v184, v98, v97
	v_cmp_lt_f32_e64 s[0:1], 0, v98
	v_exp_f32_e32 v80, v80
	s_nop 0
	v_cndmask_b32_e64 v98, v183, v184, s[0:1]
	v_mul_f32_e32 v183, 0x37800000, v98
	v_cndmask_b32_e32 v98, v98, v183, vcc
	v_cmp_class_f32_e32 vcc, v97, v189
	v_add_f32_e32 v80, 1.0, v80
	v_rcp_f32_e32 v80, v80
	v_cndmask_b32_e32 v97, v98, v97, vcc
	v_mul_f32_e32 v96, v96, v97
	v_mul_f32_e32 v197, v96, v99
	v_lshlrev_b64 v[98:99], 2, v[198:199]
	v_lshl_add_u64 v[96:97], s[20:21], 0, v[98:99]
	v_lshl_add_u64 v[96:97], v[96:97], 0, v[180:181]
	v_or_b32_e32 v208, 32, v182
	v_ashrrev_i32_e32 v209, 31, v208
	v_lshlrev_b64 v[208:209], 11, v[208:209]
	v_lshl_add_u64 v[208:209], s[8:9], 0, v[208:209]
	v_lshl_add_u64 v[208:209], v[172:173], 1, v[208:209]
	global_load_dwordx2 v[210:211], v[208:209], off
	global_store_dwordx4 v[96:97], v[112:115], off
	v_lshl_add_u64 v[98:99], s[12:13], 0, v[98:99]
	v_lshl_add_u64 v[98:99], v[98:99], 0, v[180:181]
	v_lshlrev_b64 v[112:113], 11, v[186:187]
	v_lshl_add_u64 v[112:113], s[8:9], 0, v[112:113]
	global_store_dwordx4 v[98:99], v[194:197], off
	v_lshl_add_u64 v[112:113], v[172:173], 1, v[112:113]
	v_mul_f32_e32 v80, v168, v80
	v_add_f32_e32 v184, v80, v80
	v_cmp_nlt_f32_e32 vcc, s43, v184
	s_and_saveexec_b64 s[0:1], vcc
	s_xor_b64 s[0:1], exec, s[0:1]
	v_mul_f32_e32 v183, 0x3fb8aa3b, v184
	v_exp_f32_e32 v183, v183
	s_nop 0
	v_sub_f32_e32 v183, 1.0, v183
	s_andn2_saveexec_b64 s[0:1], s[0:1]
	v_fmamk_f32 v183, v184, 0x3c088888, v188
	v_fmaak_f32 v183, v184, v183, 0x3e2aaaab
	v_fma_f32 v183, v184, v183, 0.5
	v_fma_f32 v183, v184, v183, 1.0
	v_mul_f32_e64 v183, v183, -v184
	s_or_b64 exec, exec, s[0:1]
	v_add_f32_e32 v81, v81, v165
	v_mul_f32_e32 v81, 0xbfb8aa3b, v81
	v_exp_f32_e32 v81, v81
	s_nop 0
	v_add_f32_e32 v81, 1.0, v81
	v_rcp_f32_e32 v81, v81
	s_nop 0
	v_mul_f32_e32 v81, v169, v81
	v_add_f32_e32 v190, v81, v81
	v_cmp_nlt_f32_e32 vcc, s43, v190
	s_and_saveexec_b64 s[0:1], vcc
	s_xor_b64 s[0:1], exec, s[0:1]
	v_mul_f32_e32 v184, 0x3fb8aa3b, v190
	v_exp_f32_e32 v184, v184
	s_nop 0
	v_sub_f32_e32 v184, 1.0, v184
	s_andn2_saveexec_b64 s[0:1], s[0:1]
	v_fmamk_f32 v184, v190, 0x3c088888, v188
	v_fmaak_f32 v184, v190, v184, 0x3e2aaaab
	v_fma_f32 v184, v190, v184, 0.5
	v_fma_f32 v184, v190, v184, 1.0
	v_mul_f32_e64 v184, v184, -v190
	s_or_b64 exec, exec, s[0:1]
	v_add_f32_e32 v82, v82, v166
	v_mul_f32_e32 v82, 0xbfb8aa3b, v82
	v_exp_f32_e32 v82, v82
	s_nop 0
	v_add_f32_e32 v82, 1.0, v82
	v_rcp_f32_e32 v82, v82
	s_nop 0
	v_mul_f32_e32 v82, v170, v82
	v_add_f32_e32 v191, v82, v82
	v_cmp_nlt_f32_e32 vcc, s43, v191
	s_and_saveexec_b64 s[0:1], vcc
	s_xor_b64 s[0:1], exec, s[0:1]
	v_mul_f32_e32 v190, 0x3fb8aa3b, v191
	v_exp_f32_e32 v190, v190
	s_nop 0
	v_sub_f32_e32 v190, 1.0, v190
	s_andn2_saveexec_b64 s[0:1], s[0:1]
	v_fmamk_f32 v190, v191, 0x3c088888, v188
	v_fmaak_f32 v190, v191, v190, 0x3e2aaaab
	v_fma_f32 v190, v191, v190, 0.5
	v_fma_f32 v190, v191, v190, 1.0
	v_mul_f32_e64 v190, v190, -v191
;   DI bf16_t* xc() const { return (bf16_t*)(ws + OFF_Q1); }
;   DI float* cf() const { return (float*)(ws + OFF_CF); }
; DI float bflo(unsigned u) { return __uint_as_float(u << 16); }
; DI float bfhi(unsigned u) { return __uint_as_float(u & 0xffff0000u); }
;   DI void operator()(const f32x16 (&acc)[2][4], int mbase, int nbase, int l32, int g) const {
;     ...
;         const size_t tok = mbase + 32 * mb + l32;
;         const u32x2 xr = *(const u32x2*)(p->xc() + tok * 1024 + ch);
;         const float xv[4] = {bflo(xr.x), bfhi(xr.x), bflo(xr.y), bfhi(xr.y)};
;         f32x4 av, uv;
; #pragma unroll
;         for (int i = 0; i < 4; ++i) {
;           const float gi = __builtin_amdgcn_rcpf(1.f + __expf(-(acc[0][mb][4 * j + i] + bx[i])));
;           const float gr = __builtin_amdgcn_rcpf(1.f + __expf(-(acc[1][mb][4 * j + i] + ba[i])));
;           const float la = cf[i] * gr;
;           const float x2 = 2.f * la;
;           const float ser = -x2 * (1.f + x2 * (0.5f + x2 * (0.16666667f + x2 * (0.041666668f + x2 * 0.0083333333f))));
;           const float m2 = (x2 > -0.3f) ? ser : (1.f - __expf(x2));
;           av[i] = __expf(la);
;           uv[i] = sqrtf(fmaxf(m2, 0.f)) * gi * xv[i];
;         }
;         *(f32x4*)(p->av() + tok * 1024 + ch) = av;
;         *(f32x4*)(p->uv() + tok * 1024 + ch) = uv;
;       }
	s_or_b64 exec, exec, s[0:1]
	v_add_f32_e32 v83, v83, v167
	v_mul_f32_e32 v83, 0xbfb8aa3b, v83
	v_exp_f32_e32 v83, v83
	s_nop 0
	v_add_f32_e32 v83, 1.0, v83
	v_rcp_f32_e32 v83, v83
	s_nop 0
	v_mul_f32_e32 v83, v171, v83
	v_add_f32_e32 v192, v83, v83
	v_cmp_nlt_f32_e32 vcc, s43, v192
	s_and_saveexec_b64 s[0:1], vcc
	s_xor_b64 s[0:1], exec, s[0:1]
	v_mul_f32_e32 v191, 0x3fb8aa3b, v192
	v_exp_f32_e32 v191, v191
	s_nop 0
	v_sub_f32_e32 v191, 1.0, v191
	s_andn2_saveexec_b64 s[0:1], s[0:1]
	v_fmamk_f32 v191, v192, 0x3c088888, v188
	v_fmaak_f32 v191, v192, v191, 0x3e2aaaab
	v_fma_f32 v191, v192, v191, 0.5
	v_fma_f32 v191, v192, v191, 1.0
	v_mul_f32_e64 v191, v191, -v192
	s_or_b64 exec, exec, s[0:1]
	v_max_f32_e32 v183, v183, v183
	v_max_f32_e32 v183, 0, v183
	v_mul_f32_e32 v193, 0x4f800000, v183
	v_cmp_gt_f32_e32 vcc, s44, v183
	v_add_f32_e32 v64, v64, v160
	v_mul_f32_e32 v64, 0xbfb8aa3b, v64
	v_cndmask_b32_e32 v183, v183, v193, vcc
	v_sqrt_f32_e32 v193, v183
	v_exp_f32_e32 v64, v64
	v_add_f32_e32 v65, v65, v161
	v_mul_f32_e32 v65, 0xbfb8aa3b, v65
	v_add_u32_e32 v194, -1, v193
	v_fma_f32 v195, -v194, v193, v183
	v_cmp_ge_f32_e64 s[0:1], 0, v195
	v_add_u32_e32 v195, 1, v193
	v_add_f32_e32 v64, 1.0, v64
	v_cndmask_b32_e64 v194, v193, v194, s[0:1]
	v_fma_f32 v193, -v195, v193, v183
	v_cmp_lt_f32_e64 s[0:1], 0, v193
	v_rcp_f32_e32 v64, v64
	v_exp_f32_e32 v65, v65
	v_cndmask_b32_e64 v193, v194, v195, s[0:1]
	v_mul_f32_e32 v194, 0x37800000, v193
	v_cndmask_b32_e32 v193, v193, v194, vcc
	v_cmp_class_f32_e32 vcc, v183, v189
	s_waitcnt vmcnt(2)
	v_mov_b32_e32 v114, v210
	v_mov_b32_e32 v115, v211
	v_lshlrev_b32_e32 v192, 16, v114
	v_add_f32_e32 v66, v66, v162
	v_cndmask_b32_e32 v183, v193, v183, vcc
	v_mul_f32_e32 v64, v64, v183
	v_mul_f32_e32 v192, v64, v192
	v_add_f32_e32 v64, 1.0, v65
	v_max_f32_e32 v65, v184, v184
	v_max_f32_e32 v65, 0, v65
	v_mul_f32_e32 v183, 0x4f800000, v65
	v_cmp_gt_f32_e32 vcc, s44, v65
	v_rcp_f32_e32 v64, v64
	v_mul_f32_e32 v66, 0xbfb8aa3b, v66
	v_cndmask_b32_e32 v65, v65, v183, vcc
	v_sqrt_f32_e32 v183, v65
	v_exp_f32_e32 v66, v66
	v_and_b32_e32 v114, 0xffff0000, v114
	v_add_f32_e32 v67, v67, v163
	v_add_u32_e32 v184, -1, v183
	v_fma_f32 v193, -v184, v183, v65
	v_cmp_ge_f32_e64 s[0:1], 0, v193
	v_add_u32_e32 v193, 1, v183
	v_mul_f32_e32 v67, 0xbfb8aa3b, v67
	v_cndmask_b32_e64 v184, v183, v184, s[0:1]
	v_fma_f32 v183, -v193, v183, v65
	v_cmp_lt_f32_e64 s[0:1], 0, v183
	v_exp_f32_e32 v67, v67
	v_mul_f32_e32 v80, 0x3fb8aa3b, v80
	v_cndmask_b32_e64 v183, v184, v193, s[0:1]
	v_mul_f32_e32 v184, 0x37800000, v183
	v_cndmask_b32_e32 v183, v183, v184, vcc
	v_cmp_class_f32_e32 vcc, v65, v189
	v_mul_f32_e32 v81, 0x3fb8aa3b, v81
	v_mul_f32_e32 v82, 0x3fb8aa3b, v82
	v_cndmask_b32_e32 v65, v183, v65, vcc
	v_mul_f32_e32 v64, v64, v65
	v_max_f32_e32 v65, v190, v190
	v_max_f32_e32 v65, 0, v65
	v_mul_f32_e32 v193, v64, v114
	v_add_f32_e32 v64, 1.0, v66
	v_mul_f32_e32 v66, 0x4f800000, v65
	v_cmp_gt_f32_e32 vcc, s44, v65
	v_rcp_f32_e32 v64, v64
	v_lshlrev_b32_e32 v114, 16, v115
	v_cndmask_b32_e32 v65, v65, v66, vcc
	v_sqrt_f32_e32 v66, v65
	v_mul_f32_e32 v83, 0x3fb8aa3b, v83
	v_lshlrev_b64 v[186:187], 10, v[186:187]
	v_exp_f32_e32 v80, v80
	v_add_u32_e32 v183, -1, v66
	v_fma_f32 v184, -v183, v66, v65
	v_cmp_ge_f32_e64 s[0:1], 0, v184
	v_add_u32_e32 v184, 1, v66
	v_exp_f32_e32 v81, v81
	v_cndmask_b32_e64 v183, v66, v183, s[0:1]
	v_fma_f32 v66, -v184, v66, v65
	v_cmp_lt_f32_e64 s[0:1], 0, v66
	v_exp_f32_e32 v82, v82
	v_exp_f32_e32 v83, v83
	v_cndmask_b32_e64 v66, v183, v184, s[0:1]
	v_mul_f32_e32 v183, 0x37800000, v66
	v_cndmask_b32_e32 v66, v66, v183, vcc
	v_cmp_class_f32_e32 vcc, v65, v189
	v_add_f32_e32 v48, v48, v164
	v_mul_f32_e32 v48, 0xbfb8aa3b, v48
	v_cndmask_b32_e32 v65, v66, v65, vcc
	v_mul_f32_e32 v64, v64, v65
	v_max_f32_e32 v65, v191, v191
	v_max_f32_e32 v65, 0, v65
	v_mul_f32_e32 v66, 0x4f800000, v65
	v_cmp_gt_f32_e32 vcc, s44, v65
	v_mul_f32_e32 v194, v64, v114
	v_add_f32_e32 v64, 1.0, v67
	v_cndmask_b32_e32 v65, v65, v66, vcc
	v_sqrt_f32_e32 v66, v65
	v_and_b32_e32 v67, 0xffff0000, v115
	v_rcp_f32_e32 v64, v64
	v_exp_f32_e32 v48, v48
	v_add_u32_e32 v114, -1, v66
	v_fma_f32 v115, -v114, v66, v65
	v_cmp_ge_f32_e64 s[0:1], 0, v115
	v_add_u32_e32 v115, 1, v66
	v_add_f32_e32 v48, 1.0, v48
	v_cndmask_b32_e64 v114, v66, v114, s[0:1]
	v_fma_f32 v66, -v115, v66, v65
	v_cmp_lt_f32_e64 s[0:1], 0, v66
	v_rcp_f32_e32 v48, v48
	s_nop 0
	v_cndmask_b32_e64 v66, v114, v115, s[0:1]
	v_mul_f32_e32 v114, 0x37800000, v66
	v_cndmask_b32_e32 v66, v66, v114, vcc
	v_cmp_class_f32_e32 vcc, v65, v189
	v_or_b32_e32 v114, 64, v182
	v_ashrrev_i32_e32 v115, 31, v114
	v_cndmask_b32_e32 v65, v66, v65, vcc
	v_mul_f32_e32 v64, v64, v65
	v_mul_f32_e32 v195, v64, v67
	v_lshlrev_b64 v[66:67], 2, v[186:187]
	v_lshl_add_u64 v[64:65], s[20:21], 0, v[66:67]
	v_lshl_add_u64 v[64:65], v[64:65], 0, v[180:181]
	v_or_b32_e32 v208, 64, v182
	v_ashrrev_i32_e32 v209, 31, v208
	v_lshlrev_b64 v[208:209], 11, v[208:209]
	v_lshl_add_u64 v[208:209], s[8:9], 0, v[208:209]
	v_lshl_add_u64 v[208:209], v[172:173], 1, v[208:209]
	global_load_dwordx2 v[210:211], v[208:209], off
	global_store_dwordx4 v[64:65], v[80:83], off
	v_lshl_add_u64 v[66:67], s[12:13], 0, v[66:67]
	v_lshl_add_u64 v[66:67], v[66:67], 0, v[180:181]
	v_lshlrev_b64 v[80:81], 11, v[114:115]
	v_lshl_add_u64 v[80:81], s[8:9], 0, v[80:81]
	global_store_dwordx4 v[66:67], v[192:195], off
	v_lshl_add_u64 v[80:81], v[172:173], 1, v[80:81]
	v_mul_f32_e32 v48, v168, v48
	v_add_f32_e32 v184, v48, v48
	v_cmp_nlt_f32_e32 vcc, s43, v184
	s_and_saveexec_b64 s[0:1], vcc
	s_xor_b64 s[0:1], exec, s[0:1]
	v_mul_f32_e32 v183, 0x3fb8aa3b, v184
;   DI bf16_t* xc() const { return (bf16_t*)(ws + OFF_Q1); }
;   DI float* cf() const { return (float*)(ws + OFF_CF); }
; DI float bflo(unsigned u) { return __uint_as_float(u << 16); }
; DI float bfhi(unsigned u) { return __uint_as_float(u & 0xffff0000u); }
;   DI void operator()(const f32x16 (&acc)[2][4], int mbase, int nbase, int l32, int g) const {
;     ...
;         const size_t tok = mbase + 32 * mb + l32;
;         const u32x2 xr = *(const u32x2*)(p->xc() + tok * 1024 + ch);
;         const float xv[4] = {bflo(xr.x), bfhi(xr.x), bflo(xr.y), bfhi(xr.y)};
;         f32x4 av, uv;
; #pragma unroll
;         for (int i = 0; i < 4; ++i) {
;           const float gi = __builtin_amdgcn_rcpf(1.f + __expf(-(acc[0][mb][4 * j + i] + bx[i])));
;           const float gr = __builtin_amdgcn_rcpf(1.f + __expf(-(acc[1][mb][4 * j + i] + ba[i])));
;           const float la = cf[i] * gr;
;           const float x2 = 2.f * la;
;           const float ser = -x2 * (1.f + x2 * (0.5f + x2 * (0.16666667f + x2 * (0.041666668f + x2 * 0.0083333333f))));
;           const float m2 = (x2 > -0.3f) ? ser : (1.f - __expf(x2));
;           av[i] = __expf(la);
;           uv[i] = sqrtf(fmaxf(m2, 0.f)) * gi * xv[i];
	v_exp_f32_e32 v183, v183
	s_nop 0
	v_sub_f32_e32 v183, 1.0, v183
	s_andn2_saveexec_b64 s[0:1], s[0:1]
	v_fmamk_f32 v183, v184, 0x3c088888, v188
	v_fmaak_f32 v183, v184, v183, 0x3e2aaaab
	v_fma_f32 v183, v184, v183, 0.5
	v_fma_f32 v183, v184, v183, 1.0
	v_mul_f32_e64 v183, v183, -v184
	s_or_b64 exec, exec, s[0:1]
	v_add_f32_e32 v49, v49, v165
	v_mul_f32_e32 v49, 0xbfb8aa3b, v49
	v_exp_f32_e32 v49, v49
	s_nop 0
	v_add_f32_e32 v49, 1.0, v49
	v_rcp_f32_e32 v49, v49
	s_nop 0
	v_mul_f32_e32 v49, v169, v49
	v_add_f32_e32 v186, v49, v49
	v_cmp_nlt_f32_e32 vcc, s43, v186
	s_and_saveexec_b64 s[0:1], vcc
	s_xor_b64 s[0:1], exec, s[0:1]
	v_mul_f32_e32 v184, 0x3fb8aa3b, v186
	v_exp_f32_e32 v184, v184
	s_nop 0
	v_sub_f32_e32 v184, 1.0, v184
	s_andn2_saveexec_b64 s[0:1], s[0:1]
	v_fmamk_f32 v184, v186, 0x3c088888, v188
	v_fmaak_f32 v184, v186, v184, 0x3e2aaaab
	v_fma_f32 v184, v186, v184, 0.5
	v_fma_f32 v184, v186, v184, 1.0
	v_mul_f32_e64 v184, v184, -v186
	s_or_b64 exec, exec, s[0:1]
	v_add_f32_e32 v50, v50, v166
	v_mul_f32_e32 v50, 0xbfb8aa3b, v50
	v_exp_f32_e32 v50, v50
	s_nop 0
	v_add_f32_e32 v50, 1.0, v50
	v_rcp_f32_e32 v50, v50
	s_nop 0
	v_mul_f32_e32 v50, v170, v50
	v_add_f32_e32 v187, v50, v50
	v_cmp_nlt_f32_e32 vcc, s43, v187
	s_and_saveexec_b64 s[0:1], vcc
	s_xor_b64 s[0:1], exec, s[0:1]
	v_mul_f32_e32 v186, 0x3fb8aa3b, v187
	v_exp_f32_e32 v186, v186
	s_nop 0
	v_sub_f32_e32 v186, 1.0, v186
	s_andn2_saveexec_b64 s[0:1], s[0:1]
	v_fmamk_f32 v186, v187, 0x3c088888, v188
	v_fmaak_f32 v186, v187, v186, 0x3e2aaaab
	v_fma_f32 v186, v187, v186, 0.5
	v_fma_f32 v186, v187, v186, 1.0
	v_mul_f32_e64 v186, v186, -v187
	s_or_b64 exec, exec, s[0:1]
	v_add_f32_e32 v51, v51, v167
	v_mul_f32_e32 v51, 0xbfb8aa3b, v51
	v_exp_f32_e32 v51, v51
	s_nop 0
	v_add_f32_e32 v51, 1.0, v51
	v_rcp_f32_e32 v51, v51
	s_nop 0
	v_mul_f32_e32 v51, v171, v51
	v_add_f32_e32 v190, v51, v51
	v_cmp_nlt_f32_e32 vcc, s43, v190
	s_and_saveexec_b64 s[0:1], vcc
	s_xor_b64 s[0:1], exec, s[0:1]
	v_mul_f32_e32 v187, 0x3fb8aa3b, v190
	v_exp_f32_e32 v187, v187
	s_nop 0
	v_sub_f32_e32 v187, 1.0, v187
	s_andn2_saveexec_b64 s[0:1], s[0:1]
	v_fmamk_f32 v187, v190, 0x3c088888, v188
	v_fmaak_f32 v187, v190, v187, 0x3e2aaaab
	v_fma_f32 v187, v190, v187, 0.5
	v_fma_f32 v187, v190, v187, 1.0
	v_mul_f32_e64 v187, v187, -v190
	s_or_b64 exec, exec, s[0:1]
	v_max_f32_e32 v183, v183, v183
	v_add_f32_e32 v32, v32, v160
	v_max_f32_e32 v183, 0, v183
	v_mul_f32_e32 v32, 0xbfb8aa3b, v32
	v_mul_f32_e32 v191, 0x4f800000, v183
	v_cmp_gt_f32_e32 vcc, s44, v183
	v_exp_f32_e32 v32, v32
	v_add_f32_e32 v33, v33, v161
	v_cndmask_b32_e32 v183, v183, v191, vcc
	v_sqrt_f32_e32 v191, v183
	v_add_f32_e32 v32, 1.0, v32
	v_rcp_f32_e32 v192, v32
	v_mul_f32_e32 v32, 0x3fb8aa3b, v48
	v_add_u32_e32 v48, -1, v191
	v_fma_f32 v193, -v48, v191, v183
	v_cmp_ge_f32_e64 s[0:1], 0, v193
	v_add_u32_e32 v193, 1, v191
	v_mul_f32_e32 v33, 0xbfb8aa3b, v33
	v_cndmask_b32_e64 v48, v191, v48, s[0:1]
	v_fma_f32 v191, -v193, v191, v183
	v_cmp_lt_f32_e64 s[0:1], 0, v191
	v_exp_f32_e32 v33, v33
	s_waitcnt vmcnt(2)
	v_mov_b32_e32 v82, v210
	v_mov_b32_e32 v83, v211
	v_lshlrev_b32_e32 v190, 16, v82
	v_cndmask_b32_e64 v48, v48, v193, s[0:1]
	v_mul_f32_e32 v191, 0x37800000, v48
	v_cndmask_b32_e32 v48, v48, v191, vcc
	v_cmp_class_f32_e32 vcc, v183, v189
	v_add_f32_e32 v33, 1.0, v33
	v_add_f32_e32 v34, v34, v162
	v_cndmask_b32_e32 v48, v48, v183, vcc
	v_mul_f32_e32 v48, v192, v48
	v_mul_f32_e32 v190, v48, v190
	v_rcp_f32_e32 v48, v33
	v_max_f32_e32 v33, v184, v184
	v_max_f32_e32 v33, 0, v33
	v_mul_f32_e32 v183, 0x4f800000, v33
	v_cmp_gt_f32_e32 vcc, s44, v33
	v_mul_f32_e32 v34, 0xbfb8aa3b, v34
	v_exp_f32_e32 v34, v34
	v_cndmask_b32_e32 v183, v33, v183, vcc
	v_sqrt_f32_e32 v184, v183
	v_mul_f32_e32 v33, 0x3fb8aa3b, v49
	v_and_b32_e32 v82, 0xffff0000, v82
	v_add_f32_e32 v34, 1.0, v34
	v_add_u32_e32 v49, -1, v184
	v_fma_f32 v191, -v49, v184, v183
	v_cmp_ge_f32_e64 s[0:1], 0, v191
	v_add_u32_e32 v191, 1, v184
	v_add_f32_e32 v35, v35, v163
	v_cndmask_b32_e64 v49, v184, v49, s[0:1]
	v_fma_f32 v184, -v191, v184, v183
	v_cmp_lt_f32_e64 s[0:1], 0, v184
	v_mul_f32_e32 v35, 0xbfb8aa3b, v35
	v_exp_f32_e32 v35, v35
	v_cndmask_b32_e64 v49, v49, v191, s[0:1]
	v_mul_f32_e32 v184, 0x37800000, v49
	v_cndmask_b32_e32 v49, v49, v184, vcc
	v_cmp_class_f32_e32 vcc, v183, v189
	v_add_f32_e32 v35, 1.0, v35
	v_lshlrev_b64 v[114:115], 10, v[114:115]
	v_cndmask_b32_e32 v49, v49, v183, vcc
	v_mul_f32_e32 v48, v48, v49
	v_mul_f32_e32 v191, v48, v82
	v_rcp_f32_e32 v48, v34
	v_max_f32_e32 v34, v186, v186
	v_max_f32_e32 v34, 0, v34
	v_mul_f32_e32 v49, 0x4f800000, v34
	v_cmp_gt_f32_e32 vcc, s44, v34
	v_lshlrev_b32_e32 v183, 16, v83
	v_exp_f32_e32 v32, v32
	v_cndmask_b32_e32 v49, v34, v49, vcc
	v_sqrt_f32_e32 v82, v49
	v_mul_f32_e32 v34, 0x3fb8aa3b, v50
	v_exp_f32_e32 v33, v33
	v_exp_f32_e32 v34, v34
	v_add_u32_e32 v50, -1, v82
	v_fma_f32 v184, -v50, v82, v49
	v_cmp_ge_f32_e64 s[0:1], 0, v184
	v_add_u32_e32 v184, 1, v82
	v_add_f32_e32 v16, v16, v164
	v_cndmask_b32_e64 v50, v82, v50, s[0:1]
	v_fma_f32 v82, -v184, v82, v49
	v_cmp_lt_f32_e64 s[0:1], 0, v82
	v_mul_f32_e32 v16, 0xbfb8aa3b, v16
	v_exp_f32_e32 v16, v16
	v_cndmask_b32_e64 v50, v50, v184, s[0:1]
	v_mul_f32_e32 v82, 0x37800000, v50
	v_cndmask_b32_e32 v50, v50, v82, vcc
	v_cmp_class_f32_e32 vcc, v49, v189
	v_and_b32_e32 v82, 0xffff0000, v83
	v_add_f32_e32 v16, 1.0, v16
	v_cndmask_b32_e32 v49, v50, v49, vcc
	v_mul_f32_e32 v48, v48, v49
	v_mul_f32_e32 v192, v48, v183
	v_rcp_f32_e32 v48, v35
	v_max_f32_e32 v35, v187, v187
	v_max_f32_e32 v35, 0, v35
	v_mul_f32_e32 v49, 0x4f800000, v35
	v_cmp_gt_f32_e32 vcc, s44, v35
	v_rcp_f32_e32 v16, v16
;   DI bf16_t* xc() const { return (bf16_t*)(ws + OFF_Q1); }
;   DI float* cf() const { return (float*)(ws + OFF_CF); }
; DI float bflo(unsigned u) { return __uint_as_float(u << 16); }
; DI float bfhi(unsigned u) { return __uint_as_float(u & 0xffff0000u); }
;   DI void operator()(const f32x16 (&acc)[2][4], int mbase, int nbase, int l32, int g) const {
;     ...
;         const size_t tok = mbase + 32 * mb + l32;
;         const u32x2 xr = *(const u32x2*)(p->xc() + tok * 1024 + ch);
;         const float xv[4] = {bflo(xr.x), bfhi(xr.x), bflo(xr.y), bfhi(xr.y)};
;         f32x4 av, uv;
; #pragma unroll
;         for (int i = 0; i < 4; ++i) {
;           const float gi = __builtin_amdgcn_rcpf(1.f + __expf(-(acc[0][mb][4 * j + i] + bx[i])));
;           const float gr = __builtin_amdgcn_rcpf(1.f + __expf(-(acc[1][mb][4 * j + i] + ba[i])));
;           const float la = cf[i] * gr;
;           const float x2 = 2.f * la;
;           const float ser = -x2 * (1.f + x2 * (0.5f + x2 * (0.16666667f + x2 * (0.041666668f + x2 * 0.0083333333f))));
;           const float m2 = (x2 > -0.3f) ? ser : (1.f - __expf(x2));
;           av[i] = __expf(la);
;           uv[i] = sqrtf(fmaxf(m2, 0.f)) * gi * xv[i];
;         }
;         *(f32x4*)(p->av() + tok * 1024 + ch) = av;
;         *(f32x4*)(p->uv() + tok * 1024 + ch) = uv;
;       }
	s_nop 0
	v_cndmask_b32_e32 v49, v35, v49, vcc
	v_sqrt_f32_e32 v50, v49
	v_mul_f32_e32 v35, 0x3fb8aa3b, v51
	v_exp_f32_e32 v35, v35
	v_mul_f32_e32 v16, v168, v16
	v_add_u32_e32 v51, -1, v50
	v_fma_f32 v83, -v51, v50, v49
	v_cmp_ge_f32_e64 s[0:1], 0, v83
	v_add_u32_e32 v83, 1, v50
	s_nop 0
	v_cndmask_b32_e64 v51, v50, v51, s[0:1]
	v_fma_f32 v50, -v83, v50, v49
	v_cmp_lt_f32_e64 s[0:1], 0, v50
	s_nop 1
	v_cndmask_b32_e64 v50, v51, v83, s[0:1]
	v_mul_f32_e32 v51, 0x37800000, v50
	v_cndmask_b32_e32 v50, v50, v51, vcc
	v_cmp_class_f32_e32 vcc, v49, v189
	s_nop 1
	v_cndmask_b32_e32 v49, v50, v49, vcc
	v_mul_f32_e32 v48, v48, v49
	v_lshlrev_b64 v[50:51], 2, v[114:115]
	v_mul_f32_e32 v193, v48, v82
	v_lshl_add_u64 v[48:49], s[20:21], 0, v[50:51]
	v_lshl_add_u64 v[48:49], v[48:49], 0, v[180:181]
	v_or_b32_e32 v208, 0x60, v182
	v_ashrrev_i32_e32 v209, 31, v208
	v_lshlrev_b64 v[208:209], 11, v[208:209]
	v_lshl_add_u64 v[208:209], s[8:9], 0, v[208:209]
	v_lshl_add_u64 v[208:209], v[172:173], 1, v[208:209]
	global_load_dwordx2 v[210:211], v[208:209], off
	global_store_dwordx4 v[48:49], v[32:35], off
	v_add_f32_e32 v115, v16, v16
	v_cmp_nlt_f32_e32 vcc, s43, v115
	v_or_b32_e32 v34, 0x60, v182
	v_lshl_add_u64 v[32:33], s[12:13], 0, v[50:51]
	v_ashrrev_i32_e32 v35, 31, v34
	v_lshl_add_u64 v[50:51], v[32:33], 0, v[180:181]
	v_lshlrev_b64 v[32:33], 11, v[34:35]
	v_lshl_add_u64 v[32:33], s[8:9], 0, v[32:33]
	global_store_dwordx4 v[50:51], v[190:193], off
	v_lshl_add_u64 v[82:83], v[172:173], 1, v[32:33]
	s_and_saveexec_b64 s[0:1], vcc
	s_xor_b64 s[0:1], exec, s[0:1]
	v_mul_f32_e32 v114, 0x3fb8aa3b, v115
	v_exp_f32_e32 v114, v114
	s_nop 0
	v_sub_f32_e32 v114, 1.0, v114
	s_andn2_saveexec_b64 s[0:1], s[0:1]
	v_fmamk_f32 v114, v115, 0x3c088888, v188
	v_fmaak_f32 v114, v115, v114, 0x3e2aaaab
	v_fma_f32 v114, v115, v114, 0.5
	v_fma_f32 v114, v115, v114, 1.0
	v_mul_f32_e64 v114, v114, -v115
	s_or_b64 exec, exec, s[0:1]
	v_add_f32_e32 v17, v17, v165
	v_mul_f32_e32 v17, 0xbfb8aa3b, v17
	v_exp_f32_e32 v17, v17
	s_nop 0
	v_add_f32_e32 v17, 1.0, v17
	v_rcp_f32_e32 v17, v17
	s_nop 0
	v_mul_f32_e32 v17, v169, v17
	v_add_f32_e32 v164, v17, v17
	v_cmp_nlt_f32_e32 vcc, s43, v164
	s_and_saveexec_b64 s[0:1], vcc
	s_xor_b64 s[0:1], exec, s[0:1]
	v_mul_f32_e32 v115, 0x3fb8aa3b, v164
	v_exp_f32_e32 v115, v115
	s_nop 0
	v_sub_f32_e32 v115, 1.0, v115
	s_andn2_saveexec_b64 s[0:1], s[0:1]
	v_fmamk_f32 v115, v164, 0x3c088888, v188
	v_fmaak_f32 v115, v164, v115, 0x3e2aaaab
	v_fma_f32 v115, v164, v115, 0.5
	v_fma_f32 v115, v164, v115, 1.0
	v_mul_f32_e64 v115, v115, -v164
	s_or_b64 exec, exec, s[0:1]
	v_add_f32_e32 v18, v18, v166
	v_mul_f32_e32 v18, 0xbfb8aa3b, v18
	v_exp_f32_e32 v18, v18
	s_nop 0
	v_add_f32_e32 v18, 1.0, v18
	v_rcp_f32_e32 v18, v18
	s_nop 0
	v_mul_f32_e32 v18, v170, v18
	v_add_f32_e32 v165, v18, v18
	v_cmp_nlt_f32_e32 vcc, s43, v165
	s_and_saveexec_b64 s[0:1], vcc
	s_xor_b64 s[0:1], exec, s[0:1]
	v_mul_f32_e32 v164, 0x3fb8aa3b, v165
	v_exp_f32_e32 v164, v164
	s_nop 0
	v_sub_f32_e32 v164, 1.0, v164
	s_andn2_saveexec_b64 s[0:1], s[0:1]
	v_fmamk_f32 v164, v165, 0x3c088888, v188
	v_fmaak_f32 v164, v165, v164, 0x3e2aaaab
	v_fma_f32 v164, v165, v164, 0.5
	v_fma_f32 v164, v165, v164, 1.0
	v_mul_f32_e64 v164, v164, -v165
	s_or_b64 exec, exec, s[0:1]
	v_add_f32_e32 v19, v19, v167
	v_mul_f32_e32 v19, 0xbfb8aa3b, v19
	v_exp_f32_e32 v19, v19
	s_nop 0
	v_add_f32_e32 v19, 1.0, v19
	v_rcp_f32_e32 v19, v19
	s_nop 0
	v_mul_f32_e32 v19, v171, v19
	v_add_f32_e32 v166, v19, v19
	v_cmp_nlt_f32_e32 vcc, s43, v166
	s_and_saveexec_b64 s[0:1], vcc
	s_xor_b64 s[0:1], exec, s[0:1]
	v_mul_f32_e32 v165, 0x3fb8aa3b, v166
	v_exp_f32_e32 v165, v165
	s_nop 0
	v_sub_f32_e32 v165, 1.0, v165
	s_andn2_saveexec_b64 s[0:1], s[0:1]
	v_fmamk_f32 v165, v166, 0x3c088888, v188
	v_fmaak_f32 v165, v166, v165, 0x3e2aaaab
	v_fma_f32 v165, v166, v165, 0.5
	v_fma_f32 v165, v166, v165, 1.0
	v_mul_f32_e64 v165, v165, -v166
	s_or_b64 exec, exec, s[0:1]
	v_max_f32_e32 v114, v114, v114
	v_add_f32_e32 v0, v0, v160
	v_max_f32_e32 v114, 0, v114
	v_mul_f32_e32 v0, 0xbfb8aa3b, v0
	v_mul_f32_e32 v166, 0x4f800000, v114
	v_cmp_gt_f32_e32 vcc, s44, v114
	v_exp_f32_e32 v0, v0
	v_add_f32_e32 v1, v1, v161
	v_cndmask_b32_e32 v114, v114, v166, vcc
	v_sqrt_f32_e32 v166, v114
	v_add_f32_e32 v0, 1.0, v0
	v_rcp_f32_e32 v167, v0
	v_mul_f32_e32 v0, 0x3fb8aa3b, v16
	v_add_u32_e32 v16, -1, v166
	v_fma_f32 v168, -v16, v166, v114
	v_cmp_ge_f32_e64 s[0:1], 0, v168
	v_add_u32_e32 v168, 1, v166
	v_mul_f32_e32 v1, 0xbfb8aa3b, v1
	v_cndmask_b32_e64 v16, v166, v16, s[0:1]
	v_fma_f32 v166, -v168, v166, v114
	v_exp_f32_e32 v1, v1
	v_cmp_lt_f32_e64 s[0:1], 0, v166
	s_waitcnt vmcnt(2)
;   DI bf16_t* xc() const { return (bf16_t*)(ws + OFF_Q1); }
;   DI float* cf() const { return (float*)(ws + OFF_CF); }
; DI float bflo(unsigned u) { return __uint_as_float(u << 16); }
; DI float bfhi(unsigned u) { return __uint_as_float(u & 0xffff0000u); }
;   DI void operator()(const f32x16 (&acc)[2][4], int mbase, int nbase, int l32, int g) const {
;     ...
;       const f32x4 bx = *(const f32x4*)(p->gx_b + ch), ba = *(const f32x4*)(p->ga_b + ch), cf = *(const f32x4*)(p->cf() + ch);
; #pragma unroll
;       for (int mb = 0; mb < 4; ++mb) {
;         const size_t tok = mbase + 32 * mb + l32;
;         const u32x2 xr = *(const u32x2*)(p->xc() + tok * 1024 + ch);
;         const float xv[4] = {bflo(xr.x), bfhi(xr.x), bflo(xr.y), bfhi(xr.y)};
;         f32x4 av, uv;
; #pragma unroll
;         for (int i = 0; i < 4; ++i) {
;           const float gi = __builtin_amdgcn_rcpf(1.f + __expf(-(acc[0][mb][4 * j + i] + bx[i])));
;           const float gr = __builtin_amdgcn_rcpf(1.f + __expf(-(acc[1][mb][4 * j + i] + ba[i])));
;           const float la = cf[i] * gr;
;           const float x2 = 2.f * la;
;           const float ser = -x2 * (1.f + x2 * (0.5f + x2 * (0.16666667f + x2 * (0.041666668f + x2 * 0.0083333333f))));
;           const float m2 = (x2 > -0.3f) ? ser : (1.f - __expf(x2));
;           av[i] = __expf(la);
;           uv[i] = sqrtf(fmaxf(m2, 0.f)) * gi * xv[i];
	v_mov_b32_e32 v32, v210
	v_mov_b32_e32 v33, v211
	v_lshlrev_b32_e32 v160, 16, v32
	v_add_f32_e32 v2, v2, v162
	v_cndmask_b32_e64 v16, v16, v168, s[0:1]
	v_mul_f32_e32 v166, 0x37800000, v16
	v_cndmask_b32_e32 v16, v16, v166, vcc
	v_cmp_class_f32_e32 vcc, v114, v189
	v_add_f32_e32 v1, 1.0, v1
	v_mul_f32_e32 v2, 0xbfb8aa3b, v2
	v_cndmask_b32_e32 v16, v16, v114, vcc
	v_rcp_f32_e32 v114, v1
	v_max_f32_e32 v1, v115, v115
	v_max_f32_e32 v1, 0, v1
	v_mul_f32_e32 v115, 0x4f800000, v1
	v_cmp_gt_f32_e32 vcc, s44, v1
	v_mul_f32_e32 v16, v167, v16
	v_mul_f32_e32 v16, v16, v160
	v_cndmask_b32_e32 v115, v1, v115, vcc
	v_sqrt_f32_e32 v160, v115
	v_mul_f32_e32 v1, 0x3fb8aa3b, v17
	v_exp_f32_e32 v2, v2
	v_and_b32_e32 v32, 0xffff0000, v32
	v_add_u32_e32 v17, -1, v160
	v_fma_f32 v161, -v17, v160, v115
	v_cmp_ge_f32_e64 s[0:1], 0, v161
	v_add_u32_e32 v161, 1, v160
	v_add_f32_e32 v2, 1.0, v2
	v_cndmask_b32_e64 v17, v160, v17, s[0:1]
	v_fma_f32 v160, -v161, v160, v115
	v_cmp_lt_f32_e64 s[0:1], 0, v160
	v_add_f32_e32 v3, v3, v163
	v_mul_f32_e32 v3, 0xbfb8aa3b, v3
	v_cndmask_b32_e64 v17, v17, v161, s[0:1]
	v_mul_f32_e32 v160, 0x37800000, v17
	v_cndmask_b32_e32 v17, v17, v160, vcc
	v_cmp_class_f32_e32 vcc, v115, v189
	v_exp_f32_e32 v3, v3
	v_lshlrev_b32_e32 v160, 16, v33
	v_cndmask_b32_e32 v17, v17, v115, vcc
	v_mul_f32_e32 v17, v114, v17
	v_mul_f32_e32 v17, v17, v32
	v_rcp_f32_e32 v32, v2
	v_max_f32_e32 v2, v164, v164
	v_max_f32_e32 v2, 0, v2
	v_mul_f32_e32 v114, 0x4f800000, v2
	v_cmp_gt_f32_e32 vcc, s44, v2
	v_add_f32_e32 v3, 1.0, v3
	v_lshlrev_b64 v[34:35], 10, v[34:35]
	v_cndmask_b32_e32 v114, v2, v114, vcc
	v_sqrt_f32_e32 v115, v114
	v_mul_f32_e32 v2, 0x3fb8aa3b, v18
	v_exp_f32_e32 v0, v0
	v_exp_f32_e32 v1, v1
	v_add_u32_e32 v18, -1, v115
	v_fma_f32 v161, -v18, v115, v114
	v_cmp_ge_f32_e64 s[0:1], 0, v161
	v_add_u32_e32 v161, 1, v115
	v_exp_f32_e32 v2, v2
	v_cndmask_b32_e64 v18, v115, v18, s[0:1]
	v_fma_f32 v115, -v161, v115, v114
	v_cmp_lt_f32_e64 s[0:1], 0, v115
	v_and_b32_e32 v33, 0xffff0000, v33
	s_nop 0
	v_cndmask_b32_e64 v18, v18, v161, s[0:1]
	v_mul_f32_e32 v115, 0x37800000, v18
	v_cndmask_b32_e32 v18, v18, v115, vcc
	v_cmp_class_f32_e32 vcc, v114, v189
	s_nop 1
	v_cndmask_b32_e32 v18, v18, v114, vcc
	v_mul_f32_e32 v18, v32, v18
	v_rcp_f32_e32 v32, v3
	v_max_f32_e32 v3, v165, v165
	v_max_f32_e32 v3, 0, v3
	v_mul_f32_e32 v114, 0x4f800000, v3
	v_cmp_gt_f32_e32 vcc, s44, v3
	v_mul_f32_e32 v18, v18, v160
	s_nop 0
	v_cndmask_b32_e32 v114, v3, v114, vcc
	v_sqrt_f32_e32 v115, v114
	v_mul_f32_e32 v3, 0x3fb8aa3b, v19
	v_exp_f32_e32 v3, v3
	v_add_u32_e32 v19, -1, v115
	v_fma_f32 v160, -v19, v115, v114
	v_cmp_ge_f32_e64 s[0:1], 0, v160
	v_add_u32_e32 v160, 1, v115
	s_nop 0
	v_cndmask_b32_e64 v19, v115, v19, s[0:1]
	v_fma_f32 v115, -v160, v115, v114
	v_cmp_lt_f32_e64 s[0:1], 0, v115
	s_nop 1
	v_cndmask_b32_e64 v19, v19, v160, s[0:1]
	v_mul_f32_e32 v115, 0x37800000, v19
	v_cndmask_b32_e32 v19, v19, v115, vcc
	v_cmp_class_f32_e32 vcc, v114, v189
	s_nop 1
	v_cndmask_b32_e32 v19, v19, v114, vcc
	v_mul_f32_e32 v19, v32, v19
	v_mul_f32_e32 v19, v19, v33
	v_lshlrev_b64 v[32:33], 2, v[34:35]
	v_lshl_add_u64 v[34:35], s[20:21], 0, v[32:33]
	v_lshl_add_u64 v[114:115], v[34:35], 0, v[180:181]
	global_store_dwordx4 v[114:115], v[0:3], off
	s_nop 1
	v_lshl_add_u64 v[0:1], s[12:13], 0, v[32:33]
	v_lshl_add_u64 v[160:161], v[0:1], 0, v[180:181]
	global_store_dwordx4 v[160:161], v[16:19], off
	global_load_dwordx4 v[32:35], v[174:175], off offset:32
	v_or_b32_e32 v0, 8, v172
	v_ashrrev_i32_e32 v1, 31, v0
	v_lshl_add_u64 v[0:1], v[0:1], 2, s[10:11]
	global_load_dwordx4 v[16:19], v[0:1], off
	s_nop 0
	global_load_dwordx4 v[0:3], v[176:177], off offset:32
	global_load_dwordx2 v[162:163], v[178:179], off offset:16
	s_waitcnt vmcnt(3)
	v_add_f32_e32 v116, v116, v32
	v_mul_f32_e32 v116, 0xbfb8aa3b, v116
	v_exp_f32_e32 v116, v116
	s_nop 0
	v_add_f32_e32 v116, 1.0, v116
	v_rcp_f32_e32 v116, v116
	s_waitcnt vmcnt(2)
	v_mul_f32_e32 v116, v16, v116
	v_add_f32_e32 v165, v116, v116
	v_cmp_nlt_f32_e32 vcc, s43, v165
	s_and_saveexec_b64 s[0:1], vcc
	s_xor_b64 s[0:1], exec, s[0:1]
	v_mul_f32_e32 v164, 0x3fb8aa3b, v165
	v_exp_f32_e32 v164, v164
	s_nop 0
	v_sub_f32_e32 v164, 1.0, v164
	s_andn2_saveexec_b64 s[0:1], s[0:1]
	v_fmamk_f32 v164, v165, 0x3c088888, v188
	v_fmaak_f32 v164, v165, v164, 0x3e2aaaab
	v_fma_f32 v164, v165, v164, 0.5
	v_fma_f32 v164, v165, v164, 1.0
	v_mul_f32_e64 v164, v164, -v165
	s_or_b64 exec, exec, s[0:1]
	v_add_f32_e32 v117, v117, v33
	v_mul_f32_e32 v117, 0xbfb8aa3b, v117
	v_exp_f32_e32 v117, v117
	s_nop 0
	v_add_f32_e32 v117, 1.0, v117
	v_rcp_f32_e32 v117, v117
	s_nop 0
	v_mul_f32_e32 v117, v17, v117
	v_add_f32_e32 v166, v117, v117
	v_cmp_nlt_f32_e32 vcc, s43, v166
	s_and_saveexec_b64 s[0:1], vcc
	s_xor_b64 s[0:1], exec, s[0:1]
	v_mul_f32_e32 v165, 0x3fb8aa3b, v166
	v_exp_f32_e32 v165, v165
	s_nop 0
	v_sub_f32_e32 v165, 1.0, v165
	s_andn2_saveexec_b64 s[0:1], s[0:1]
	v_fmamk_f32 v165, v166, 0x3c088888, v188
	v_fmaak_f32 v165, v166, v165, 0x3e2aaaab
	v_fma_f32 v165, v166, v165, 0.5
	v_fma_f32 v165, v166, v165, 1.0
	v_mul_f32_e64 v165, v165, -v166
	s_or_b64 exec, exec, s[0:1]
	v_add_f32_e32 v118, v118, v34
	v_mul_f32_e32 v118, 0xbfb8aa3b, v118
	v_exp_f32_e32 v118, v118
	s_nop 0
	v_add_f32_e32 v118, 1.0, v118
	v_rcp_f32_e32 v118, v118
	s_nop 0
	v_mul_f32_e32 v118, v18, v118
	v_add_f32_e32 v167, v118, v118
	v_cmp_nlt_f32_e32 vcc, s43, v167
	s_and_saveexec_b64 s[0:1], vcc
	s_xor_b64 s[0:1], exec, s[0:1]
	v_mul_f32_e32 v166, 0x3fb8aa3b, v167
	v_exp_f32_e32 v166, v166
	s_nop 0
	v_sub_f32_e32 v166, 1.0, v166
	s_andn2_saveexec_b64 s[0:1], s[0:1]
	v_fmamk_f32 v166, v167, 0x3c088888, v188
	v_fmaak_f32 v166, v167, v166, 0x3e2aaaab
	v_fma_f32 v166, v167, v166, 0.5
	v_fma_f32 v166, v167, v166, 1.0
	v_mul_f32_e64 v166, v166, -v167
	s_or_b64 exec, exec, s[0:1]
	v_add_f32_e32 v119, v119, v35
	v_mul_f32_e32 v119, 0xbfb8aa3b, v119
	v_exp_f32_e32 v119, v119
	s_nop 0
	v_add_f32_e32 v119, 1.0, v119
	v_rcp_f32_e32 v119, v119
	s_nop 0
	v_mul_f32_e32 v119, v19, v119
	v_add_f32_e32 v168, v119, v119
	v_cmp_nlt_f32_e32 vcc, s43, v168
	s_and_saveexec_b64 s[0:1], vcc
	s_xor_b64 s[0:1], exec, s[0:1]
	v_mul_f32_e32 v167, 0x3fb8aa3b, v168
	v_exp_f32_e32 v167, v167
	s_nop 0
	v_sub_f32_e32 v167, 1.0, v167
	s_andn2_saveexec_b64 s[0:1], s[0:1]
	v_fmamk_f32 v167, v168, 0x3c088888, v188
	v_fmaak_f32 v167, v168, v167, 0x3e2aaaab
	v_fma_f32 v167, v168, v167, 0.5
	v_fma_f32 v167, v168, v167, 1.0
	v_mul_f32_e64 v167, v167, -v168
	s_or_b64 exec, exec, s[0:1]
	v_max_f32_e32 v164, v164, v164
	s_waitcnt vmcnt(1)
;   DI bf16_t* xc() const { return (bf16_t*)(ws + OFF_Q1); }
;   DI float* cf() const { return (float*)(ws + OFF_CF); }
; DI float bflo(unsigned u) { return __uint_as_float(u << 16); }
; DI float bfhi(unsigned u) { return __uint_as_float(u & 0xffff0000u); }
;   DI void operator()(const f32x16 (&acc)[2][4], int mbase, int nbase, int l32, int g) const {
;     ...
;         const size_t tok = mbase + 32 * mb + l32;
;         const u32x2 xr = *(const u32x2*)(p->xc() + tok * 1024 + ch);
;         const float xv[4] = {bflo(xr.x), bfhi(xr.x), bflo(xr.y), bfhi(xr.y)};
;         f32x4 av, uv;
; #pragma unroll
;         for (int i = 0; i < 4; ++i) {
;           const float gi = __builtin_amdgcn_rcpf(1.f + __expf(-(acc[0][mb][4 * j + i] + bx[i])));
;           const float gr = __builtin_amdgcn_rcpf(1.f + __expf(-(acc[1][mb][4 * j + i] + ba[i])));
;           const float la = cf[i] * gr;
;           const float x2 = 2.f * la;
;           const float ser = -x2 * (1.f + x2 * (0.5f + x2 * (0.16666667f + x2 * (0.041666668f + x2 * 0.0083333333f))));
;           const float m2 = (x2 > -0.3f) ? ser : (1.f - __expf(x2));
;           av[i] = __expf(la);
;           uv[i] = sqrtf(fmaxf(m2, 0.f)) * gi * xv[i];
;         }
;         *(f32x4*)(p->av() + tok * 1024 + ch) = av;
;         *(f32x4*)(p->uv() + tok * 1024 + ch) = uv;
;       }
	v_add_f32_e32 v100, v100, v0
	v_max_f32_e32 v164, 0, v164
	v_mul_f32_e32 v100, 0xbfb8aa3b, v100
	v_mul_f32_e32 v169, 0x4f800000, v164
	v_cmp_gt_f32_e32 vcc, s44, v164
	v_exp_f32_e32 v100, v100
	v_add_f32_e32 v101, v101, v1
	v_cndmask_b32_e32 v164, v164, v169, vcc
	v_sqrt_f32_e32 v169, v164
	v_add_f32_e32 v100, 1.0, v100
	v_rcp_f32_e32 v170, v100
	v_mul_f32_e32 v100, 0x3fb8aa3b, v116
	v_add_u32_e32 v116, -1, v169
	v_fma_f32 v171, -v116, v169, v164
	v_cmp_ge_f32_e64 s[0:1], 0, v171
	v_add_u32_e32 v171, 1, v169
	v_mul_f32_e32 v101, 0xbfb8aa3b, v101
	v_cndmask_b32_e64 v116, v169, v116, s[0:1]
	v_fma_f32 v169, -v171, v169, v164
	v_exp_f32_e32 v101, v101
	v_cmp_lt_f32_e64 s[0:1], 0, v169
	s_waitcnt vmcnt(0)
	v_lshlrev_b32_e32 v168, 16, v162
	v_add_f32_e32 v102, v102, v2
	v_cndmask_b32_e64 v116, v116, v171, s[0:1]
	v_mul_f32_e32 v169, 0x37800000, v116
	v_cndmask_b32_e32 v116, v116, v169, vcc
	v_cmp_class_f32_e32 vcc, v164, v189
	v_add_f32_e32 v101, 1.0, v101
	v_mul_f32_e32 v102, 0xbfb8aa3b, v102
	v_cndmask_b32_e32 v116, v116, v164, vcc
	v_rcp_f32_e32 v164, v101
	v_max_f32_e32 v101, v165, v165
	v_max_f32_e32 v101, 0, v101
	v_mul_f32_e32 v165, 0x4f800000, v101
	v_cmp_gt_f32_e32 vcc, s44, v101
	v_mul_f32_e32 v116, v170, v116
	v_mul_f32_e32 v116, v116, v168
	v_cndmask_b32_e32 v165, v101, v165, vcc
	v_sqrt_f32_e32 v168, v165
	v_mul_f32_e32 v101, 0x3fb8aa3b, v117
	v_exp_f32_e32 v102, v102
	v_and_b32_e32 v162, 0xffff0000, v162
	v_add_u32_e32 v117, -1, v168
	v_fma_f32 v169, -v117, v168, v165
	v_cmp_ge_f32_e64 s[0:1], 0, v169
	v_add_u32_e32 v169, 1, v168
	v_add_f32_e32 v102, 1.0, v102
	v_cndmask_b32_e64 v117, v168, v117, s[0:1]
	v_fma_f32 v168, -v169, v168, v165
	v_cmp_lt_f32_e64 s[0:1], 0, v168
	v_add_f32_e32 v103, v103, v3
	v_mul_f32_e32 v103, 0xbfb8aa3b, v103
	v_cndmask_b32_e64 v117, v117, v169, s[0:1]
	v_mul_f32_e32 v168, 0x37800000, v117
	v_cndmask_b32_e32 v117, v117, v168, vcc
	v_cmp_class_f32_e32 vcc, v165, v189
	v_exp_f32_e32 v103, v103
	v_exp_f32_e32 v100, v100
	v_cndmask_b32_e32 v117, v117, v165, vcc
	v_mul_f32_e32 v117, v164, v117
	v_mul_f32_e32 v117, v117, v162
	v_rcp_f32_e32 v162, v102
	v_max_f32_e32 v102, v166, v166
	v_max_f32_e32 v102, 0, v102
	v_mul_f32_e32 v164, 0x4f800000, v102
	v_cmp_gt_f32_e32 vcc, s44, v102
	v_add_f32_e32 v103, 1.0, v103
	v_lshlrev_b32_e32 v166, 16, v163
	v_cndmask_b32_e32 v164, v102, v164, vcc
	v_sqrt_f32_e32 v165, v164
	v_mul_f32_e32 v102, 0x3fb8aa3b, v118
	v_exp_f32_e32 v101, v101
	v_exp_f32_e32 v102, v102
	v_add_u32_e32 v118, -1, v165
	v_fma_f32 v168, -v118, v165, v164
	v_cmp_ge_f32_e64 s[0:1], 0, v168
	v_add_u32_e32 v168, 1, v165
	v_and_b32_e32 v163, 0xffff0000, v163
	v_cndmask_b32_e64 v118, v165, v118, s[0:1]
	v_fma_f32 v165, -v168, v165, v164
	v_cmp_lt_f32_e64 s[0:1], 0, v165
	v_add_f32_e32 v84, v84, v32
	v_mul_f32_e32 v84, 0xbfb8aa3b, v84
	v_cndmask_b32_e64 v118, v118, v168, s[0:1]
	v_mul_f32_e32 v165, 0x37800000, v118
	v_cndmask_b32_e32 v118, v118, v165, vcc
	v_cmp_class_f32_e32 vcc, v164, v189
	v_exp_f32_e32 v84, v84
	s_nop 0
	v_cndmask_b32_e32 v118, v118, v164, vcc
	v_mul_f32_e32 v118, v162, v118
	v_rcp_f32_e32 v162, v103
	v_max_f32_e32 v103, v167, v167
	v_max_f32_e32 v103, 0, v103
	v_mul_f32_e32 v164, 0x4f800000, v103
	v_cmp_gt_f32_e32 vcc, s44, v103
	v_mul_f32_e32 v118, v118, v166
	v_add_f32_e32 v84, 1.0, v84
	v_cndmask_b32_e32 v164, v103, v164, vcc
	v_sqrt_f32_e32 v165, v164
	v_mul_f32_e32 v103, 0x3fb8aa3b, v119
	v_exp_f32_e32 v103, v103
	v_rcp_f32_e32 v84, v84
	v_add_u32_e32 v119, -1, v165
	v_fma_f32 v166, -v119, v165, v164
	v_cmp_ge_f32_e64 s[0:1], 0, v166
	v_add_u32_e32 v166, 1, v165
	v_mul_f32_e32 v84, v16, v84
	v_cndmask_b32_e64 v119, v165, v119, s[0:1]
	v_fma_f32 v165, -v166, v165, v164
	v_cmp_lt_f32_e64 s[0:1], 0, v165
	s_nop 1
	v_cndmask_b32_e64 v119, v119, v166, s[0:1]
	v_mul_f32_e32 v165, 0x37800000, v119
	v_cndmask_b32_e32 v119, v119, v165, vcc
	v_cmp_class_f32_e32 vcc, v164, v189
	s_nop 1
	v_cndmask_b32_e32 v119, v119, v164, vcc
	v_mul_f32_e32 v119, v162, v119
	v_mul_f32_e32 v119, v119, v163
	global_load_dwordx2 v[210:211], v[112:113], off offset:16
	global_store_dwordx4 v[96:97], v[100:103], off offset:32
	global_store_dwordx4 v[98:99], v[116:119], off offset:32
	v_add_f32_e32 v103, v84, v84
	v_cmp_nlt_f32_e32 vcc, s43, v103
	s_and_saveexec_b64 s[0:1], vcc
	s_xor_b64 s[0:1], exec, s[0:1]
	v_mul_f32_e32 v102, 0x3fb8aa3b, v103
	v_exp_f32_e32 v102, v102
	s_nop 0
	v_sub_f32_e32 v102, 1.0, v102
	s_andn2_saveexec_b64 s[0:1], s[0:1]
	v_fmamk_f32 v102, v103, 0x3c088888, v188
	v_fmaak_f32 v102, v103, v102, 0x3e2aaaab
	v_fma_f32 v102, v103, v102, 0.5
	v_fma_f32 v102, v103, v102, 1.0
	v_mul_f32_e64 v102, v102, -v103
	s_or_b64 exec, exec, s[0:1]
	v_add_f32_e32 v85, v85, v33
	v_mul_f32_e32 v85, 0xbfb8aa3b, v85
	v_exp_f32_e32 v85, v85
	s_nop 0
	v_add_f32_e32 v85, 1.0, v85
	v_rcp_f32_e32 v85, v85
	s_nop 0
	v_mul_f32_e32 v85, v17, v85
	v_add_f32_e32 v116, v85, v85
	v_cmp_nlt_f32_e32 vcc, s43, v116
	s_and_saveexec_b64 s[0:1], vcc
	s_xor_b64 s[0:1], exec, s[0:1]
	v_mul_f32_e32 v103, 0x3fb8aa3b, v116
	v_exp_f32_e32 v103, v103
	s_nop 0
	v_sub_f32_e32 v103, 1.0, v103
	s_andn2_saveexec_b64 s[0:1], s[0:1]
	v_fmamk_f32 v103, v116, 0x3c088888, v188
	v_fmaak_f32 v103, v116, v103, 0x3e2aaaab
	v_fma_f32 v103, v116, v103, 0.5
	v_fma_f32 v103, v116, v103, 1.0
	v_mul_f32_e64 v103, v103, -v116
	s_or_b64 exec, exec, s[0:1]
	v_add_f32_e32 v86, v86, v34
	v_mul_f32_e32 v86, 0xbfb8aa3b, v86
	v_exp_f32_e32 v86, v86
	s_nop 0
	v_add_f32_e32 v86, 1.0, v86
	v_rcp_f32_e32 v86, v86
	s_nop 0
	v_mul_f32_e32 v86, v18, v86
	v_add_f32_e32 v117, v86, v86
	v_cmp_nlt_f32_e32 vcc, s43, v117
	s_and_saveexec_b64 s[0:1], vcc
;   DI bf16_t* xc() const { return (bf16_t*)(ws + OFF_Q1); }
;   DI float* cf() const { return (float*)(ws + OFF_CF); }
; DI float bflo(unsigned u) { return __uint_as_float(u << 16); }
; DI float bfhi(unsigned u) { return __uint_as_float(u & 0xffff0000u); }
;   DI void operator()(const f32x16 (&acc)[2][4], int mbase, int nbase, int l32, int g) const {
;     ...
;         const size_t tok = mbase + 32 * mb + l32;
;         const u32x2 xr = *(const u32x2*)(p->xc() + tok * 1024 + ch);
;         const float xv[4] = {bflo(xr.x), bfhi(xr.x), bflo(xr.y), bfhi(xr.y)};
;         f32x4 av, uv;
; #pragma unroll
;         for (int i = 0; i < 4; ++i) {
;           const float gi = __builtin_amdgcn_rcpf(1.f + __expf(-(acc[0][mb][4 * j + i] + bx[i])));
;           const float gr = __builtin_amdgcn_rcpf(1.f + __expf(-(acc[1][mb][4 * j + i] + ba[i])));
;           const float la = cf[i] * gr;
;           const float x2 = 2.f * la;
;           const float ser = -x2 * (1.f + x2 * (0.5f + x2 * (0.16666667f + x2 * (0.041666668f + x2 * 0.0083333333f))));
;           const float m2 = (x2 > -0.3f) ? ser : (1.f - __expf(x2));
;           av[i] = __expf(la);
;           uv[i] = sqrtf(fmaxf(m2, 0.f)) * gi * xv[i];
;         }
;         *(f32x4*)(p->av() + tok * 1024 + ch) = av;
;         *(f32x4*)(p->uv() + tok * 1024 + ch) = uv;
;       }
	s_xor_b64 s[0:1], exec, s[0:1]
	v_mul_f32_e32 v116, 0x3fb8aa3b, v117
	v_exp_f32_e32 v116, v116
	s_nop 0
	v_sub_f32_e32 v116, 1.0, v116
	s_andn2_saveexec_b64 s[0:1], s[0:1]
	v_fmamk_f32 v116, v117, 0x3c088888, v188
	v_fmaak_f32 v116, v117, v116, 0x3e2aaaab
	v_fma_f32 v116, v117, v116, 0.5
	v_fma_f32 v116, v117, v116, 1.0
	v_mul_f32_e64 v116, v116, -v117
	s_or_b64 exec, exec, s[0:1]
	v_add_f32_e32 v87, v87, v35
	v_mul_f32_e32 v87, 0xbfb8aa3b, v87
	v_exp_f32_e32 v87, v87
	s_nop 0
	v_add_f32_e32 v87, 1.0, v87
	v_rcp_f32_e32 v87, v87
	s_nop 0
	v_mul_f32_e32 v87, v19, v87
	v_add_f32_e32 v118, v87, v87
	v_cmp_nlt_f32_e32 vcc, s43, v118
	s_and_saveexec_b64 s[0:1], vcc
	s_xor_b64 s[0:1], exec, s[0:1]
	v_mul_f32_e32 v117, 0x3fb8aa3b, v118
	v_exp_f32_e32 v117, v117
	s_nop 0
	v_sub_f32_e32 v117, 1.0, v117
	s_andn2_saveexec_b64 s[0:1], s[0:1]
	v_fmamk_f32 v117, v118, 0x3c088888, v188
	v_fmaak_f32 v117, v118, v117, 0x3e2aaaab
	v_fma_f32 v117, v118, v117, 0.5
	v_fma_f32 v117, v118, v117, 1.0
	v_mul_f32_e64 v117, v117, -v118
	s_or_b64 exec, exec, s[0:1]
	v_max_f32_e32 v102, v102, v102
	v_add_f32_e32 v68, v68, v0
	v_max_f32_e32 v102, 0, v102
	v_mul_f32_e32 v68, 0xbfb8aa3b, v68
	v_mul_f32_e32 v119, 0x4f800000, v102
	v_cmp_gt_f32_e32 vcc, s44, v102
	v_exp_f32_e32 v68, v68
	v_add_f32_e32 v69, v69, v1
	v_cndmask_b32_e32 v102, v102, v119, vcc
	v_sqrt_f32_e32 v119, v102
	v_add_f32_e32 v68, 1.0, v68
	v_rcp_f32_e32 v162, v68
	v_mul_f32_e32 v68, 0x3fb8aa3b, v84
	v_add_u32_e32 v84, -1, v119
	v_fma_f32 v163, -v84, v119, v102
	v_cmp_ge_f32_e64 s[0:1], 0, v163
	v_add_u32_e32 v163, 1, v119
	v_mul_f32_e32 v69, 0xbfb8aa3b, v69
	v_cndmask_b32_e64 v84, v119, v84, s[0:1]
	v_fma_f32 v119, -v163, v119, v102
	v_exp_f32_e32 v69, v69
	v_cmp_lt_f32_e64 s[0:1], 0, v119
	s_waitcnt vmcnt(2)
	v_mov_b32_e32 v100, v210
	v_mov_b32_e32 v101, v211
	v_lshlrev_b32_e32 v118, 16, v100
	v_add_f32_e32 v70, v70, v2
	v_cndmask_b32_e64 v84, v84, v163, s[0:1]
	v_mul_f32_e32 v119, 0x37800000, v84
	v_cndmask_b32_e32 v84, v84, v119, vcc
	v_cmp_class_f32_e32 vcc, v102, v189
	v_add_f32_e32 v69, 1.0, v69
	v_mul_f32_e32 v70, 0xbfb8aa3b, v70
	v_cndmask_b32_e32 v84, v84, v102, vcc
	v_rcp_f32_e32 v102, v69
	v_max_f32_e32 v69, v103, v103
	v_max_f32_e32 v69, 0, v69
	v_mul_f32_e32 v103, 0x4f800000, v69
	v_cmp_gt_f32_e32 vcc, s44, v69
	v_mul_f32_e32 v84, v162, v84
	v_mul_f32_e32 v84, v84, v118
	v_cndmask_b32_e32 v103, v69, v103, vcc
	v_sqrt_f32_e32 v118, v103
	v_mul_f32_e32 v69, 0x3fb8aa3b, v85
	v_exp_f32_e32 v70, v70
	v_and_b32_e32 v100, 0xffff0000, v100
	v_add_u32_e32 v85, -1, v118
	v_fma_f32 v119, -v85, v118, v103
	v_cmp_ge_f32_e64 s[0:1], 0, v119
	v_add_u32_e32 v119, 1, v118
	v_add_f32_e32 v70, 1.0, v70
	v_cndmask_b32_e64 v85, v118, v85, s[0:1]
	v_fma_f32 v118, -v119, v118, v103
	v_cmp_lt_f32_e64 s[0:1], 0, v118
	v_add_f32_e32 v71, v71, v3
	v_mul_f32_e32 v71, 0xbfb8aa3b, v71
	v_cndmask_b32_e64 v85, v85, v119, s[0:1]
	v_mul_f32_e32 v118, 0x37800000, v85
	v_cndmask_b32_e32 v85, v85, v118, vcc
	v_cmp_class_f32_e32 vcc, v103, v189
	v_exp_f32_e32 v71, v71
	v_exp_f32_e32 v68, v68
	v_cndmask_b32_e32 v85, v85, v103, vcc
	v_mul_f32_e32 v85, v102, v85
	v_mul_f32_e32 v85, v85, v100
	v_rcp_f32_e32 v100, v70
	v_max_f32_e32 v70, v116, v116
	v_max_f32_e32 v70, 0, v70
	v_mul_f32_e32 v102, 0x4f800000, v70
	v_cmp_gt_f32_e32 vcc, s44, v70
	v_add_f32_e32 v71, 1.0, v71
	v_lshlrev_b32_e32 v116, 16, v101
	v_cndmask_b32_e32 v102, v70, v102, vcc
	v_sqrt_f32_e32 v103, v102
	v_mul_f32_e32 v70, 0x3fb8aa3b, v86
	v_exp_f32_e32 v69, v69
	v_exp_f32_e32 v70, v70
	v_add_u32_e32 v86, -1, v103
	v_fma_f32 v118, -v86, v103, v102
	v_cmp_ge_f32_e64 s[0:1], 0, v118
	v_add_u32_e32 v118, 1, v103
	v_and_b32_e32 v101, 0xffff0000, v101
	v_cndmask_b32_e64 v86, v103, v86, s[0:1]
	v_fma_f32 v103, -v118, v103, v102
	v_cmp_lt_f32_e64 s[0:1], 0, v103
	v_add_f32_e32 v52, v52, v32
	v_mul_f32_e32 v52, 0xbfb8aa3b, v52
	v_cndmask_b32_e64 v86, v86, v118, s[0:1]
	v_mul_f32_e32 v103, 0x37800000, v86
	v_cndmask_b32_e32 v86, v86, v103, vcc
	v_cmp_class_f32_e32 vcc, v102, v189
	v_exp_f32_e32 v52, v52
	s_nop 0
	v_cndmask_b32_e32 v86, v86, v102, vcc
	v_mul_f32_e32 v86, v100, v86
	v_rcp_f32_e32 v100, v71
	v_max_f32_e32 v71, v117, v117
	v_max_f32_e32 v71, 0, v71
	v_mul_f32_e32 v102, 0x4f800000, v71
	v_cmp_gt_f32_e32 vcc, s44, v71
	v_mul_f32_e32 v86, v86, v116
	v_add_f32_e32 v52, 1.0, v52
	v_cndmask_b32_e32 v102, v71, v102, vcc
	v_sqrt_f32_e32 v103, v102
	v_mul_f32_e32 v71, 0x3fb8aa3b, v87
	v_exp_f32_e32 v71, v71
	v_rcp_f32_e32 v52, v52
	v_add_u32_e32 v87, -1, v103
	v_fma_f32 v116, -v87, v103, v102
	v_cmp_ge_f32_e64 s[0:1], 0, v116
	v_add_u32_e32 v116, 1, v103
	v_mul_f32_e32 v52, v16, v52
	v_cndmask_b32_e64 v87, v103, v87, s[0:1]
	v_fma_f32 v103, -v116, v103, v102
	v_cmp_lt_f32_e64 s[0:1], 0, v103
	s_nop 1
	v_cndmask_b32_e64 v87, v87, v116, s[0:1]
	v_mul_f32_e32 v103, 0x37800000, v87
	v_cndmask_b32_e32 v87, v87, v103, vcc
	v_cmp_class_f32_e32 vcc, v102, v189
	s_nop 1
	v_cndmask_b32_e32 v87, v87, v102, vcc
	v_mul_f32_e32 v87, v100, v87
	v_mul_f32_e32 v87, v87, v101
	global_load_dwordx2 v[210:211], v[80:81], off offset:16
	global_store_dwordx4 v[64:65], v[68:71], off offset:32
	global_store_dwordx4 v[66:67], v[84:87], off offset:32
	v_add_f32_e32 v71, v52, v52
	v_cmp_nlt_f32_e32 vcc, s43, v71
	s_and_saveexec_b64 s[0:1], vcc
	s_xor_b64 s[0:1], exec, s[0:1]
	v_mul_f32_e32 v70, 0x3fb8aa3b, v71
	v_exp_f32_e32 v70, v70
	s_nop 0
	v_sub_f32_e32 v70, 1.0, v70
	s_andn2_saveexec_b64 s[0:1], s[0:1]
	v_fmamk_f32 v70, v71, 0x3c088888, v188
	v_fmaak_f32 v70, v71, v70, 0x3e2aaaab
	v_fma_f32 v70, v71, v70, 0.5
	v_fma_f32 v70, v71, v70, 1.0
	v_mul_f32_e64 v70, v70, -v71
	s_or_b64 exec, exec, s[0:1]
;   DI bf16_t* xc() const { return (bf16_t*)(ws + OFF_Q1); }
;   DI float* cf() const { return (float*)(ws + OFF_CF); }
; DI float bflo(unsigned u) { return __uint_as_float(u << 16); }
; DI float bfhi(unsigned u) { return __uint_as_float(u & 0xffff0000u); }
;   DI void operator()(const f32x16 (&acc)[2][4], int mbase, int nbase, int l32, int g) const {
;     ...
;         const size_t tok = mbase + 32 * mb + l32;
;         const u32x2 xr = *(const u32x2*)(p->xc() + tok * 1024 + ch);
;         const float xv[4] = {bflo(xr.x), bfhi(xr.x), bflo(xr.y), bfhi(xr.y)};
;         f32x4 av, uv;
; #pragma unroll
;         for (int i = 0; i < 4; ++i) {
;           const float gi = __builtin_amdgcn_rcpf(1.f + __expf(-(acc[0][mb][4 * j + i] + bx[i])));
;           const float gr = __builtin_amdgcn_rcpf(1.f + __expf(-(acc[1][mb][4 * j + i] + ba[i])));
;           const float la = cf[i] * gr;
;           const float x2 = 2.f * la;
;           const float ser = -x2 * (1.f + x2 * (0.5f + x2 * (0.16666667f + x2 * (0.041666668f + x2 * 0.0083333333f))));
;           const float m2 = (x2 > -0.3f) ? ser : (1.f - __expf(x2));
;           av[i] = __expf(la);
;           uv[i] = sqrtf(fmaxf(m2, 0.f)) * gi * xv[i];
	v_add_f32_e32 v53, v53, v33
	v_mul_f32_e32 v53, 0xbfb8aa3b, v53
	v_exp_f32_e32 v53, v53
	s_nop 0
	v_add_f32_e32 v53, 1.0, v53
	v_rcp_f32_e32 v53, v53
	s_nop 0
	v_mul_f32_e32 v53, v17, v53
	v_add_f32_e32 v84, v53, v53
	v_cmp_nlt_f32_e32 vcc, s43, v84
	s_and_saveexec_b64 s[0:1], vcc
	s_xor_b64 s[0:1], exec, s[0:1]
	v_mul_f32_e32 v71, 0x3fb8aa3b, v84
	v_exp_f32_e32 v71, v71
	s_nop 0
	v_sub_f32_e32 v71, 1.0, v71
	s_andn2_saveexec_b64 s[0:1], s[0:1]
	v_fmamk_f32 v71, v84, 0x3c088888, v188
	v_fmaak_f32 v71, v84, v71, 0x3e2aaaab
	v_fma_f32 v71, v84, v71, 0.5
	v_fma_f32 v71, v84, v71, 1.0
	v_mul_f32_e64 v71, v71, -v84
	s_or_b64 exec, exec, s[0:1]
	v_add_f32_e32 v54, v54, v34
	v_mul_f32_e32 v54, 0xbfb8aa3b, v54
	v_exp_f32_e32 v54, v54
	s_nop 0
	v_add_f32_e32 v54, 1.0, v54
	v_rcp_f32_e32 v54, v54
	s_nop 0
	v_mul_f32_e32 v54, v18, v54
	v_add_f32_e32 v85, v54, v54
	v_cmp_nlt_f32_e32 vcc, s43, v85
	s_and_saveexec_b64 s[0:1], vcc
	s_xor_b64 s[0:1], exec, s[0:1]
	v_mul_f32_e32 v84, 0x3fb8aa3b, v85
	v_exp_f32_e32 v84, v84
	s_nop 0
	v_sub_f32_e32 v84, 1.0, v84
	s_andn2_saveexec_b64 s[0:1], s[0:1]
	v_fmamk_f32 v84, v85, 0x3c088888, v188
	v_fmaak_f32 v84, v85, v84, 0x3e2aaaab
	v_fma_f32 v84, v85, v84, 0.5
	v_fma_f32 v84, v85, v84, 1.0
	v_mul_f32_e64 v84, v84, -v85
	s_or_b64 exec, exec, s[0:1]
	v_add_f32_e32 v55, v55, v35
	v_mul_f32_e32 v55, 0xbfb8aa3b, v55
	v_exp_f32_e32 v55, v55
	s_nop 0
	v_add_f32_e32 v55, 1.0, v55
	v_rcp_f32_e32 v55, v55
	s_nop 0
	v_mul_f32_e32 v55, v19, v55
	v_add_f32_e32 v86, v55, v55
	v_cmp_nlt_f32_e32 vcc, s43, v86
	s_and_saveexec_b64 s[0:1], vcc
	s_xor_b64 s[0:1], exec, s[0:1]
	v_mul_f32_e32 v85, 0x3fb8aa3b, v86
	v_exp_f32_e32 v85, v85
	s_nop 0
	v_sub_f32_e32 v85, 1.0, v85
	s_andn2_saveexec_b64 s[0:1], s[0:1]
	v_fmamk_f32 v85, v86, 0x3c088888, v188
	v_fmaak_f32 v85, v86, v85, 0x3e2aaaab
	v_fma_f32 v85, v86, v85, 0.5
	v_fma_f32 v85, v86, v85, 1.0
	v_mul_f32_e64 v85, v85, -v86
	s_or_b64 exec, exec, s[0:1]
	v_max_f32_e32 v70, v70, v70
	v_add_f32_e32 v36, v36, v0
	v_max_f32_e32 v70, 0, v70
	v_mul_f32_e32 v36, 0xbfb8aa3b, v36
	v_mul_f32_e32 v87, 0x4f800000, v70
	v_cmp_gt_f32_e32 vcc, s44, v70
	v_exp_f32_e32 v36, v36
	v_add_f32_e32 v37, v37, v1
	v_cndmask_b32_e32 v70, v70, v87, vcc
	v_sqrt_f32_e32 v87, v70
	v_add_f32_e32 v36, 1.0, v36
	v_rcp_f32_e32 v100, v36
	v_mul_f32_e32 v36, 0x3fb8aa3b, v52
	v_add_u32_e32 v52, -1, v87
	v_fma_f32 v101, -v52, v87, v70
	v_cmp_ge_f32_e64 s[0:1], 0, v101
	v_add_u32_e32 v101, 1, v87
	v_mul_f32_e32 v37, 0xbfb8aa3b, v37
	v_cndmask_b32_e64 v52, v87, v52, s[0:1]
	v_fma_f32 v87, -v101, v87, v70
	v_exp_f32_e32 v37, v37
	v_cmp_lt_f32_e64 s[0:1], 0, v87
	s_waitcnt vmcnt(2)
	v_mov_b32_e32 v68, v210
	v_mov_b32_e32 v69, v211
	v_lshlrev_b32_e32 v86, 16, v68
	v_add_f32_e32 v38, v38, v2
	v_cndmask_b32_e64 v52, v52, v101, s[0:1]
	v_mul_f32_e32 v87, 0x37800000, v52
	v_cndmask_b32_e32 v52, v52, v87, vcc
	v_cmp_class_f32_e32 vcc, v70, v189
	v_add_f32_e32 v37, 1.0, v37
	v_mul_f32_e32 v38, 0xbfb8aa3b, v38
	v_cndmask_b32_e32 v52, v52, v70, vcc
	v_rcp_f32_e32 v70, v37
	v_max_f32_e32 v37, v71, v71
	v_max_f32_e32 v37, 0, v37
	v_mul_f32_e32 v71, 0x4f800000, v37
	v_cmp_gt_f32_e32 vcc, s44, v37
	v_mul_f32_e32 v52, v100, v52
	v_mul_f32_e32 v52, v52, v86
	v_cndmask_b32_e32 v71, v37, v71, vcc
	v_sqrt_f32_e32 v86, v71
	v_mul_f32_e32 v37, 0x3fb8aa3b, v53
	v_exp_f32_e32 v38, v38
	v_and_b32_e32 v68, 0xffff0000, v68
	v_add_u32_e32 v53, -1, v86
	v_fma_f32 v87, -v53, v86, v71
	v_cmp_ge_f32_e64 s[0:1], 0, v87
	v_add_u32_e32 v87, 1, v86
	v_add_f32_e32 v38, 1.0, v38
	v_cndmask_b32_e64 v53, v86, v53, s[0:1]
	v_fma_f32 v86, -v87, v86, v71
	v_cmp_lt_f32_e64 s[0:1], 0, v86
	v_add_f32_e32 v39, v39, v3
	v_mul_f32_e32 v39, 0xbfb8aa3b, v39
	v_cndmask_b32_e64 v53, v53, v87, s[0:1]
	v_mul_f32_e32 v86, 0x37800000, v53
	v_cndmask_b32_e32 v53, v53, v86, vcc
	v_cmp_class_f32_e32 vcc, v71, v189
	v_exp_f32_e32 v39, v39
	v_exp_f32_e32 v36, v36
	v_cndmask_b32_e32 v53, v53, v71, vcc
	v_mul_f32_e32 v53, v70, v53
	v_mul_f32_e32 v53, v53, v68
	v_rcp_f32_e32 v68, v38
	v_max_f32_e32 v38, v84, v84
	v_max_f32_e32 v38, 0, v38
	v_mul_f32_e32 v70, 0x4f800000, v38
	v_cmp_gt_f32_e32 vcc, s44, v38
	v_add_f32_e32 v39, 1.0, v39
	v_lshlrev_b32_e32 v84, 16, v69
	v_cndmask_b32_e32 v70, v38, v70, vcc
	v_sqrt_f32_e32 v71, v70
	v_mul_f32_e32 v38, 0x3fb8aa3b, v54
	v_exp_f32_e32 v37, v37
	v_exp_f32_e32 v38, v38
	v_add_u32_e32 v54, -1, v71
	v_fma_f32 v86, -v54, v71, v70
	v_cmp_ge_f32_e64 s[0:1], 0, v86
	v_add_u32_e32 v86, 1, v71
	v_and_b32_e32 v69, 0xffff0000, v69
	v_cndmask_b32_e64 v54, v71, v54, s[0:1]
	v_fma_f32 v71, -v86, v71, v70
	v_cmp_lt_f32_e64 s[0:1], 0, v71
	v_add_f32_e32 v20, v20, v32
	v_mul_f32_e32 v20, 0xbfb8aa3b, v20
	v_cndmask_b32_e64 v54, v54, v86, s[0:1]
	v_mul_f32_e32 v71, 0x37800000, v54
	v_cndmask_b32_e32 v54, v54, v71, vcc
	v_cmp_class_f32_e32 vcc, v70, v189
	v_exp_f32_e32 v20, v20
	s_nop 0
	v_cndmask_b32_e32 v54, v54, v70, vcc
	v_mul_f32_e32 v54, v68, v54
	v_rcp_f32_e32 v68, v39
	v_max_f32_e32 v39, v85, v85
	v_max_f32_e32 v39, 0, v39
	v_mul_f32_e32 v70, 0x4f800000, v39
	v_cmp_gt_f32_e32 vcc, s44, v39
	v_mul_f32_e32 v54, v54, v84
	v_add_f32_e32 v20, 1.0, v20
	v_cndmask_b32_e32 v70, v39, v70, vcc
	v_sqrt_f32_e32 v71, v70
	v_mul_f32_e32 v39, 0x3fb8aa3b, v55
	v_exp_f32_e32 v39, v39
	v_rcp_f32_e32 v20, v20
	v_add_u32_e32 v55, -1, v71
	v_fma_f32 v84, -v55, v71, v70
	v_cmp_ge_f32_e64 s[0:1], 0, v84
	v_add_u32_e32 v84, 1, v71
	v_mul_f32_e32 v16, v16, v20
	v_cndmask_b32_e64 v55, v71, v55, s[0:1]
	v_fma_f32 v71, -v84, v71, v70
	v_cmp_lt_f32_e64 s[0:1], 0, v71
	v_add_f32_e32 v32, v16, v16
	s_nop 0
	v_cndmask_b32_e64 v55, v55, v84, s[0:1]
	v_mul_f32_e32 v71, 0x37800000, v55
;   DI bf16_t* xc() const { return (bf16_t*)(ws + OFF_Q1); }
;   DI float* cf() const { return (float*)(ws + OFF_CF); }
; DI float bflo(unsigned u) { return __uint_as_float(u << 16); }
; DI float bfhi(unsigned u) { return __uint_as_float(u & 0xffff0000u); }
;   DI void operator()(const f32x16 (&acc)[2][4], int mbase, int nbase, int l32, int g) const {
;     ...
;       const f32x4 bx = *(const f32x4*)(p->gx_b + ch), ba = *(const f32x4*)(p->ga_b + ch), cf = *(const f32x4*)(p->cf() + ch);
; #pragma unroll
;       for (int mb = 0; mb < 4; ++mb) {
;         const size_t tok = mbase + 32 * mb + l32;
;         const u32x2 xr = *(const u32x2*)(p->xc() + tok * 1024 + ch);
;         const float xv[4] = {bflo(xr.x), bfhi(xr.x), bflo(xr.y), bfhi(xr.y)};
;         f32x4 av, uv;
; #pragma unroll
;         for (int i = 0; i < 4; ++i) {
;           const float gi = __builtin_amdgcn_rcpf(1.f + __expf(-(acc[0][mb][4 * j + i] + bx[i])));
;           const float gr = __builtin_amdgcn_rcpf(1.f + __expf(-(acc[1][mb][4 * j + i] + ba[i])));
;           const float la = cf[i] * gr;
;           const float x2 = 2.f * la;
;           const float ser = -x2 * (1.f + x2 * (0.5f + x2 * (0.16666667f + x2 * (0.041666668f + x2 * 0.0083333333f))));
;           const float m2 = (x2 > -0.3f) ? ser : (1.f - __expf(x2));
;           av[i] = __expf(la);
;           uv[i] = sqrtf(fmaxf(m2, 0.f)) * gi * xv[i];
;         }
;         *(f32x4*)(p->av() + tok * 1024 + ch) = av;
;         *(f32x4*)(p->uv() + tok * 1024 + ch) = uv;
;       }
	v_cndmask_b32_e32 v55, v55, v71, vcc
	v_cmp_class_f32_e32 vcc, v70, v189
	s_nop 1
	v_cndmask_b32_e32 v55, v55, v70, vcc
	v_mul_f32_e32 v55, v68, v55
	v_mul_f32_e32 v55, v55, v69
	global_load_dwordx2 v[210:211], v[82:83], off offset:16
	global_store_dwordx4 v[48:49], v[36:39], off offset:32
	global_store_dwordx4 v[50:51], v[52:55], off offset:32
	v_cmp_nlt_f32_e32 vcc, s43, v32
	s_and_saveexec_b64 s[0:1], vcc
	s_xor_b64 s[0:1], exec, s[0:1]
	v_mul_f32_e32 v20, 0x3fb8aa3b, v32
	v_exp_f32_e32 v20, v20
	s_nop 0
	v_sub_f32_e32 v20, 1.0, v20
	s_andn2_saveexec_b64 s[0:1], s[0:1]
	v_fmamk_f32 v20, v32, 0x3c088888, v188
	v_fmaak_f32 v20, v32, v20, 0x3e2aaaab
	v_fma_f32 v20, v32, v20, 0.5
	v_fma_f32 v20, v32, v20, 1.0
	v_mul_f32_e64 v20, v20, -v32
	s_or_b64 exec, exec, s[0:1]
	v_add_f32_e32 v21, v21, v33
	v_mul_f32_e32 v21, 0xbfb8aa3b, v21
	v_exp_f32_e32 v21, v21
	s_nop 0
	v_add_f32_e32 v21, 1.0, v21
	v_rcp_f32_e32 v21, v21
	s_nop 0
	v_mul_f32_e32 v17, v17, v21
	v_add_f32_e32 v32, v17, v17
	v_cmp_nlt_f32_e32 vcc, s43, v32
	s_and_saveexec_b64 s[0:1], vcc
	s_xor_b64 s[0:1], exec, s[0:1]
	v_mul_f32_e32 v21, 0x3fb8aa3b, v32
	v_exp_f32_e32 v21, v21
	s_nop 0
	v_sub_f32_e32 v21, 1.0, v21
	s_andn2_saveexec_b64 s[0:1], s[0:1]
	v_fmamk_f32 v21, v32, 0x3c088888, v188
	v_fmaak_f32 v21, v32, v21, 0x3e2aaaab
	v_fma_f32 v21, v32, v21, 0.5
	v_fma_f32 v21, v32, v21, 1.0
	v_mul_f32_e64 v21, v21, -v32
	s_or_b64 exec, exec, s[0:1]
	v_add_f32_e32 v22, v22, v34
	v_mul_f32_e32 v22, 0xbfb8aa3b, v22
	v_exp_f32_e32 v22, v22
	s_nop 0
	v_add_f32_e32 v22, 1.0, v22
	v_rcp_f32_e32 v22, v22
	s_nop 0
	v_mul_f32_e32 v18, v18, v22
	v_add_f32_e32 v32, v18, v18
	v_cmp_nlt_f32_e32 vcc, s43, v32
	s_and_saveexec_b64 s[0:1], vcc
	s_xor_b64 s[0:1], exec, s[0:1]
	v_mul_f32_e32 v22, 0x3fb8aa3b, v32
	v_exp_f32_e32 v22, v22
	s_nop 0
	v_sub_f32_e32 v22, 1.0, v22
	s_andn2_saveexec_b64 s[0:1], s[0:1]
	v_fmamk_f32 v22, v32, 0x3c088888, v188
	v_fmaak_f32 v22, v32, v22, 0x3e2aaaab
	v_fma_f32 v22, v32, v22, 0.5
	v_fma_f32 v22, v32, v22, 1.0
	v_mul_f32_e64 v22, v22, -v32
	s_or_b64 exec, exec, s[0:1]
	v_add_f32_e32 v23, v23, v35
	v_mul_f32_e32 v23, 0xbfb8aa3b, v23
	v_exp_f32_e32 v23, v23
	s_nop 0
	v_add_f32_e32 v23, 1.0, v23
	v_rcp_f32_e32 v23, v23
	s_nop 0
	v_mul_f32_e32 v19, v19, v23
	v_add_f32_e32 v32, v19, v19
	v_cmp_nlt_f32_e32 vcc, s43, v32
	s_and_saveexec_b64 s[0:1], vcc
	s_xor_b64 s[0:1], exec, s[0:1]
	v_mul_f32_e32 v23, 0x3fb8aa3b, v32
	v_exp_f32_e32 v23, v23
	s_nop 0
	v_sub_f32_e32 v23, 1.0, v23
	s_andn2_saveexec_b64 s[0:1], s[0:1]
	v_fmamk_f32 v23, v32, 0x3c088888, v188
	v_fmaak_f32 v23, v32, v23, 0x3e2aaaab
	v_fma_f32 v23, v32, v23, 0.5
	v_fma_f32 v23, v32, v23, 1.0
	v_mul_f32_e64 v23, v23, -v32
	s_or_b64 exec, exec, s[0:1]
	v_max_f32_e32 v20, v20, v20
	v_add_f32_e32 v0, v4, v0
	v_max_f32_e32 v20, 0, v20
	v_mul_f32_e32 v0, 0xbfb8aa3b, v0
	v_mul_f32_e32 v32, 0x4f800000, v20
	v_cmp_gt_f32_e32 vcc, s44, v20
	v_exp_f32_e32 v0, v0
	v_add_f32_e32 v1, v5, v1
	v_cndmask_b32_e32 v20, v20, v32, vcc
	v_sqrt_f32_e32 v32, v20
	v_add_f32_e32 v0, 1.0, v0
	v_rcp_f32_e32 v33, v0
	v_mul_f32_e32 v0, 0x3fb8aa3b, v16
	v_add_u32_e32 v16, -1, v32
	v_fma_f32 v34, -v16, v32, v20
	v_cmp_ge_f32_e64 s[0:1], 0, v34
	v_add_u32_e32 v34, 1, v32
	v_mul_f32_e32 v1, 0xbfb8aa3b, v1
	v_cndmask_b32_e64 v16, v32, v16, s[0:1]
	v_fma_f32 v32, -v34, v32, v20
	v_cmp_lt_f32_e64 s[0:1], 0, v32
	v_exp_f32_e32 v1, v1
	s_waitcnt vmcnt(2)
	v_mov_b32_e32 v36, v210
	v_mov_b32_e32 v37, v211
	v_lshlrev_b32_e32 v4, 16, v36
	v_cndmask_b32_e64 v16, v16, v34, s[0:1]
	v_mul_f32_e32 v32, 0x37800000, v16
	v_cndmask_b32_e32 v16, v16, v32, vcc
	v_cmp_class_f32_e32 vcc, v20, v189
	v_add_f32_e32 v1, 1.0, v1
	v_add_f32_e32 v2, v6, v2
	v_cndmask_b32_e32 v5, v16, v20, vcc
	v_mul_f32_e32 v5, v33, v5
	v_mul_f32_e32 v4, v5, v4
	v_rcp_f32_e32 v5, v1
	v_max_f32_e32 v1, v21, v21
	v_max_f32_e32 v1, 0, v1
	v_mul_f32_e32 v16, 0x4f800000, v1
	v_cmp_gt_f32_e32 vcc, s44, v1
	v_mul_f32_e32 v2, 0xbfb8aa3b, v2
	v_exp_f32_e32 v2, v2
	v_cndmask_b32_e32 v16, v1, v16, vcc
	v_sqrt_f32_e32 v20, v16
	v_mul_f32_e32 v1, 0x3fb8aa3b, v17
	v_add_f32_e32 v2, 1.0, v2
	v_and_b32_e32 v21, 0xffff0000, v36
	v_add_u32_e32 v17, -1, v20
	v_fma_f32 v32, -v17, v20, v16
	v_cmp_ge_f32_e64 s[0:1], 0, v32
	v_add_u32_e32 v32, 1, v20
	v_add_f32_e32 v3, v7, v3
	v_cndmask_b32_e64 v17, v20, v17, s[0:1]
	v_fma_f32 v20, -v32, v20, v16
	v_cmp_lt_f32_e64 s[0:1], 0, v20
	v_mul_f32_e32 v3, 0xbfb8aa3b, v3
	v_exp_f32_e32 v3, v3
	v_cndmask_b32_e64 v17, v17, v32, s[0:1]
	v_mul_f32_e32 v20, 0x37800000, v17
	v_cndmask_b32_e32 v17, v17, v20, vcc
	v_cmp_class_f32_e32 vcc, v16, v189
	v_add_f32_e32 v3, 1.0, v3
	v_lshlrev_b32_e32 v20, 16, v37
	v_cndmask_b32_e32 v6, v17, v16, vcc
	v_mul_f32_e32 v5, v5, v6
	v_rcp_f32_e32 v6, v2
	v_max_f32_e32 v2, v22, v22
	v_max_f32_e32 v2, 0, v2
	v_mul_f32_e32 v16, 0x4f800000, v2
	v_cmp_gt_f32_e32 vcc, s44, v2
	v_mul_f32_e32 v5, v5, v21
	v_exp_f32_e32 v0, v0
	v_cndmask_b32_e32 v16, v2, v16, vcc
	v_sqrt_f32_e32 v17, v16
	v_mul_f32_e32 v2, 0x3fb8aa3b, v18
	v_exp_f32_e32 v1, v1
	v_exp_f32_e32 v2, v2
	v_add_u32_e32 v18, -1, v17
	v_fma_f32 v21, -v18, v17, v16
	v_cmp_ge_f32_e64 s[0:1], 0, v21
	v_add_u32_e32 v21, 1, v17
	s_nop 0
	v_cndmask_b32_e64 v18, v17, v18, s[0:1]
	v_fma_f32 v17, -v21, v17, v16
	v_cmp_lt_f32_e64 s[0:1], 0, v17
	s_nop 1
	v_cndmask_b32_e64 v17, v18, v21, s[0:1]
	v_mul_f32_e32 v18, 0x37800000, v17
	v_cndmask_b32_e32 v17, v17, v18, vcc
	v_cmp_class_f32_e32 vcc, v16, v189
	v_and_b32_e32 v18, 0xffff0000, v37
	s_nop 0
	v_cndmask_b32_e32 v7, v17, v16, vcc
	v_mul_f32_e32 v6, v6, v7
	v_rcp_f32_e32 v7, v3
	v_max_f32_e32 v3, v23, v23
	v_max_f32_e32 v3, 0, v3
	v_mul_f32_e32 v16, 0x4f800000, v3
	v_cmp_gt_f32_e32 vcc, s44, v3
	v_mul_f32_e32 v6, v6, v20
	s_nop 0
	v_cndmask_b32_e32 v16, v3, v16, vcc
	v_sqrt_f32_e32 v17, v16
	v_mul_f32_e32 v3, 0x3fb8aa3b, v19
	v_exp_f32_e32 v3, v3
	v_add_u32_e32 v19, -1, v17
	v_fma_f32 v20, -v19, v17, v16
	v_cmp_ge_f32_e64 s[0:1], 0, v20
	v_add_u32_e32 v20, 1, v17
	s_nop 0
	v_cndmask_b32_e64 v19, v17, v19, s[0:1]
	v_fma_f32 v17, -v20, v17, v16
	v_cmp_lt_f32_e64 s[0:1], 0, v17
	s_nop 1
	v_cndmask_b32_e64 v17, v19, v20, s[0:1]
	v_mul_f32_e32 v19, 0x37800000, v17
	v_cndmask_b32_e32 v17, v17, v19, vcc
	v_cmp_class_f32_e32 vcc, v16, v189
	s_nop 1
	v_cndmask_b32_e32 v16, v17, v16, vcc
	v_mul_f32_e32 v7, v7, v16
	v_mul_f32_e32 v7, v7, v18
	global_store_dwordx4 v[114:115], v[0:3], off offset:32
	global_store_dwordx4 v[160:161], v[4:7], off offset:32
	global_load_dwordx4 v[16:19], v[174:175], off offset:64
	v_or_b32_e32 v0, 16, v172
	v_ashrrev_i32_e32 v1, 31, v0
	v_lshl_add_u64 v[0:1], v[0:1], 2, s[10:11]
	global_load_dwordx4 v[4:7], v[0:1], off
	s_nop 0
	global_load_dwordx4 v[0:3], v[176:177], off offset:64
	global_load_dwordx2 v[20:21], v[178:179], off offset:32
	s_waitcnt vmcnt(3)
;   DI bf16_t* xc() const { return (bf16_t*)(ws + OFF_Q1); }
;   DI float* cf() const { return (float*)(ws + OFF_CF); }
; DI float bflo(unsigned u) { return __uint_as_float(u << 16); }
; DI float bfhi(unsigned u) { return __uint_as_float(u & 0xffff0000u); }
;   DI void operator()(const f32x16 (&acc)[2][4], int mbase, int nbase, int l32, int g) const {
;     ...
;         const size_t tok = mbase + 32 * mb + l32;
;         const u32x2 xr = *(const u32x2*)(p->xc() + tok * 1024 + ch);
;         const float xv[4] = {bflo(xr.x), bfhi(xr.x), bflo(xr.y), bfhi(xr.y)};
;         f32x4 av, uv;
; #pragma unroll
;         for (int i = 0; i < 4; ++i) {
;           const float gi = __builtin_amdgcn_rcpf(1.f + __expf(-(acc[0][mb][4 * j + i] + bx[i])));
;           const float gr = __builtin_amdgcn_rcpf(1.f + __expf(-(acc[1][mb][4 * j + i] + ba[i])));
;           const float la = cf[i] * gr;
;           const float x2 = 2.f * la;
;           const float ser = -x2 * (1.f + x2 * (0.5f + x2 * (0.16666667f + x2 * (0.041666668f + x2 * 0.0083333333f))));
;           const float m2 = (x2 > -0.3f) ? ser : (1.f - __expf(x2));
;           av[i] = __expf(la);
;           uv[i] = sqrtf(fmaxf(m2, 0.f)) * gi * xv[i];
	v_add_f32_e32 v22, v120, v16
	v_mul_f32_e32 v22, 0xbfb8aa3b, v22
	v_exp_f32_e32 v22, v22
	s_nop 0
	v_add_f32_e32 v22, 1.0, v22
	v_rcp_f32_e32 v22, v22
	s_waitcnt vmcnt(2)
	v_mul_f32_e32 v22, v4, v22
	v_add_f32_e32 v23, v22, v22
	v_cmp_nlt_f32_e32 vcc, s43, v23
	s_and_saveexec_b64 s[0:1], vcc
	s_xor_b64 s[0:1], exec, s[0:1]
	v_mul_f32_e32 v23, 0x3fb8aa3b, v23
	v_exp_f32_e32 v23, v23
	s_nop 0
	v_sub_f32_e32 v34, 1.0, v23
	s_andn2_saveexec_b64 s[0:1], s[0:1]
	v_fmamk_f32 v32, v23, 0x3c088888, v188
	v_fmaak_f32 v32, v23, v32, 0x3e2aaaab
	v_fma_f32 v32, v23, v32, 0.5
	v_fma_f32 v32, v23, v32, 1.0
	v_mul_f32_e64 v34, v32, -v23
	s_or_b64 exec, exec, s[0:1]
	v_add_f32_e32 v23, v121, v17
	v_mul_f32_e32 v23, 0xbfb8aa3b, v23
	v_exp_f32_e32 v23, v23
	s_nop 0
	v_add_f32_e32 v23, 1.0, v23
	v_rcp_f32_e32 v23, v23
	s_nop 0
	v_mul_f32_e32 v23, v5, v23
	v_add_f32_e32 v32, v23, v23
	v_cmp_nlt_f32_e32 vcc, s43, v32
	s_and_saveexec_b64 s[0:1], vcc
	s_xor_b64 s[0:1], exec, s[0:1]
	v_mul_f32_e32 v32, 0x3fb8aa3b, v32
	v_exp_f32_e32 v32, v32
	s_nop 0
	v_sub_f32_e32 v35, 1.0, v32
	s_andn2_saveexec_b64 s[0:1], s[0:1]
	v_fmamk_f32 v33, v32, 0x3c088888, v188
	v_fmaak_f32 v33, v32, v33, 0x3e2aaaab
	v_fma_f32 v33, v32, v33, 0.5
	v_fma_f32 v33, v32, v33, 1.0
	v_mul_f32_e64 v35, v33, -v32
	s_or_b64 exec, exec, s[0:1]
	v_add_f32_e32 v32, v122, v18
	v_mul_f32_e32 v32, 0xbfb8aa3b, v32
	v_exp_f32_e32 v32, v32
	s_nop 0
	v_add_f32_e32 v32, 1.0, v32
	v_rcp_f32_e32 v32, v32
	s_nop 0
	v_mul_f32_e32 v32, v6, v32
	v_add_f32_e32 v33, v32, v32
	v_cmp_nlt_f32_e32 vcc, s43, v33
	s_and_saveexec_b64 s[0:1], vcc
	s_xor_b64 s[0:1], exec, s[0:1]
	v_mul_f32_e32 v33, 0x3fb8aa3b, v33
	v_exp_f32_e32 v33, v33
	s_nop 0
	v_sub_f32_e32 v36, 1.0, v33
	s_andn2_saveexec_b64 s[0:1], s[0:1]
	v_fmamk_f32 v36, v33, 0x3c088888, v188
	v_fmaak_f32 v36, v33, v36, 0x3e2aaaab
	v_fma_f32 v36, v33, v36, 0.5
	v_fma_f32 v36, v33, v36, 1.0
	v_mul_f32_e64 v36, v36, -v33
	s_or_b64 exec, exec, s[0:1]
	v_add_f32_e32 v33, v123, v19
	v_mul_f32_e32 v33, 0xbfb8aa3b, v33
	v_exp_f32_e32 v33, v33
	s_nop 0
	v_add_f32_e32 v33, 1.0, v33
	v_rcp_f32_e32 v33, v33
	s_nop 0
	v_mul_f32_e32 v33, v7, v33
	v_add_f32_e32 v38, v33, v33
	v_cmp_nlt_f32_e32 vcc, s43, v38
	s_and_saveexec_b64 s[0:1], vcc
	s_xor_b64 s[0:1], exec, s[0:1]
	v_mul_f32_e32 v37, 0x3fb8aa3b, v38
	v_exp_f32_e32 v37, v37
	s_nop 0
	v_sub_f32_e32 v37, 1.0, v37
	s_andn2_saveexec_b64 s[0:1], s[0:1]
	v_fmamk_f32 v37, v38, 0x3c088888, v188
	v_fmaak_f32 v37, v38, v37, 0x3e2aaaab
	v_fma_f32 v37, v38, v37, 0.5
	v_fma_f32 v37, v38, v37, 1.0
	v_mul_f32_e64 v37, v37, -v38
	s_or_b64 exec, exec, s[0:1]
	v_max_f32_e32 v34, v34, v34
	v_max_f32_e32 v34, 0, v34
	v_mul_f32_e32 v52, 0x4f800000, v34
	v_cmp_gt_f32_e32 vcc, s44, v34
	s_waitcnt vmcnt(1)
	v_add_f32_e32 v38, v104, v0
	v_mul_f32_e32 v38, 0xbfb8aa3b, v38
	v_cndmask_b32_e32 v52, v34, v52, vcc
	v_sqrt_f32_e32 v53, v52
	v_mul_f32_e32 v22, 0x3fb8aa3b, v22
	v_exp_f32_e32 v38, v38
	v_exp_f32_e32 v34, v22
	v_add_u32_e32 v22, -1, v53
	v_fma_f32 v54, -v22, v53, v52
	v_cmp_ge_f32_e64 s[0:1], 0, v54
	v_add_u32_e32 v54, 1, v53
	v_add_f32_e32 v38, 1.0, v38
	v_cndmask_b32_e64 v22, v53, v22, s[0:1]
	v_fma_f32 v53, -v54, v53, v52
	v_cmp_lt_f32_e64 s[0:1], 0, v53
	v_rcp_f32_e32 v38, v38
	v_max_f32_e32 v35, v35, v35
	v_cndmask_b32_e64 v22, v22, v54, s[0:1]
	v_mul_f32_e32 v53, 0x37800000, v22
	v_cndmask_b32_e32 v22, v22, v53, vcc
	v_cmp_class_f32_e32 vcc, v52, v189
	v_max_f32_e32 v35, 0, v35
	s_waitcnt vmcnt(0)
	v_lshlrev_b32_e32 v39, 16, v20
	v_cndmask_b32_e32 v22, v22, v52, vcc
	v_mul_f32_e32 v22, v38, v22
	v_mul_f32_e32 v38, 0x4f800000, v35
	v_cmp_gt_f32_e32 vcc, s44, v35
	v_add_f32_e32 v53, v105, v1
	v_mul_f32_e32 v53, 0xbfb8aa3b, v53
	v_cndmask_b32_e32 v38, v35, v38, vcc
	v_mul_f32_e32 v52, v22, v39
	v_sqrt_f32_e32 v39, v38
	v_exp_f32_e32 v53, v53
	v_mul_f32_e32 v23, 0x3fb8aa3b, v23
	v_exp_f32_e32 v35, v23
	v_add_u32_e32 v23, -1, v39
	v_add_f32_e32 v22, 1.0, v53
	v_fma_f32 v53, -v23, v39, v38
	v_cmp_ge_f32_e64 s[0:1], 0, v53
	v_add_u32_e32 v53, 1, v39
	v_rcp_f32_e32 v22, v22
	v_cndmask_b32_e64 v23, v39, v23, s[0:1]
	v_fma_f32 v39, -v53, v39, v38
	v_cmp_lt_f32_e64 s[0:1], 0, v39
	v_and_b32_e32 v20, 0xffff0000, v20
	v_mul_f32_e32 v32, 0x3fb8aa3b, v32
	v_cndmask_b32_e64 v23, v23, v53, s[0:1]
	v_mul_f32_e32 v39, 0x37800000, v23
	v_cndmask_b32_e32 v23, v23, v39, vcc
	v_cmp_class_f32_e32 vcc, v38, v189
	v_add_f32_e32 v39, v106, v2
	v_mul_f32_e32 v39, 0xbfb8aa3b, v39
	v_cndmask_b32_e32 v23, v23, v38, vcc
	v_mul_f32_e32 v22, v22, v23
	v_mul_f32_e32 v53, v22, v20
	v_max_f32_e32 v22, v36, v36
	v_max_f32_e32 v22, 0, v22
	v_mul_f32_e32 v23, 0x4f800000, v22
	v_cmp_gt_f32_e32 vcc, s44, v22
	v_exp_f32_e32 v39, v39
	v_exp_f32_e32 v36, v32
	v_cndmask_b32_e32 v22, v22, v23, vcc
	v_sqrt_f32_e32 v23, v22
	v_add_f32_e32 v20, 1.0, v39
	v_rcp_f32_e32 v20, v20
	v_lshlrev_b32_e32 v38, 16, v21
	v_add_u32_e32 v32, -1, v23
	v_fma_f32 v39, -v32, v23, v22
	v_cmp_ge_f32_e64 s[0:1], 0, v39
	v_add_u32_e32 v39, 1, v23
	v_and_b32_e32 v21, 0xffff0000, v21
	v_cndmask_b32_e64 v32, v23, v32, s[0:1]
	v_fma_f32 v23, -v39, v23, v22
	v_cmp_lt_f32_e64 s[0:1], 0, v23
	s_nop 1
	v_cndmask_b32_e64 v23, v32, v39, s[0:1]
	v_mul_f32_e32 v32, 0x37800000, v23
	v_cndmask_b32_e32 v23, v23, v32, vcc
	v_cmp_class_f32_e32 vcc, v22, v189
	v_add_f32_e32 v32, v107, v3
	v_mul_f32_e32 v32, 0xbfb8aa3b, v32
	v_cndmask_b32_e32 v22, v23, v22, vcc
	v_mul_f32_e32 v20, v20, v22
	v_max_f32_e32 v22, v37, v37
	v_max_f32_e32 v22, 0, v22
	v_mul_f32_e32 v23, 0x4f800000, v22
	v_cmp_gt_f32_e32 vcc, s44, v22
	v_exp_f32_e32 v32, v32
	v_mul_f32_e32 v54, v20, v38
	v_cndmask_b32_e32 v22, v22, v23, vcc
	v_sqrt_f32_e32 v23, v22
;   DI bf16_t* xc() const { return (bf16_t*)(ws + OFF_Q1); }
;   DI float* cf() const { return (float*)(ws + OFF_CF); }
; DI float bflo(unsigned u) { return __uint_as_float(u << 16); }
; DI float bfhi(unsigned u) { return __uint_as_float(u & 0xffff0000u); }
;   DI void operator()(const f32x16 (&acc)[2][4], int mbase, int nbase, int l32, int g) const {
;     ...
;         const size_t tok = mbase + 32 * mb + l32;
;         const u32x2 xr = *(const u32x2*)(p->xc() + tok * 1024 + ch);
;         const float xv[4] = {bflo(xr.x), bfhi(xr.x), bflo(xr.y), bfhi(xr.y)};
;         f32x4 av, uv;
; #pragma unroll
;         for (int i = 0; i < 4; ++i) {
;           const float gi = __builtin_amdgcn_rcpf(1.f + __expf(-(acc[0][mb][4 * j + i] + bx[i])));
;           const float gr = __builtin_amdgcn_rcpf(1.f + __expf(-(acc[1][mb][4 * j + i] + ba[i])));
;           const float la = cf[i] * gr;
;           const float x2 = 2.f * la;
;           const float ser = -x2 * (1.f + x2 * (0.5f + x2 * (0.16666667f + x2 * (0.041666668f + x2 * 0.0083333333f))));
;           const float m2 = (x2 > -0.3f) ? ser : (1.f - __expf(x2));
;           av[i] = __expf(la);
;           uv[i] = sqrtf(fmaxf(m2, 0.f)) * gi * xv[i];
;         }
;         *(f32x4*)(p->av() + tok * 1024 + ch) = av;
;         *(f32x4*)(p->uv() + tok * 1024 + ch) = uv;
;       }
	v_add_f32_e32 v20, 1.0, v32
	v_mul_f32_e32 v32, 0x3fb8aa3b, v33
	v_exp_f32_e32 v37, v32
	v_add_u32_e32 v32, -1, v23
	v_fma_f32 v33, -v32, v23, v22
	v_cmp_ge_f32_e64 s[0:1], 0, v33
	v_add_u32_e32 v33, 1, v23
	v_rcp_f32_e32 v20, v20
	v_cndmask_b32_e64 v32, v23, v32, s[0:1]
	v_fma_f32 v23, -v33, v23, v22
	v_cmp_lt_f32_e64 s[0:1], 0, v23
	s_nop 1
	v_cndmask_b32_e64 v23, v32, v33, s[0:1]
	v_mul_f32_e32 v32, 0x37800000, v23
	v_cndmask_b32_e32 v23, v23, v32, vcc
	v_cmp_class_f32_e32 vcc, v22, v189
	s_nop 1
	v_cndmask_b32_e32 v22, v23, v22, vcc
	v_mul_f32_e32 v20, v20, v22
	v_mul_f32_e32 v55, v20, v21
	global_load_dwordx2 v[210:211], v[112:113], off offset:32
	global_store_dwordx4 v[96:97], v[34:37], off offset:64
	global_store_dwordx4 v[98:99], v[52:55], off offset:64
	v_add_f32_e32 v22, v88, v16
	v_mul_f32_e32 v22, 0xbfb8aa3b, v22
	v_exp_f32_e32 v22, v22
	s_nop 0
	v_add_f32_e32 v22, 1.0, v22
	v_rcp_f32_e32 v22, v22
	s_nop 0
	v_mul_f32_e32 v22, v4, v22
	v_add_f32_e32 v23, v22, v22
	v_cmp_nlt_f32_e32 vcc, s43, v23
	s_and_saveexec_b64 s[0:1], vcc
	s_xor_b64 s[0:1], exec, s[0:1]
	v_mul_f32_e32 v23, 0x3fb8aa3b, v23
	v_exp_f32_e32 v23, v23
	s_nop 0
	v_sub_f32_e32 v34, 1.0, v23
	s_andn2_saveexec_b64 s[0:1], s[0:1]
	v_fmamk_f32 v32, v23, 0x3c088888, v188
	v_fmaak_f32 v32, v23, v32, 0x3e2aaaab
	v_fma_f32 v32, v23, v32, 0.5
	v_fma_f32 v32, v23, v32, 1.0
	v_mul_f32_e64 v34, v32, -v23
	s_or_b64 exec, exec, s[0:1]
	v_add_f32_e32 v23, v89, v17
	v_mul_f32_e32 v23, 0xbfb8aa3b, v23
	v_exp_f32_e32 v23, v23
	s_nop 0
	v_add_f32_e32 v23, 1.0, v23
	v_rcp_f32_e32 v23, v23
	s_nop 0
	v_mul_f32_e32 v23, v5, v23
	v_add_f32_e32 v32, v23, v23
	v_cmp_nlt_f32_e32 vcc, s43, v32
	s_and_saveexec_b64 s[0:1], vcc
	s_xor_b64 s[0:1], exec, s[0:1]
	v_mul_f32_e32 v32, 0x3fb8aa3b, v32
	v_exp_f32_e32 v32, v32
	s_nop 0
	v_sub_f32_e32 v35, 1.0, v32
	s_andn2_saveexec_b64 s[0:1], s[0:1]
	v_fmamk_f32 v33, v32, 0x3c088888, v188
	v_fmaak_f32 v33, v32, v33, 0x3e2aaaab
	v_fma_f32 v33, v32, v33, 0.5
	v_fma_f32 v33, v32, v33, 1.0
	v_mul_f32_e64 v35, v33, -v32
	s_or_b64 exec, exec, s[0:1]
	v_add_f32_e32 v32, v90, v18
	v_mul_f32_e32 v32, 0xbfb8aa3b, v32
	v_exp_f32_e32 v32, v32
	s_nop 0
	v_add_f32_e32 v32, 1.0, v32
	v_rcp_f32_e32 v32, v32
	s_nop 0
	v_mul_f32_e32 v32, v6, v32
	v_add_f32_e32 v33, v32, v32
	v_cmp_nlt_f32_e32 vcc, s43, v33
	s_and_saveexec_b64 s[0:1], vcc
	s_xor_b64 s[0:1], exec, s[0:1]
	v_mul_f32_e32 v33, 0x3fb8aa3b, v33
	v_exp_f32_e32 v33, v33
	s_nop 0
	v_sub_f32_e32 v36, 1.0, v33
	s_andn2_saveexec_b64 s[0:1], s[0:1]
	v_fmamk_f32 v36, v33, 0x3c088888, v188
	v_fmaak_f32 v36, v33, v36, 0x3e2aaaab
	v_fma_f32 v36, v33, v36, 0.5
	v_fma_f32 v36, v33, v36, 1.0
	v_mul_f32_e64 v36, v36, -v33
	s_or_b64 exec, exec, s[0:1]
	v_add_f32_e32 v33, v91, v19
	v_mul_f32_e32 v33, 0xbfb8aa3b, v33
	v_exp_f32_e32 v33, v33
	s_nop 0
	v_add_f32_e32 v33, 1.0, v33
	v_rcp_f32_e32 v33, v33
	s_nop 0
	v_mul_f32_e32 v33, v7, v33
	v_add_f32_e32 v38, v33, v33
	v_cmp_nlt_f32_e32 vcc, s43, v38
	s_and_saveexec_b64 s[0:1], vcc
	s_xor_b64 s[0:1], exec, s[0:1]
	v_mul_f32_e32 v37, 0x3fb8aa3b, v38
	v_exp_f32_e32 v37, v37
	s_nop 0
	v_sub_f32_e32 v37, 1.0, v37
	s_andn2_saveexec_b64 s[0:1], s[0:1]
	v_fmamk_f32 v37, v38, 0x3c088888, v188
	v_fmaak_f32 v37, v38, v37, 0x3e2aaaab
	v_fma_f32 v37, v38, v37, 0.5
	v_fma_f32 v37, v38, v37, 1.0
	v_mul_f32_e64 v37, v37, -v38
	s_or_b64 exec, exec, s[0:1]
	v_max_f32_e32 v34, v34, v34
	v_max_f32_e32 v34, 0, v34
	v_mul_f32_e32 v52, 0x4f800000, v34
	v_cmp_gt_f32_e32 vcc, s44, v34
	v_add_f32_e32 v38, v72, v0
	v_mul_f32_e32 v38, 0xbfb8aa3b, v38
	v_cndmask_b32_e32 v52, v34, v52, vcc
	v_sqrt_f32_e32 v53, v52
	v_mul_f32_e32 v22, 0x3fb8aa3b, v22
	v_exp_f32_e32 v38, v38
	v_exp_f32_e32 v34, v22
	v_add_u32_e32 v22, -1, v53
	v_fma_f32 v54, -v22, v53, v52
	v_cmp_ge_f32_e64 s[0:1], 0, v54
	v_add_u32_e32 v54, 1, v53
	v_add_f32_e32 v38, 1.0, v38
	v_cndmask_b32_e64 v22, v53, v22, s[0:1]
	v_fma_f32 v53, -v54, v53, v52
	v_cmp_lt_f32_e64 s[0:1], 0, v53
	v_rcp_f32_e32 v38, v38
	v_max_f32_e32 v35, v35, v35
	v_cndmask_b32_e64 v22, v22, v54, s[0:1]
	v_mul_f32_e32 v53, 0x37800000, v22
	v_cndmask_b32_e32 v22, v22, v53, vcc
	v_cmp_class_f32_e32 vcc, v52, v189
	v_max_f32_e32 v35, 0, v35
	s_waitcnt vmcnt(2)
	v_mov_b32_e32 v20, v210
	v_mov_b32_e32 v21, v211
	v_lshlrev_b32_e32 v39, 16, v20
	v_cndmask_b32_e32 v22, v22, v52, vcc
	v_mul_f32_e32 v22, v38, v22
	v_mul_f32_e32 v38, 0x4f800000, v35
	v_cmp_gt_f32_e32 vcc, s44, v35
	v_add_f32_e32 v53, v73, v1
	v_mul_f32_e32 v53, 0xbfb8aa3b, v53
	v_cndmask_b32_e32 v38, v35, v38, vcc
	v_mul_f32_e32 v52, v22, v39
	v_sqrt_f32_e32 v39, v38
	v_exp_f32_e32 v53, v53
	v_mul_f32_e32 v23, 0x3fb8aa3b, v23
	v_exp_f32_e32 v35, v23
	v_add_u32_e32 v23, -1, v39
	v_add_f32_e32 v22, 1.0, v53
	v_fma_f32 v53, -v23, v39, v38
	v_cmp_ge_f32_e64 s[0:1], 0, v53
	v_add_u32_e32 v53, 1, v39
	v_rcp_f32_e32 v22, v22
	v_cndmask_b32_e64 v23, v39, v23, s[0:1]
	v_fma_f32 v39, -v53, v39, v38
	v_cmp_lt_f32_e64 s[0:1], 0, v39
	v_and_b32_e32 v20, 0xffff0000, v20
	v_mul_f32_e32 v32, 0x3fb8aa3b, v32
	v_cndmask_b32_e64 v23, v23, v53, s[0:1]
	v_mul_f32_e32 v39, 0x37800000, v23
	v_cndmask_b32_e32 v23, v23, v39, vcc
	v_cmp_class_f32_e32 vcc, v38, v189
	v_add_f32_e32 v39, v74, v2
	v_mul_f32_e32 v39, 0xbfb8aa3b, v39
	v_cndmask_b32_e32 v23, v23, v38, vcc
	v_mul_f32_e32 v22, v22, v23
	v_mul_f32_e32 v53, v22, v20
	v_max_f32_e32 v22, v36, v36
	v_max_f32_e32 v22, 0, v22
	v_mul_f32_e32 v23, 0x4f800000, v22
	v_cmp_gt_f32_e32 vcc, s44, v22
	v_exp_f32_e32 v39, v39
	v_exp_f32_e32 v36, v32
	v_cndmask_b32_e32 v22, v22, v23, vcc
	v_sqrt_f32_e32 v23, v22
	v_add_f32_e32 v20, 1.0, v39
	v_rcp_f32_e32 v20, v20
	v_lshlrev_b32_e32 v38, 16, v21
;   DI bf16_t* xc() const { return (bf16_t*)(ws + OFF_Q1); }
;   DI float* cf() const { return (float*)(ws + OFF_CF); }
; DI float bflo(unsigned u) { return __uint_as_float(u << 16); }
; DI float bfhi(unsigned u) { return __uint_as_float(u & 0xffff0000u); }
;   DI void operator()(const f32x16 (&acc)[2][4], int mbase, int nbase, int l32, int g) const {
;     ...
;         const size_t tok = mbase + 32 * mb + l32;
;         const u32x2 xr = *(const u32x2*)(p->xc() + tok * 1024 + ch);
;         const float xv[4] = {bflo(xr.x), bfhi(xr.x), bflo(xr.y), bfhi(xr.y)};
;         f32x4 av, uv;
; #pragma unroll
;         for (int i = 0; i < 4; ++i) {
;           const float gi = __builtin_amdgcn_rcpf(1.f + __expf(-(acc[0][mb][4 * j + i] + bx[i])));
;           const float gr = __builtin_amdgcn_rcpf(1.f + __expf(-(acc[1][mb][4 * j + i] + ba[i])));
;           const float la = cf[i] * gr;
;           const float x2 = 2.f * la;
;           const float ser = -x2 * (1.f + x2 * (0.5f + x2 * (0.16666667f + x2 * (0.041666668f + x2 * 0.0083333333f))));
;           const float m2 = (x2 > -0.3f) ? ser : (1.f - __expf(x2));
;           av[i] = __expf(la);
;           uv[i] = sqrtf(fmaxf(m2, 0.f)) * gi * xv[i];
;         }
;         *(f32x4*)(p->av() + tok * 1024 + ch) = av;
;         *(f32x4*)(p->uv() + tok * 1024 + ch) = uv;
;       }
	v_add_u32_e32 v32, -1, v23
	v_fma_f32 v39, -v32, v23, v22
	v_cmp_ge_f32_e64 s[0:1], 0, v39
	v_add_u32_e32 v39, 1, v23
	v_and_b32_e32 v21, 0xffff0000, v21
	v_cndmask_b32_e64 v32, v23, v32, s[0:1]
	v_fma_f32 v23, -v39, v23, v22
	v_cmp_lt_f32_e64 s[0:1], 0, v23
	s_nop 1
	v_cndmask_b32_e64 v23, v32, v39, s[0:1]
	v_mul_f32_e32 v32, 0x37800000, v23
	v_cndmask_b32_e32 v23, v23, v32, vcc
	v_cmp_class_f32_e32 vcc, v22, v189
	v_add_f32_e32 v32, v75, v3
	v_mul_f32_e32 v32, 0xbfb8aa3b, v32
	v_cndmask_b32_e32 v22, v23, v22, vcc
	v_mul_f32_e32 v20, v20, v22
	v_max_f32_e32 v22, v37, v37
	v_max_f32_e32 v22, 0, v22
	v_mul_f32_e32 v23, 0x4f800000, v22
	v_cmp_gt_f32_e32 vcc, s44, v22
	v_exp_f32_e32 v32, v32
	v_mul_f32_e32 v54, v20, v38
	v_cndmask_b32_e32 v22, v22, v23, vcc
	v_sqrt_f32_e32 v23, v22
	v_add_f32_e32 v20, 1.0, v32
	v_mul_f32_e32 v32, 0x3fb8aa3b, v33
	v_exp_f32_e32 v37, v32
	v_add_u32_e32 v32, -1, v23
	v_fma_f32 v33, -v32, v23, v22
	v_cmp_ge_f32_e64 s[0:1], 0, v33
	v_add_u32_e32 v33, 1, v23
	v_rcp_f32_e32 v20, v20
	v_cndmask_b32_e64 v32, v23, v32, s[0:1]
	v_fma_f32 v23, -v33, v23, v22
	v_cmp_lt_f32_e64 s[0:1], 0, v23
	s_nop 1
	v_cndmask_b32_e64 v23, v32, v33, s[0:1]
	v_mul_f32_e32 v32, 0x37800000, v23
	v_cndmask_b32_e32 v23, v23, v32, vcc
	v_cmp_class_f32_e32 vcc, v22, v189
	s_nop 1
	v_cndmask_b32_e32 v22, v23, v22, vcc
	v_mul_f32_e32 v20, v20, v22
	v_mul_f32_e32 v55, v20, v21
	global_load_dwordx2 v[210:211], v[80:81], off offset:32
	global_store_dwordx4 v[64:65], v[34:37], off offset:64
	global_store_dwordx4 v[66:67], v[52:55], off offset:64
	v_add_f32_e32 v22, v56, v16
	v_mul_f32_e32 v22, 0xbfb8aa3b, v22
	v_exp_f32_e32 v22, v22
	s_nop 0
	v_add_f32_e32 v22, 1.0, v22
	v_rcp_f32_e32 v22, v22
	s_nop 0
	v_mul_f32_e32 v22, v4, v22
	v_add_f32_e32 v23, v22, v22
	v_cmp_nlt_f32_e32 vcc, s43, v23
	s_and_saveexec_b64 s[0:1], vcc
	s_xor_b64 s[0:1], exec, s[0:1]
	v_mul_f32_e32 v23, 0x3fb8aa3b, v23
	v_exp_f32_e32 v23, v23
	s_nop 0
	v_sub_f32_e32 v34, 1.0, v23
	s_andn2_saveexec_b64 s[0:1], s[0:1]
	v_fmamk_f32 v32, v23, 0x3c088888, v188
	v_fmaak_f32 v32, v23, v32, 0x3e2aaaab
	v_fma_f32 v32, v23, v32, 0.5
	v_fma_f32 v32, v23, v32, 1.0
	v_mul_f32_e64 v34, v32, -v23
	s_or_b64 exec, exec, s[0:1]
	v_add_f32_e32 v23, v57, v17
	v_mul_f32_e32 v23, 0xbfb8aa3b, v23
	v_exp_f32_e32 v23, v23
	s_nop 0
	v_add_f32_e32 v23, 1.0, v23
	v_rcp_f32_e32 v23, v23
	s_nop 0
	v_mul_f32_e32 v23, v5, v23
	v_add_f32_e32 v32, v23, v23
	v_cmp_nlt_f32_e32 vcc, s43, v32
	s_and_saveexec_b64 s[0:1], vcc
	s_xor_b64 s[0:1], exec, s[0:1]
	v_mul_f32_e32 v32, 0x3fb8aa3b, v32
	v_exp_f32_e32 v32, v32
	s_nop 0
	v_sub_f32_e32 v35, 1.0, v32
	s_andn2_saveexec_b64 s[0:1], s[0:1]
	v_fmamk_f32 v33, v32, 0x3c088888, v188
	v_fmaak_f32 v33, v32, v33, 0x3e2aaaab
	v_fma_f32 v33, v32, v33, 0.5
	v_fma_f32 v33, v32, v33, 1.0
	v_mul_f32_e64 v35, v33, -v32
	s_or_b64 exec, exec, s[0:1]
	v_add_f32_e32 v32, v58, v18
	v_mul_f32_e32 v32, 0xbfb8aa3b, v32
	v_exp_f32_e32 v32, v32
	s_nop 0
	v_add_f32_e32 v32, 1.0, v32
	v_rcp_f32_e32 v32, v32
	s_nop 0
	v_mul_f32_e32 v32, v6, v32
	v_add_f32_e32 v33, v32, v32
	v_cmp_nlt_f32_e32 vcc, s43, v33
	s_and_saveexec_b64 s[0:1], vcc
	s_xor_b64 s[0:1], exec, s[0:1]
	v_mul_f32_e32 v33, 0x3fb8aa3b, v33
	v_exp_f32_e32 v33, v33
	s_nop 0
	v_sub_f32_e32 v36, 1.0, v33
	s_andn2_saveexec_b64 s[0:1], s[0:1]
	v_fmamk_f32 v36, v33, 0x3c088888, v188
	v_fmaak_f32 v36, v33, v36, 0x3e2aaaab
	v_fma_f32 v36, v33, v36, 0.5
	v_fma_f32 v36, v33, v36, 1.0
	v_mul_f32_e64 v36, v36, -v33
	s_or_b64 exec, exec, s[0:1]
	v_add_f32_e32 v33, v59, v19
	v_mul_f32_e32 v33, 0xbfb8aa3b, v33
	v_exp_f32_e32 v33, v33
	s_nop 0
	v_add_f32_e32 v33, 1.0, v33
	v_rcp_f32_e32 v33, v33
	s_nop 0
	v_mul_f32_e32 v33, v7, v33
	v_add_f32_e32 v38, v33, v33
	v_cmp_nlt_f32_e32 vcc, s43, v38
	s_and_saveexec_b64 s[0:1], vcc
	s_xor_b64 s[0:1], exec, s[0:1]
	v_mul_f32_e32 v37, 0x3fb8aa3b, v38
	v_exp_f32_e32 v37, v37
	s_nop 0
	v_sub_f32_e32 v37, 1.0, v37
	s_andn2_saveexec_b64 s[0:1], s[0:1]
	v_fmamk_f32 v37, v38, 0x3c088888, v188
	v_fmaak_f32 v37, v38, v37, 0x3e2aaaab
	v_fma_f32 v37, v38, v37, 0.5
	v_fma_f32 v37, v38, v37, 1.0
	v_mul_f32_e64 v37, v37, -v38
	s_or_b64 exec, exec, s[0:1]
	v_max_f32_e32 v34, v34, v34
	v_max_f32_e32 v34, 0, v34
	v_add_f32_e32 v38, v40, v0
	v_mul_f32_e32 v40, 0x4f800000, v34
	v_cmp_gt_f32_e32 vcc, s44, v34
	v_mul_f32_e32 v38, 0xbfb8aa3b, v38
	v_mul_f32_e32 v22, 0x3fb8aa3b, v22
	v_cndmask_b32_e32 v40, v34, v40, vcc
	v_sqrt_f32_e32 v52, v40
	v_exp_f32_e32 v38, v38
	v_exp_f32_e32 v34, v22
	v_max_f32_e32 v35, v35, v35
	v_add_u32_e32 v22, -1, v52
	v_fma_f32 v53, -v22, v52, v40
	v_cmp_ge_f32_e64 s[0:1], 0, v53
	v_add_u32_e32 v53, 1, v52
	v_add_f32_e32 v38, 1.0, v38
	v_cndmask_b32_e64 v22, v52, v22, s[0:1]
	v_fma_f32 v52, -v53, v52, v40
	v_cmp_lt_f32_e64 s[0:1], 0, v52
	v_rcp_f32_e32 v38, v38
	s_waitcnt vmcnt(2)
;   DI bf16_t* xc() const { return (bf16_t*)(ws + OFF_Q1); }
;   DI float* cf() const { return (float*)(ws + OFF_CF); }
; DI float bflo(unsigned u) { return __uint_as_float(u << 16); }
; DI float bfhi(unsigned u) { return __uint_as_float(u & 0xffff0000u); }
;   DI void operator()(const f32x16 (&acc)[2][4], int mbase, int nbase, int l32, int g) const {
;     ...
;         const size_t tok = mbase + 32 * mb + l32;
;         const u32x2 xr = *(const u32x2*)(p->xc() + tok * 1024 + ch);
;         const float xv[4] = {bflo(xr.x), bfhi(xr.x), bflo(xr.y), bfhi(xr.y)};
;         f32x4 av, uv;
; #pragma unroll
;         for (int i = 0; i < 4; ++i) {
;           const float gi = __builtin_amdgcn_rcpf(1.f + __expf(-(acc[0][mb][4 * j + i] + bx[i])));
;           const float gr = __builtin_amdgcn_rcpf(1.f + __expf(-(acc[1][mb][4 * j + i] + ba[i])));
;           const float la = cf[i] * gr;
;           const float x2 = 2.f * la;
;           const float ser = -x2 * (1.f + x2 * (0.5f + x2 * (0.16666667f + x2 * (0.041666668f + x2 * 0.0083333333f))));
;           const float m2 = (x2 > -0.3f) ? ser : (1.f - __expf(x2));
;           av[i] = __expf(la);
;           uv[i] = sqrtf(fmaxf(m2, 0.f)) * gi * xv[i];
;         }
;         *(f32x4*)(p->av() + tok * 1024 + ch) = av;
;         *(f32x4*)(p->uv() + tok * 1024 + ch) = uv;
;       }
	v_mov_b32_e32 v20, v210
	v_mov_b32_e32 v21, v211
	v_lshlrev_b32_e32 v39, 16, v20
	v_cndmask_b32_e64 v22, v22, v53, s[0:1]
	v_mul_f32_e32 v52, 0x37800000, v22
	v_cndmask_b32_e32 v22, v22, v52, vcc
	v_cmp_class_f32_e32 vcc, v40, v189
	v_max_f32_e32 v35, 0, v35
	v_add_f32_e32 v41, v41, v1
	v_cndmask_b32_e32 v22, v22, v40, vcc
	v_mul_f32_e32 v22, v38, v22
	v_mul_f32_e32 v38, v22, v39
	v_mul_f32_e32 v39, 0x4f800000, v35
	v_cmp_gt_f32_e32 vcc, s44, v35
	v_mul_f32_e32 v41, 0xbfb8aa3b, v41
	v_exp_f32_e32 v41, v41
	v_cndmask_b32_e32 v39, v35, v39, vcc
	v_sqrt_f32_e32 v40, v39
	v_mul_f32_e32 v23, 0x3fb8aa3b, v23
	v_exp_f32_e32 v35, v23
	v_add_f32_e32 v22, 1.0, v41
	v_add_u32_e32 v23, -1, v40
	v_fma_f32 v41, -v23, v40, v39
	v_cmp_ge_f32_e64 s[0:1], 0, v41
	v_add_u32_e32 v41, 1, v40
	v_rcp_f32_e32 v22, v22
	v_cndmask_b32_e64 v23, v40, v23, s[0:1]
	v_fma_f32 v40, -v41, v40, v39
	v_cmp_lt_f32_e64 s[0:1], 0, v40
	v_and_b32_e32 v20, 0xffff0000, v20
	v_mul_f32_e32 v32, 0x3fb8aa3b, v32
	v_cndmask_b32_e64 v23, v23, v41, s[0:1]
	v_mul_f32_e32 v40, 0x37800000, v23
	v_cndmask_b32_e32 v23, v23, v40, vcc
	v_cmp_class_f32_e32 vcc, v39, v189
	v_add_f32_e32 v40, v42, v2
	v_mul_f32_e32 v40, 0xbfb8aa3b, v40
	v_cndmask_b32_e32 v23, v23, v39, vcc
	v_mul_f32_e32 v22, v22, v23
	v_mul_f32_e32 v39, v22, v20
	v_max_f32_e32 v22, v36, v36
	v_max_f32_e32 v22, 0, v22
	v_mul_f32_e32 v23, 0x4f800000, v22
	v_cmp_gt_f32_e32 vcc, s44, v22
	v_exp_f32_e32 v40, v40
	v_exp_f32_e32 v36, v32
	v_cndmask_b32_e32 v22, v22, v23, vcc
	v_sqrt_f32_e32 v23, v22
	v_add_f32_e32 v20, 1.0, v40
	v_rcp_f32_e32 v20, v20
	v_lshlrev_b32_e32 v40, 16, v21
	v_add_u32_e32 v32, -1, v23
	v_fma_f32 v41, -v32, v23, v22
	v_cmp_ge_f32_e64 s[0:1], 0, v41
	v_add_u32_e32 v41, 1, v23
	v_and_b32_e32 v21, 0xffff0000, v21
	v_cndmask_b32_e64 v32, v23, v32, s[0:1]
	v_fma_f32 v23, -v41, v23, v22
	v_cmp_lt_f32_e64 s[0:1], 0, v23
	v_add_f32_e32 v16, v24, v16
	v_mul_f32_e32 v16, 0xbfb8aa3b, v16
	v_cndmask_b32_e64 v23, v32, v41, s[0:1]
	v_mul_f32_e32 v32, 0x37800000, v23
	v_cndmask_b32_e32 v23, v23, v32, vcc
	v_cmp_class_f32_e32 vcc, v22, v189
	v_add_f32_e32 v32, v43, v3
	v_mul_f32_e32 v32, 0xbfb8aa3b, v32
	v_cndmask_b32_e32 v22, v23, v22, vcc
	v_mul_f32_e32 v20, v20, v22
	v_max_f32_e32 v22, v37, v37
	v_max_f32_e32 v22, 0, v22
	v_mul_f32_e32 v23, 0x4f800000, v22
	v_cmp_gt_f32_e32 vcc, s44, v22
	v_exp_f32_e32 v32, v32
	v_mul_f32_e32 v40, v20, v40
	v_cndmask_b32_e32 v22, v22, v23, vcc
	v_sqrt_f32_e32 v23, v22
	v_add_f32_e32 v20, 1.0, v32
	v_mul_f32_e32 v32, 0x3fb8aa3b, v33
	v_exp_f32_e32 v37, v32
	v_add_u32_e32 v32, -1, v23
	v_fma_f32 v33, -v32, v23, v22
	v_cmp_ge_f32_e64 s[0:1], 0, v33
	v_add_u32_e32 v33, 1, v23
	v_rcp_f32_e32 v20, v20
	v_cndmask_b32_e64 v32, v23, v32, s[0:1]
	v_fma_f32 v23, -v33, v23, v22
	v_cmp_lt_f32_e64 s[0:1], 0, v23
	v_exp_f32_e32 v16, v16
	s_nop 0
	v_cndmask_b32_e64 v23, v32, v33, s[0:1]
	v_mul_f32_e32 v32, 0x37800000, v23
	v_cndmask_b32_e32 v23, v23, v32, vcc
	v_cmp_class_f32_e32 vcc, v22, v189
	v_add_f32_e32 v16, 1.0, v16
	v_rcp_f32_e32 v16, v16
	v_cndmask_b32_e32 v22, v23, v22, vcc
	v_mul_f32_e32 v20, v20, v22
	v_mul_f32_e32 v41, v20, v21
	global_load_dwordx2 v[210:211], v[82:83], off offset:32
	global_store_dwordx4 v[48:49], v[34:37], off offset:64
	global_store_dwordx4 v[50:51], v[38:41], off offset:64
	v_mul_f32_e32 v4, v4, v16
	v_add_f32_e32 v22, v4, v4
	v_cmp_nlt_f32_e32 vcc, s43, v22
	s_and_saveexec_b64 s[0:1], vcc
	s_xor_b64 s[0:1], exec, s[0:1]
	v_mul_f32_e32 v16, 0x3fb8aa3b, v22
	v_exp_f32_e32 v16, v16
	s_nop 0
	v_sub_f32_e32 v16, 1.0, v16
	s_andn2_saveexec_b64 s[0:1], s[0:1]
	v_fmamk_f32 v16, v22, 0x3c088888, v188
	v_fmaak_f32 v16, v22, v16, 0x3e2aaaab
	v_fma_f32 v16, v22, v16, 0.5
	v_fma_f32 v16, v22, v16, 1.0
	v_mul_f32_e64 v16, v16, -v22
	s_or_b64 exec, exec, s[0:1]
	v_add_f32_e32 v17, v25, v17
	v_mul_f32_e32 v17, 0xbfb8aa3b, v17
	v_exp_f32_e32 v17, v17
	s_nop 0
	v_add_f32_e32 v17, 1.0, v17
	v_rcp_f32_e32 v17, v17
	s_nop 0
	v_mul_f32_e32 v5, v5, v17
	v_add_f32_e32 v22, v5, v5
	v_cmp_nlt_f32_e32 vcc, s43, v22
	s_and_saveexec_b64 s[0:1], vcc
	s_xor_b64 s[0:1], exec, s[0:1]
	v_mul_f32_e32 v17, 0x3fb8aa3b, v22
	v_exp_f32_e32 v17, v17
	s_nop 0
	v_sub_f32_e32 v17, 1.0, v17
	s_andn2_saveexec_b64 s[0:1], s[0:1]
	v_fmamk_f32 v17, v22, 0x3c088888, v188
	v_fmaak_f32 v17, v22, v17, 0x3e2aaaab
	v_fma_f32 v17, v22, v17, 0.5
	v_fma_f32 v17, v22, v17, 1.0
	v_mul_f32_e64 v17, v17, -v22
	s_or_b64 exec, exec, s[0:1]
	v_add_f32_e32 v18, v26, v18
	v_mul_f32_e32 v18, 0xbfb8aa3b, v18
	v_exp_f32_e32 v18, v18
	s_nop 0
	v_add_f32_e32 v18, 1.0, v18
	v_rcp_f32_e32 v18, v18
	s_nop 0
	v_mul_f32_e32 v6, v6, v18
	v_add_f32_e32 v22, v6, v6
	v_cmp_nlt_f32_e32 vcc, s43, v22
	s_and_saveexec_b64 s[0:1], vcc
	s_xor_b64 s[0:1], exec, s[0:1]
	v_mul_f32_e32 v18, 0x3fb8aa3b, v22
	v_exp_f32_e32 v18, v18
	s_nop 0
	v_sub_f32_e32 v18, 1.0, v18
	s_andn2_saveexec_b64 s[0:1], s[0:1]
	v_fmamk_f32 v18, v22, 0x3c088888, v188
	v_fmaak_f32 v18, v22, v18, 0x3e2aaaab
	v_fma_f32 v18, v22, v18, 0.5
	v_fma_f32 v18, v22, v18, 1.0
	v_mul_f32_e64 v18, v18, -v22
	s_or_b64 exec, exec, s[0:1]
	v_add_f32_e32 v19, v27, v19
	v_mul_f32_e32 v19, 0xbfb8aa3b, v19
	v_exp_f32_e32 v19, v19
	s_nop 0
	v_add_f32_e32 v19, 1.0, v19
	v_rcp_f32_e32 v19, v19
	s_nop 0
	v_mul_f32_e32 v7, v7, v19
	v_add_f32_e32 v22, v7, v7
	v_cmp_nlt_f32_e32 vcc, s43, v22
	s_and_saveexec_b64 s[0:1], vcc
	s_xor_b64 s[0:1], exec, s[0:1]
	v_mul_f32_e32 v19, 0x3fb8aa3b, v22
	v_exp_f32_e32 v19, v19
	s_nop 0
	v_sub_f32_e32 v19, 1.0, v19
	s_andn2_saveexec_b64 s[0:1], s[0:1]
	v_fmamk_f32 v19, v22, 0x3c088888, v188
	v_fmaak_f32 v19, v22, v19, 0x3e2aaaab
	v_fma_f32 v19, v22, v19, 0.5
	v_fma_f32 v19, v22, v19, 1.0
	v_mul_f32_e64 v19, v19, -v22
	s_or_b64 exec, exec, s[0:1]
	v_max_f32_e32 v16, v16, v16
	v_add_f32_e32 v0, v8, v0
	v_max_f32_e32 v16, 0, v16
	v_mul_f32_e32 v0, 0xbfb8aa3b, v0
	v_mul_f32_e32 v22, 0x4f800000, v16
	v_cmp_gt_f32_e32 vcc, s44, v16
	v_exp_f32_e32 v0, v0
	v_add_f32_e32 v1, v9, v1
	v_cndmask_b32_e32 v16, v16, v22, vcc
	v_sqrt_f32_e32 v22, v16
	v_add_f32_e32 v0, 1.0, v0
	v_rcp_f32_e32 v23, v0
	v_mul_f32_e32 v0, 0x3fb8aa3b, v4
	v_add_u32_e32 v4, -1, v22
	v_fma_f32 v24, -v4, v22, v16
	v_cmp_ge_f32_e64 s[0:1], 0, v24
	v_add_u32_e32 v24, 1, v22
	v_mul_f32_e32 v1, 0xbfb8aa3b, v1
	v_cndmask_b32_e64 v4, v22, v4, s[0:1]
	v_fma_f32 v22, -v24, v22, v16
	v_cmp_lt_f32_e64 s[0:1], 0, v22
	v_exp_f32_e32 v1, v1
	s_waitcnt vmcnt(2)
;   DI bf16_t* xc() const { return (bf16_t*)(ws + OFF_Q1); }
;   DI float* cf() const { return (float*)(ws + OFF_CF); }
; DI float bflo(unsigned u) { return __uint_as_float(u << 16); }
; DI float bfhi(unsigned u) { return __uint_as_float(u & 0xffff0000u); }
;   DI void operator()(const f32x16 (&acc)[2][4], int mbase, int nbase, int l32, int g) const {
;     ...
;       const f32x4 bx = *(const f32x4*)(p->gx_b + ch), ba = *(const f32x4*)(p->ga_b + ch), cf = *(const f32x4*)(p->cf() + ch);
; #pragma unroll
;       for (int mb = 0; mb < 4; ++mb) {
;         const size_t tok = mbase + 32 * mb + l32;
;         const u32x2 xr = *(const u32x2*)(p->xc() + tok * 1024 + ch);
;         const float xv[4] = {bflo(xr.x), bfhi(xr.x), bflo(xr.y), bfhi(xr.y)};
;         f32x4 av, uv;
; #pragma unroll
;         for (int i = 0; i < 4; ++i) {
;           const float gi = __builtin_amdgcn_rcpf(1.f + __expf(-(acc[0][mb][4 * j + i] + bx[i])));
;           const float gr = __builtin_amdgcn_rcpf(1.f + __expf(-(acc[1][mb][4 * j + i] + ba[i])));
;           const float la = cf[i] * gr;
;           const float x2 = 2.f * la;
;           const float ser = -x2 * (1.f + x2 * (0.5f + x2 * (0.16666667f + x2 * (0.041666668f + x2 * 0.0083333333f))));
;           const float m2 = (x2 > -0.3f) ? ser : (1.f - __expf(x2));
;           av[i] = __expf(la);
;           uv[i] = sqrtf(fmaxf(m2, 0.f)) * gi * xv[i];
	v_mov_b32_e32 v20, v210
	v_mov_b32_e32 v21, v211
	v_lshlrev_b32_e32 v8, 16, v20
	v_cndmask_b32_e64 v4, v4, v24, s[0:1]
	v_mul_f32_e32 v22, 0x37800000, v4
	v_cndmask_b32_e32 v4, v4, v22, vcc
	v_cmp_class_f32_e32 vcc, v16, v189
	v_add_f32_e32 v1, 1.0, v1
	v_add_f32_e32 v2, v10, v2
	v_cndmask_b32_e32 v4, v4, v16, vcc
	v_mul_f32_e32 v4, v23, v4
	v_mul_f32_e32 v4, v4, v8
	v_rcp_f32_e32 v8, v1
	v_max_f32_e32 v1, v17, v17
	v_max_f32_e32 v1, 0, v1
	v_mul_f32_e32 v9, 0x4f800000, v1
	v_cmp_gt_f32_e32 vcc, s44, v1
	v_and_b32_e32 v17, 0xffff0000, v20
	v_mul_f32_e32 v2, 0xbfb8aa3b, v2
	v_cndmask_b32_e32 v9, v1, v9, vcc
	v_sqrt_f32_e32 v16, v9
	v_mul_f32_e32 v1, 0x3fb8aa3b, v5
	v_exp_f32_e32 v2, v2
	v_add_f32_e32 v3, v11, v3
	v_add_u32_e32 v5, -1, v16
	v_fma_f32 v20, -v5, v16, v9
	v_cmp_ge_f32_e64 s[0:1], 0, v20
	v_add_u32_e32 v20, 1, v16
	v_add_f32_e32 v2, 1.0, v2
	v_cndmask_b32_e64 v5, v16, v5, s[0:1]
	v_fma_f32 v16, -v20, v16, v9
	v_cmp_lt_f32_e64 s[0:1], 0, v16
	v_mul_f32_e32 v3, 0xbfb8aa3b, v3
	v_exp_f32_e32 v3, v3
	v_cndmask_b32_e64 v5, v5, v20, s[0:1]
	v_mul_f32_e32 v16, 0x37800000, v5
	v_cndmask_b32_e32 v5, v5, v16, vcc
	v_cmp_class_f32_e32 vcc, v9, v189
	v_add_f32_e32 v3, 1.0, v3
	v_lshlrev_b32_e32 v16, 16, v21
	v_cndmask_b32_e32 v5, v5, v9, vcc
	v_mul_f32_e32 v5, v8, v5
	v_rcp_f32_e32 v8, v2
	v_max_f32_e32 v2, v18, v18
	v_max_f32_e32 v2, 0, v2
	v_mul_f32_e32 v9, 0x4f800000, v2
	v_cmp_gt_f32_e32 vcc, s44, v2
	v_mul_f32_e32 v5, v5, v17
	v_exp_f32_e32 v0, v0
	v_cndmask_b32_e32 v9, v2, v9, vcc
	v_sqrt_f32_e32 v10, v9
	v_mul_f32_e32 v2, 0x3fb8aa3b, v6
	v_exp_f32_e32 v1, v1
	v_exp_f32_e32 v2, v2
	v_add_u32_e32 v6, -1, v10
	v_fma_f32 v17, -v6, v10, v9
	v_cmp_ge_f32_e64 s[0:1], 0, v17
	v_add_u32_e32 v17, 1, v10
	v_and_b32_e32 v11, 0xffff0000, v21
	v_cndmask_b32_e64 v6, v10, v6, s[0:1]
	v_fma_f32 v10, -v17, v10, v9
	v_cmp_lt_f32_e64 s[0:1], 0, v10
	s_nop 1
	v_cndmask_b32_e64 v6, v6, v17, s[0:1]
	v_mul_f32_e32 v10, 0x37800000, v6
	v_cndmask_b32_e32 v6, v6, v10, vcc
	v_cmp_class_f32_e32 vcc, v9, v189
	s_nop 1
	v_cndmask_b32_e32 v6, v6, v9, vcc
	v_mul_f32_e32 v6, v8, v6
	v_rcp_f32_e32 v8, v3
	v_max_f32_e32 v3, v19, v19
	v_max_f32_e32 v3, 0, v3
	v_mul_f32_e32 v9, 0x4f800000, v3
	v_cmp_gt_f32_e32 vcc, s44, v3
	v_mul_f32_e32 v6, v6, v16
	s_nop 0
	v_cndmask_b32_e32 v9, v3, v9, vcc
	v_sqrt_f32_e32 v10, v9
	v_mul_f32_e32 v3, 0x3fb8aa3b, v7
	v_exp_f32_e32 v3, v3
	v_add_u32_e32 v7, -1, v10
	v_fma_f32 v16, -v7, v10, v9
	v_cmp_ge_f32_e64 s[0:1], 0, v16
	v_add_u32_e32 v16, 1, v10
	s_nop 0
	v_cndmask_b32_e64 v7, v10, v7, s[0:1]
	v_fma_f32 v10, -v16, v10, v9
	v_cmp_lt_f32_e64 s[0:1], 0, v10
	s_nop 1
	v_cndmask_b32_e64 v7, v7, v16, s[0:1]
	v_mul_f32_e32 v10, 0x37800000, v7
	v_cndmask_b32_e32 v7, v7, v10, vcc
	v_cmp_class_f32_e32 vcc, v9, v189
	s_nop 1
	v_cndmask_b32_e32 v7, v7, v9, vcc
	v_mul_f32_e32 v7, v8, v7
	v_mul_f32_e32 v7, v7, v11
	global_store_dwordx4 v[114:115], v[0:3], off offset:64
	global_store_dwordx4 v[160:161], v[4:7], off offset:64
	global_load_dwordx4 v[8:11], v[174:175], off offset:96
	v_or_b32_e32 v0, 24, v172
	v_ashrrev_i32_e32 v1, 31, v0
	v_lshl_add_u64 v[0:1], v[0:1], 2, s[10:11]
	global_load_dwordx4 v[4:7], v[0:1], off
	s_nop 0
	global_load_dwordx4 v[0:3], v[176:177], off offset:96
	global_load_dwordx2 v[16:17], v[178:179], off offset:48
	s_waitcnt vmcnt(3)
	v_add_f32_e32 v18, v124, v8
	v_mul_f32_e32 v18, 0xbfb8aa3b, v18
	v_exp_f32_e32 v18, v18
	s_nop 0
	v_add_f32_e32 v18, 1.0, v18
	v_rcp_f32_e32 v18, v18
	s_waitcnt vmcnt(2)
	v_mul_f32_e32 v18, v4, v18
	v_add_f32_e32 v19, v18, v18
	v_cmp_nlt_f32_e32 vcc, s43, v19
	s_and_saveexec_b64 s[0:1], vcc
	s_xor_b64 s[0:1], exec, s[0:1]
	v_mul_f32_e32 v19, 0x3fb8aa3b, v19
	v_exp_f32_e32 v19, v19
	s_nop 0
	v_sub_f32_e32 v22, 1.0, v19
	s_andn2_saveexec_b64 s[0:1], s[0:1]
	v_fmamk_f32 v20, v19, 0x3c088888, v188
	v_fmaak_f32 v20, v19, v20, 0x3e2aaaab
	v_fma_f32 v20, v19, v20, 0.5
	v_fma_f32 v20, v19, v20, 1.0
	v_mul_f32_e64 v22, v20, -v19
	s_or_b64 exec, exec, s[0:1]
	v_add_f32_e32 v19, v125, v9
	v_mul_f32_e32 v19, 0xbfb8aa3b, v19
	v_exp_f32_e32 v19, v19
	s_nop 0
	v_add_f32_e32 v19, 1.0, v19
	v_rcp_f32_e32 v19, v19
	s_nop 0
	v_mul_f32_e32 v19, v5, v19
	v_add_f32_e32 v20, v19, v19
	v_cmp_nlt_f32_e32 vcc, s43, v20
	s_and_saveexec_b64 s[0:1], vcc
	s_xor_b64 s[0:1], exec, s[0:1]
	v_mul_f32_e32 v20, 0x3fb8aa3b, v20
	v_exp_f32_e32 v20, v20
	s_nop 0
	v_sub_f32_e32 v23, 1.0, v20
	s_andn2_saveexec_b64 s[0:1], s[0:1]
	v_fmamk_f32 v21, v20, 0x3c088888, v188
	v_fmaak_f32 v21, v20, v21, 0x3e2aaaab
	v_fma_f32 v21, v20, v21, 0.5
	v_fma_f32 v21, v20, v21, 1.0
	v_mul_f32_e64 v23, v21, -v20
	s_or_b64 exec, exec, s[0:1]
	v_add_f32_e32 v20, v126, v10
	v_mul_f32_e32 v20, 0xbfb8aa3b, v20
	v_exp_f32_e32 v20, v20
	s_nop 0
	v_add_f32_e32 v20, 1.0, v20
	v_rcp_f32_e32 v20, v20
	s_nop 0
	v_mul_f32_e32 v20, v6, v20
	v_add_f32_e32 v21, v20, v20
	v_cmp_nlt_f32_e32 vcc, s43, v21
	s_and_saveexec_b64 s[0:1], vcc
	s_xor_b64 s[0:1], exec, s[0:1]
	v_mul_f32_e32 v21, 0x3fb8aa3b, v21
	v_exp_f32_e32 v21, v21
	s_nop 0
	v_sub_f32_e32 v24, 1.0, v21
	s_andn2_saveexec_b64 s[0:1], s[0:1]
	v_fmamk_f32 v24, v21, 0x3c088888, v188
	v_fmaak_f32 v24, v21, v24, 0x3e2aaaab
	v_fma_f32 v24, v21, v24, 0.5
	v_fma_f32 v24, v21, v24, 1.0
	v_mul_f32_e64 v24, v24, -v21
	s_or_b64 exec, exec, s[0:1]
	v_add_f32_e32 v21, v127, v11
	v_mul_f32_e32 v21, 0xbfb8aa3b, v21
	v_exp_f32_e32 v21, v21
	s_nop 0
	v_add_f32_e32 v21, 1.0, v21
	v_rcp_f32_e32 v21, v21
	s_nop 0
	v_mul_f32_e32 v21, v7, v21
	v_add_f32_e32 v26, v21, v21
	v_cmp_nlt_f32_e32 vcc, s43, v26
	s_and_saveexec_b64 s[0:1], vcc
	s_xor_b64 s[0:1], exec, s[0:1]
	v_mul_f32_e32 v25, 0x3fb8aa3b, v26
	v_exp_f32_e32 v25, v25
	s_nop 0
	v_sub_f32_e32 v25, 1.0, v25
	s_andn2_saveexec_b64 s[0:1], s[0:1]
	v_fmamk_f32 v25, v26, 0x3c088888, v188
	v_fmaak_f32 v25, v26, v25, 0x3e2aaaab
	v_fma_f32 v25, v26, v25, 0.5
	v_fma_f32 v25, v26, v25, 1.0
	v_mul_f32_e64 v25, v25, -v26
	s_or_b64 exec, exec, s[0:1]
	v_max_f32_e32 v22, v22, v22
	v_max_f32_e32 v22, 0, v22
	v_mul_f32_e32 v32, 0x4f800000, v22
	v_cmp_gt_f32_e32 vcc, s44, v22
	s_waitcnt vmcnt(1)
;   DI bf16_t* xc() const { return (bf16_t*)(ws + OFF_Q1); }
;   DI float* cf() const { return (float*)(ws + OFF_CF); }
; DI float bflo(unsigned u) { return __uint_as_float(u << 16); }
; DI float bfhi(unsigned u) { return __uint_as_float(u & 0xffff0000u); }
;   DI void operator()(const f32x16 (&acc)[2][4], int mbase, int nbase, int l32, int g) const {
;     ...
;         const size_t tok = mbase + 32 * mb + l32;
;         const u32x2 xr = *(const u32x2*)(p->xc() + tok * 1024 + ch);
;         const float xv[4] = {bflo(xr.x), bfhi(xr.x), bflo(xr.y), bfhi(xr.y)};
;         f32x4 av, uv;
; #pragma unroll
;         for (int i = 0; i < 4; ++i) {
;           const float gi = __builtin_amdgcn_rcpf(1.f + __expf(-(acc[0][mb][4 * j + i] + bx[i])));
;           const float gr = __builtin_amdgcn_rcpf(1.f + __expf(-(acc[1][mb][4 * j + i] + ba[i])));
;           const float la = cf[i] * gr;
;           const float x2 = 2.f * la;
;           const float ser = -x2 * (1.f + x2 * (0.5f + x2 * (0.16666667f + x2 * (0.041666668f + x2 * 0.0083333333f))));
;           const float m2 = (x2 > -0.3f) ? ser : (1.f - __expf(x2));
;           av[i] = __expf(la);
;           uv[i] = sqrtf(fmaxf(m2, 0.f)) * gi * xv[i];
;         }
;         *(f32x4*)(p->av() + tok * 1024 + ch) = av;
;         *(f32x4*)(p->uv() + tok * 1024 + ch) = uv;
;       }
	v_add_f32_e32 v26, v108, v0
	v_mul_f32_e32 v26, 0xbfb8aa3b, v26
	v_cndmask_b32_e32 v22, v22, v32, vcc
	v_sqrt_f32_e32 v32, v22
	v_exp_f32_e32 v26, v26
	v_max_f32_e32 v23, v23, v23
	s_waitcnt vmcnt(0)
	v_lshlrev_b32_e32 v27, 16, v16
	v_add_u32_e32 v33, -1, v32
	v_fma_f32 v34, -v33, v32, v22
	v_cmp_ge_f32_e64 s[0:1], 0, v34
	v_add_u32_e32 v34, 1, v32
	v_add_f32_e32 v26, 1.0, v26
	v_cndmask_b32_e64 v33, v32, v33, s[0:1]
	v_fma_f32 v32, -v34, v32, v22
	v_cmp_lt_f32_e64 s[0:1], 0, v32
	v_rcp_f32_e32 v26, v26
	v_max_f32_e32 v23, 0, v23
	v_cndmask_b32_e64 v32, v33, v34, s[0:1]
	v_mul_f32_e32 v33, 0x37800000, v32
	v_cndmask_b32_e32 v32, v32, v33, vcc
	v_cmp_class_f32_e32 vcc, v22, v189
	v_add_f32_e32 v33, v109, v1
	v_mul_f32_e32 v33, 0xbfb8aa3b, v33
	v_cndmask_b32_e32 v22, v32, v22, vcc
	v_mul_f32_e32 v22, v26, v22
	v_mul_f32_e32 v22, v22, v27
	v_mul_f32_e32 v27, 0x4f800000, v23
	v_cmp_gt_f32_e32 vcc, s44, v23
	v_exp_f32_e32 v33, v33
	v_max_f32_e32 v24, v24, v24
	v_cndmask_b32_e32 v23, v23, v27, vcc
	v_sqrt_f32_e32 v27, v23
	v_add_f32_e32 v26, 1.0, v33
	v_rcp_f32_e32 v26, v26
	v_max_f32_e32 v24, 0, v24
	v_add_u32_e32 v32, -1, v27
	v_fma_f32 v33, -v32, v27, v23
	v_cmp_ge_f32_e64 s[0:1], 0, v33
	v_add_u32_e32 v33, 1, v27
	v_and_b32_e32 v16, 0xffff0000, v16
	v_cndmask_b32_e64 v32, v27, v32, s[0:1]
	v_fma_f32 v27, -v33, v27, v23
	v_cmp_lt_f32_e64 s[0:1], 0, v27
	v_max_f32_e32 v25, v25, v25
	v_max_f32_e32 v25, 0, v25
	v_cndmask_b32_e64 v27, v32, v33, s[0:1]
	v_mul_f32_e32 v32, 0x37800000, v27
	v_cndmask_b32_e32 v27, v27, v32, vcc
	v_cmp_class_f32_e32 vcc, v23, v189
	v_add_f32_e32 v32, v110, v2
	v_mul_f32_e32 v32, 0xbfb8aa3b, v32
	v_cndmask_b32_e32 v23, v27, v23, vcc
	v_mul_f32_e32 v23, v26, v23
	v_mul_f32_e32 v26, 0x4f800000, v24
	v_cmp_gt_f32_e32 vcc, s44, v24
	v_exp_f32_e32 v32, v32
	v_mul_f32_e32 v23, v23, v16
	v_cndmask_b32_e32 v24, v24, v26, vcc
	v_sqrt_f32_e32 v26, v24
	v_add_f32_e32 v16, 1.0, v32
	v_rcp_f32_e32 v16, v16
	v_lshlrev_b32_e32 v27, 16, v17
	v_add_u32_e32 v32, -1, v26
	v_fma_f32 v33, -v32, v26, v24
	v_cmp_ge_f32_e64 s[0:1], 0, v33
	v_add_u32_e32 v33, 1, v26
	v_mul_f32_e32 v18, 0x3fb8aa3b, v18
	v_cndmask_b32_e64 v32, v26, v32, s[0:1]
	v_fma_f32 v26, -v33, v26, v24
	v_cmp_lt_f32_e64 s[0:1], 0, v26
	v_mul_f32_e32 v19, 0x3fb8aa3b, v19
	v_mul_f32_e32 v20, 0x3fb8aa3b, v20
	v_cndmask_b32_e64 v26, v32, v33, s[0:1]
	v_mul_f32_e32 v32, 0x37800000, v26
	v_cndmask_b32_e32 v26, v26, v32, vcc
	v_cmp_class_f32_e32 vcc, v24, v189
	v_add_f32_e32 v32, v111, v3
	v_mul_f32_e32 v32, 0xbfb8aa3b, v32
	v_cndmask_b32_e32 v24, v26, v24, vcc
	v_mul_f32_e32 v26, 0x4f800000, v25
	v_cmp_gt_f32_e32 vcc, s44, v25
	v_exp_f32_e32 v32, v32
	v_mul_f32_e32 v16, v16, v24
	v_cndmask_b32_e32 v25, v25, v26, vcc
	v_sqrt_f32_e32 v26, v25
	v_mul_f32_e32 v24, v16, v27
	v_add_f32_e32 v16, 1.0, v32
	v_rcp_f32_e32 v16, v16
	v_add_u32_e32 v27, -1, v26
	v_fma_f32 v32, -v27, v26, v25
	v_cmp_ge_f32_e64 s[0:1], 0, v32
	v_add_u32_e32 v32, 1, v26
	v_mul_f32_e32 v21, 0x3fb8aa3b, v21
	v_cndmask_b32_e64 v27, v26, v27, s[0:1]
	v_fma_f32 v26, -v32, v26, v25
	v_cmp_lt_f32_e64 s[0:1], 0, v26
	v_exp_f32_e32 v18, v18
	v_exp_f32_e32 v19, v19
	v_cndmask_b32_e64 v26, v27, v32, s[0:1]
	v_exp_f32_e32 v20, v20
	v_exp_f32_e32 v21, v21
	v_mul_f32_e32 v27, 0x37800000, v26
	v_cndmask_b32_e32 v26, v26, v27, vcc
	v_cmp_class_f32_e32 vcc, v25, v189
	v_and_b32_e32 v17, 0xffff0000, v17
	s_nop 0
	v_cndmask_b32_e32 v25, v26, v25, vcc
	v_mul_f32_e32 v16, v16, v25
	v_mul_f32_e32 v25, v16, v17
	global_load_dwordx2 v[210:211], v[112:113], off offset:48
	global_store_dwordx4 v[96:97], v[18:21], off offset:96
	global_store_dwordx4 v[98:99], v[22:25], off offset:96
	v_add_f32_e32 v18, v92, v8
	v_mul_f32_e32 v18, 0xbfb8aa3b, v18
	v_exp_f32_e32 v18, v18
	s_nop 0
	v_add_f32_e32 v18, 1.0, v18
	v_rcp_f32_e32 v18, v18
	s_nop 0
	v_mul_f32_e32 v18, v4, v18
	v_add_f32_e32 v19, v18, v18
	v_cmp_nlt_f32_e32 vcc, s43, v19
	s_and_saveexec_b64 s[0:1], vcc
	s_xor_b64 s[0:1], exec, s[0:1]
	v_mul_f32_e32 v19, 0x3fb8aa3b, v19
	v_exp_f32_e32 v19, v19
	s_nop 0
	v_sub_f32_e32 v22, 1.0, v19
	s_andn2_saveexec_b64 s[0:1], s[0:1]
	v_fmamk_f32 v20, v19, 0x3c088888, v188
	v_fmaak_f32 v20, v19, v20, 0x3e2aaaab
	v_fma_f32 v20, v19, v20, 0.5
	v_fma_f32 v20, v19, v20, 1.0
	v_mul_f32_e64 v22, v20, -v19
	s_or_b64 exec, exec, s[0:1]
	v_add_f32_e32 v19, v93, v9
	v_mul_f32_e32 v19, 0xbfb8aa3b, v19
	v_exp_f32_e32 v19, v19
	s_nop 0
	v_add_f32_e32 v19, 1.0, v19
	v_rcp_f32_e32 v19, v19
	s_nop 0
	v_mul_f32_e32 v19, v5, v19
	v_add_f32_e32 v20, v19, v19
	v_cmp_nlt_f32_e32 vcc, s43, v20
	s_and_saveexec_b64 s[0:1], vcc
	s_xor_b64 s[0:1], exec, s[0:1]
	v_mul_f32_e32 v20, 0x3fb8aa3b, v20
	v_exp_f32_e32 v20, v20
	s_nop 0
	v_sub_f32_e32 v23, 1.0, v20
	s_andn2_saveexec_b64 s[0:1], s[0:1]
	v_fmamk_f32 v21, v20, 0x3c088888, v188
	v_fmaak_f32 v21, v20, v21, 0x3e2aaaab
	v_fma_f32 v21, v20, v21, 0.5
	v_fma_f32 v21, v20, v21, 1.0
	v_mul_f32_e64 v23, v21, -v20
	s_or_b64 exec, exec, s[0:1]
	v_add_f32_e32 v20, v94, v10
	v_mul_f32_e32 v20, 0xbfb8aa3b, v20
	v_exp_f32_e32 v20, v20
	s_nop 0
	v_add_f32_e32 v20, 1.0, v20
	v_rcp_f32_e32 v20, v20
	s_nop 0
	v_mul_f32_e32 v20, v6, v20
	v_add_f32_e32 v21, v20, v20
	v_cmp_nlt_f32_e32 vcc, s43, v21
	s_and_saveexec_b64 s[0:1], vcc
	s_xor_b64 s[0:1], exec, s[0:1]
	v_mul_f32_e32 v21, 0x3fb8aa3b, v21
	v_exp_f32_e32 v21, v21
	s_nop 0
	v_sub_f32_e32 v24, 1.0, v21
	s_andn2_saveexec_b64 s[0:1], s[0:1]
	v_fmamk_f32 v24, v21, 0x3c088888, v188
	v_fmaak_f32 v24, v21, v24, 0x3e2aaaab
	v_fma_f32 v24, v21, v24, 0.5
	v_fma_f32 v24, v21, v24, 1.0
	v_mul_f32_e64 v24, v24, -v21
	s_or_b64 exec, exec, s[0:1]
	v_add_f32_e32 v21, v95, v11
	v_mul_f32_e32 v21, 0xbfb8aa3b, v21
	v_exp_f32_e32 v21, v21
	s_nop 0
	v_add_f32_e32 v21, 1.0, v21
	v_rcp_f32_e32 v21, v21
	s_nop 0
	v_mul_f32_e32 v21, v7, v21
	v_add_f32_e32 v26, v21, v21
	v_cmp_nlt_f32_e32 vcc, s43, v26
	s_and_saveexec_b64 s[0:1], vcc
	s_xor_b64 s[0:1], exec, s[0:1]
	v_mul_f32_e32 v25, 0x3fb8aa3b, v26
	v_exp_f32_e32 v25, v25
	s_nop 0
	v_sub_f32_e32 v25, 1.0, v25
	s_andn2_saveexec_b64 s[0:1], s[0:1]
	v_fmamk_f32 v25, v26, 0x3c088888, v188
	v_fmaak_f32 v25, v26, v25, 0x3e2aaaab
	v_fma_f32 v25, v26, v25, 0.5
	v_fma_f32 v25, v26, v25, 1.0
	v_mul_f32_e64 v25, v25, -v26
	s_or_b64 exec, exec, s[0:1]
	v_max_f32_e32 v22, v22, v22
	v_max_f32_e32 v22, 0, v22
	v_mul_f32_e32 v32, 0x4f800000, v22
	v_cmp_gt_f32_e32 vcc, s44, v22
	v_add_f32_e32 v26, v76, v0
	v_mul_f32_e32 v26, 0xbfb8aa3b, v26
	v_cndmask_b32_e32 v22, v22, v32, vcc
	v_sqrt_f32_e32 v32, v22
	v_exp_f32_e32 v26, v26
	v_max_f32_e32 v23, v23, v23
	s_waitcnt vmcnt(2)
;   DI bf16_t* xc() const { return (bf16_t*)(ws + OFF_Q1); }
;   DI float* cf() const { return (float*)(ws + OFF_CF); }
; DI float bflo(unsigned u) { return __uint_as_float(u << 16); }
; DI float bfhi(unsigned u) { return __uint_as_float(u & 0xffff0000u); }
;   DI void operator()(const f32x16 (&acc)[2][4], int mbase, int nbase, int l32, int g) const {
;     ...
;         const size_t tok = mbase + 32 * mb + l32;
;         const u32x2 xr = *(const u32x2*)(p->xc() + tok * 1024 + ch);
;         const float xv[4] = {bflo(xr.x), bfhi(xr.x), bflo(xr.y), bfhi(xr.y)};
;         f32x4 av, uv;
; #pragma unroll
;         for (int i = 0; i < 4; ++i) {
;           const float gi = __builtin_amdgcn_rcpf(1.f + __expf(-(acc[0][mb][4 * j + i] + bx[i])));
;           const float gr = __builtin_amdgcn_rcpf(1.f + __expf(-(acc[1][mb][4 * j + i] + ba[i])));
;           const float la = cf[i] * gr;
;           const float x2 = 2.f * la;
;           const float ser = -x2 * (1.f + x2 * (0.5f + x2 * (0.16666667f + x2 * (0.041666668f + x2 * 0.0083333333f))));
;           const float m2 = (x2 > -0.3f) ? ser : (1.f - __expf(x2));
;           av[i] = __expf(la);
;           uv[i] = sqrtf(fmaxf(m2, 0.f)) * gi * xv[i];
;         }
;         *(f32x4*)(p->av() + tok * 1024 + ch) = av;
;         *(f32x4*)(p->uv() + tok * 1024 + ch) = uv;
;       }
	v_mov_b32_e32 v16, v210
	v_mov_b32_e32 v17, v211
	v_lshlrev_b32_e32 v27, 16, v16
	v_add_u32_e32 v33, -1, v32
	v_fma_f32 v34, -v33, v32, v22
	v_cmp_ge_f32_e64 s[0:1], 0, v34
	v_add_u32_e32 v34, 1, v32
	v_add_f32_e32 v26, 1.0, v26
	v_cndmask_b32_e64 v33, v32, v33, s[0:1]
	v_fma_f32 v32, -v34, v32, v22
	v_cmp_lt_f32_e64 s[0:1], 0, v32
	v_rcp_f32_e32 v26, v26
	v_max_f32_e32 v23, 0, v23
	v_cndmask_b32_e64 v32, v33, v34, s[0:1]
	v_mul_f32_e32 v33, 0x37800000, v32
	v_cndmask_b32_e32 v32, v32, v33, vcc
	v_cmp_class_f32_e32 vcc, v22, v189
	v_add_f32_e32 v33, v77, v1
	v_mul_f32_e32 v33, 0xbfb8aa3b, v33
	v_cndmask_b32_e32 v22, v32, v22, vcc
	v_mul_f32_e32 v22, v26, v22
	v_mul_f32_e32 v22, v22, v27
	v_mul_f32_e32 v27, 0x4f800000, v23
	v_cmp_gt_f32_e32 vcc, s44, v23
	v_exp_f32_e32 v33, v33
	v_max_f32_e32 v24, v24, v24
	v_cndmask_b32_e32 v23, v23, v27, vcc
	v_sqrt_f32_e32 v27, v23
	v_add_f32_e32 v26, 1.0, v33
	v_rcp_f32_e32 v26, v26
	v_max_f32_e32 v24, 0, v24
	v_add_u32_e32 v32, -1, v27
	v_fma_f32 v33, -v32, v27, v23
	v_cmp_ge_f32_e64 s[0:1], 0, v33
	v_add_u32_e32 v33, 1, v27
	v_and_b32_e32 v16, 0xffff0000, v16
	v_cndmask_b32_e64 v32, v27, v32, s[0:1]
	v_fma_f32 v27, -v33, v27, v23
	v_cmp_lt_f32_e64 s[0:1], 0, v27
	v_max_f32_e32 v25, v25, v25
	v_max_f32_e32 v25, 0, v25
	v_cndmask_b32_e64 v27, v32, v33, s[0:1]
	v_mul_f32_e32 v32, 0x37800000, v27
	v_cndmask_b32_e32 v27, v27, v32, vcc
	v_cmp_class_f32_e32 vcc, v23, v189
	v_add_f32_e32 v32, v78, v2
	v_mul_f32_e32 v32, 0xbfb8aa3b, v32
	v_cndmask_b32_e32 v23, v27, v23, vcc
	v_mul_f32_e32 v23, v26, v23
	v_mul_f32_e32 v26, 0x4f800000, v24
	v_cmp_gt_f32_e32 vcc, s44, v24
	v_exp_f32_e32 v32, v32
	v_mul_f32_e32 v23, v23, v16
	v_cndmask_b32_e32 v24, v24, v26, vcc
	v_sqrt_f32_e32 v26, v24
	v_add_f32_e32 v16, 1.0, v32
	v_rcp_f32_e32 v16, v16
	v_lshlrev_b32_e32 v27, 16, v17
	v_add_u32_e32 v32, -1, v26
	v_fma_f32 v33, -v32, v26, v24
	v_cmp_ge_f32_e64 s[0:1], 0, v33
	v_add_u32_e32 v33, 1, v26
	v_mul_f32_e32 v18, 0x3fb8aa3b, v18
	v_cndmask_b32_e64 v32, v26, v32, s[0:1]
	v_fma_f32 v26, -v33, v26, v24
	v_cmp_lt_f32_e64 s[0:1], 0, v26
	v_mul_f32_e32 v19, 0x3fb8aa3b, v19
	v_mul_f32_e32 v20, 0x3fb8aa3b, v20
	v_cndmask_b32_e64 v26, v32, v33, s[0:1]
	v_mul_f32_e32 v32, 0x37800000, v26
	v_cndmask_b32_e32 v26, v26, v32, vcc
	v_cmp_class_f32_e32 vcc, v24, v189
	v_add_f32_e32 v32, v79, v3
	v_mul_f32_e32 v32, 0xbfb8aa3b, v32
	v_cndmask_b32_e32 v24, v26, v24, vcc
	v_mul_f32_e32 v26, 0x4f800000, v25
	v_cmp_gt_f32_e32 vcc, s44, v25
	v_exp_f32_e32 v32, v32
	v_mul_f32_e32 v16, v16, v24
	v_cndmask_b32_e32 v25, v25, v26, vcc
	v_sqrt_f32_e32 v26, v25
	v_mul_f32_e32 v24, v16, v27
	v_add_f32_e32 v16, 1.0, v32
	v_rcp_f32_e32 v16, v16
	v_add_u32_e32 v27, -1, v26
	v_fma_f32 v32, -v27, v26, v25
	v_cmp_ge_f32_e64 s[0:1], 0, v32
	v_add_u32_e32 v32, 1, v26
	v_mul_f32_e32 v21, 0x3fb8aa3b, v21
	v_cndmask_b32_e64 v27, v26, v27, s[0:1]
	v_fma_f32 v26, -v32, v26, v25
	v_cmp_lt_f32_e64 s[0:1], 0, v26
	v_exp_f32_e32 v18, v18
	v_exp_f32_e32 v19, v19
	v_cndmask_b32_e64 v26, v27, v32, s[0:1]
	v_exp_f32_e32 v20, v20
	v_exp_f32_e32 v21, v21
	v_mul_f32_e32 v27, 0x37800000, v26
	v_cndmask_b32_e32 v26, v26, v27, vcc
	v_cmp_class_f32_e32 vcc, v25, v189
	v_and_b32_e32 v17, 0xffff0000, v17
	s_nop 0
	v_cndmask_b32_e32 v25, v26, v25, vcc
	v_mul_f32_e32 v16, v16, v25
	v_mul_f32_e32 v25, v16, v17
	global_load_dwordx2 v[210:211], v[80:81], off offset:48
	global_store_dwordx4 v[64:65], v[18:21], off offset:96
	global_store_dwordx4 v[66:67], v[22:25], off offset:96
	v_add_f32_e32 v18, v60, v8
	v_mul_f32_e32 v18, 0xbfb8aa3b, v18
	v_exp_f32_e32 v18, v18
	s_nop 0
	v_add_f32_e32 v18, 1.0, v18
	v_rcp_f32_e32 v18, v18
	s_nop 0
	v_mul_f32_e32 v18, v4, v18
	v_add_f32_e32 v19, v18, v18
	v_cmp_nlt_f32_e32 vcc, s43, v19
	s_and_saveexec_b64 s[0:1], vcc
	s_xor_b64 s[0:1], exec, s[0:1]
	v_mul_f32_e32 v19, 0x3fb8aa3b, v19
	v_exp_f32_e32 v19, v19
	s_nop 0
	v_sub_f32_e32 v22, 1.0, v19
	s_andn2_saveexec_b64 s[0:1], s[0:1]
	v_fmamk_f32 v20, v19, 0x3c088888, v188
	v_fmaak_f32 v20, v19, v20, 0x3e2aaaab
	v_fma_f32 v20, v19, v20, 0.5
	v_fma_f32 v20, v19, v20, 1.0
	v_mul_f32_e64 v22, v20, -v19
	s_or_b64 exec, exec, s[0:1]
	v_add_f32_e32 v19, v61, v9
	v_mul_f32_e32 v19, 0xbfb8aa3b, v19
	v_exp_f32_e32 v19, v19
	s_nop 0
	v_add_f32_e32 v19, 1.0, v19
	v_rcp_f32_e32 v19, v19
	s_nop 0
	v_mul_f32_e32 v19, v5, v19
	v_add_f32_e32 v20, v19, v19
	v_cmp_nlt_f32_e32 vcc, s43, v20
	s_and_saveexec_b64 s[0:1], vcc
	s_xor_b64 s[0:1], exec, s[0:1]
	v_mul_f32_e32 v20, 0x3fb8aa3b, v20
	v_exp_f32_e32 v20, v20
	s_nop 0
	v_sub_f32_e32 v23, 1.0, v20
	s_andn2_saveexec_b64 s[0:1], s[0:1]
	v_fmamk_f32 v21, v20, 0x3c088888, v188
	v_fmaak_f32 v21, v20, v21, 0x3e2aaaab
	v_fma_f32 v21, v20, v21, 0.5
	v_fma_f32 v21, v20, v21, 1.0
	v_mul_f32_e64 v23, v21, -v20
	s_or_b64 exec, exec, s[0:1]
	v_add_f32_e32 v20, v62, v10
	v_mul_f32_e32 v20, 0xbfb8aa3b, v20
	v_exp_f32_e32 v20, v20
	s_nop 0
	v_add_f32_e32 v20, 1.0, v20
	v_rcp_f32_e32 v20, v20
	s_nop 0
	v_mul_f32_e32 v20, v6, v20
	v_add_f32_e32 v21, v20, v20
	v_cmp_nlt_f32_e32 vcc, s43, v21
	s_and_saveexec_b64 s[0:1], vcc
	s_xor_b64 s[0:1], exec, s[0:1]
	v_mul_f32_e32 v21, 0x3fb8aa3b, v21
	v_exp_f32_e32 v21, v21
	s_nop 0
	v_sub_f32_e32 v24, 1.0, v21
	s_andn2_saveexec_b64 s[0:1], s[0:1]
	v_fmamk_f32 v24, v21, 0x3c088888, v188
	v_fmaak_f32 v24, v21, v24, 0x3e2aaaab
	v_fma_f32 v24, v21, v24, 0.5
	v_fma_f32 v24, v21, v24, 1.0
	v_mul_f32_e64 v24, v24, -v21
	s_or_b64 exec, exec, s[0:1]
	v_add_f32_e32 v21, v63, v11
	v_mul_f32_e32 v21, 0xbfb8aa3b, v21
	v_exp_f32_e32 v21, v21
	s_nop 0
	v_add_f32_e32 v21, 1.0, v21
	v_rcp_f32_e32 v21, v21
	s_nop 0
	v_mul_f32_e32 v21, v7, v21
	v_add_f32_e32 v26, v21, v21
	v_cmp_nlt_f32_e32 vcc, s43, v26
	s_and_saveexec_b64 s[0:1], vcc
	s_xor_b64 s[0:1], exec, s[0:1]
	v_mul_f32_e32 v25, 0x3fb8aa3b, v26
	v_exp_f32_e32 v25, v25
	s_nop 0
	v_sub_f32_e32 v25, 1.0, v25
	s_andn2_saveexec_b64 s[0:1], s[0:1]
	v_fmamk_f32 v25, v26, 0x3c088888, v188
	v_fmaak_f32 v25, v26, v25, 0x3e2aaaab
	v_fma_f32 v25, v26, v25, 0.5
	v_fma_f32 v25, v26, v25, 1.0
	v_mul_f32_e64 v25, v25, -v26
	s_or_b64 exec, exec, s[0:1]
	v_max_f32_e32 v22, v22, v22
	v_max_f32_e32 v22, 0, v22
	v_mul_f32_e32 v32, 0x4f800000, v22
	v_cmp_gt_f32_e32 vcc, s44, v22
	v_add_f32_e32 v26, v44, v0
	v_mul_f32_e32 v26, 0xbfb8aa3b, v26
	v_cndmask_b32_e32 v22, v22, v32, vcc
	v_sqrt_f32_e32 v32, v22
	v_exp_f32_e32 v26, v26
	v_max_f32_e32 v23, v23, v23
	s_waitcnt vmcnt(2)
;   DI bf16_t* xc() const { return (bf16_t*)(ws + OFF_Q1); }
;   DI float* cf() const { return (float*)(ws + OFF_CF); }
; DI float bflo(unsigned u) { return __uint_as_float(u << 16); }
; DI float bfhi(unsigned u) { return __uint_as_float(u & 0xffff0000u); }
;   DI void operator()(const f32x16 (&acc)[2][4], int mbase, int nbase, int l32, int g) const {
;     ...
;     for (int j = 0; j < 4; ++j) {
;       const int ch = ch0 + 8 * j + 4 * g;
;       const f32x4 bx = *(const f32x4*)(p->gx_b + ch), ba = *(const f32x4*)(p->ga_b + ch), cf = *(const f32x4*)(p->cf() + ch);
; #pragma unroll
;       for (int mb = 0; mb < 4; ++mb) {
;         const size_t tok = mbase + 32 * mb + l32;
;         const u32x2 xr = *(const u32x2*)(p->xc() + tok * 1024 + ch);
;         const float xv[4] = {bflo(xr.x), bfhi(xr.x), bflo(xr.y), bfhi(xr.y)};
;         f32x4 av, uv;
; #pragma unroll
;         for (int i = 0; i < 4; ++i) {
;           const float gi = __builtin_amdgcn_rcpf(1.f + __expf(-(acc[0][mb][4 * j + i] + bx[i])));
;           const float gr = __builtin_amdgcn_rcpf(1.f + __expf(-(acc[1][mb][4 * j + i] + ba[i])));
;           const float la = cf[i] * gr;
;           const float x2 = 2.f * la;
;           const float ser = -x2 * (1.f + x2 * (0.5f + x2 * (0.16666667f + x2 * (0.041666668f + x2 * 0.0083333333f))));
;           const float m2 = (x2 > -0.3f) ? ser : (1.f - __expf(x2));
;           av[i] = __expf(la);
;           uv[i] = sqrtf(fmaxf(m2, 0.f)) * gi * xv[i];
;         }
;         *(f32x4*)(p->av() + tok * 1024 + ch) = av;
;         *(f32x4*)(p->uv() + tok * 1024 + ch) = uv;
;       }
	v_mov_b32_e32 v16, v210
	v_mov_b32_e32 v17, v211
	v_lshlrev_b32_e32 v27, 16, v16
	v_add_u32_e32 v33, -1, v32
	v_fma_f32 v34, -v33, v32, v22
	v_cmp_ge_f32_e64 s[0:1], 0, v34
	v_add_u32_e32 v34, 1, v32
	v_add_f32_e32 v26, 1.0, v26
	v_cndmask_b32_e64 v33, v32, v33, s[0:1]
	v_fma_f32 v32, -v34, v32, v22
	v_cmp_lt_f32_e64 s[0:1], 0, v32
	v_rcp_f32_e32 v26, v26
	v_max_f32_e32 v23, 0, v23
	v_cndmask_b32_e64 v32, v33, v34, s[0:1]
	v_mul_f32_e32 v33, 0x37800000, v32
	v_cndmask_b32_e32 v32, v32, v33, vcc
	v_cmp_class_f32_e32 vcc, v22, v189
	v_add_f32_e32 v33, v45, v1
	v_mul_f32_e32 v33, 0xbfb8aa3b, v33
	v_cndmask_b32_e32 v22, v32, v22, vcc
	v_mul_f32_e32 v22, v26, v22
	v_mul_f32_e32 v22, v22, v27
	v_mul_f32_e32 v27, 0x4f800000, v23
	v_cmp_gt_f32_e32 vcc, s44, v23
	v_exp_f32_e32 v33, v33
	v_max_f32_e32 v24, v24, v24
	v_cndmask_b32_e32 v23, v23, v27, vcc
	v_sqrt_f32_e32 v27, v23
	v_add_f32_e32 v26, 1.0, v33
	v_rcp_f32_e32 v26, v26
	v_max_f32_e32 v24, 0, v24
	v_add_u32_e32 v32, -1, v27
	v_fma_f32 v33, -v32, v27, v23
	v_cmp_ge_f32_e64 s[0:1], 0, v33
	v_add_u32_e32 v33, 1, v27
	v_and_b32_e32 v16, 0xffff0000, v16
	v_cndmask_b32_e64 v32, v27, v32, s[0:1]
	v_fma_f32 v27, -v33, v27, v23
	v_cmp_lt_f32_e64 s[0:1], 0, v27
	v_max_f32_e32 v25, v25, v25
	v_max_f32_e32 v25, 0, v25
	v_cndmask_b32_e64 v27, v32, v33, s[0:1]
	v_mul_f32_e32 v32, 0x37800000, v27
	v_cndmask_b32_e32 v27, v27, v32, vcc
	v_cmp_class_f32_e32 vcc, v23, v189
	v_add_f32_e32 v32, v46, v2
	v_mul_f32_e32 v32, 0xbfb8aa3b, v32
	v_cndmask_b32_e32 v23, v27, v23, vcc
	v_mul_f32_e32 v23, v26, v23
	v_mul_f32_e32 v26, 0x4f800000, v24
	v_cmp_gt_f32_e32 vcc, s44, v24
	v_exp_f32_e32 v32, v32
	v_mul_f32_e32 v23, v23, v16
	v_cndmask_b32_e32 v24, v24, v26, vcc
	v_sqrt_f32_e32 v26, v24
	v_add_f32_e32 v16, 1.0, v32
	v_rcp_f32_e32 v16, v16
	v_lshlrev_b32_e32 v27, 16, v17
	v_add_u32_e32 v32, -1, v26
	v_fma_f32 v33, -v32, v26, v24
	v_cmp_ge_f32_e64 s[0:1], 0, v33
	v_add_u32_e32 v33, 1, v26
	v_mul_f32_e32 v18, 0x3fb8aa3b, v18
	v_cndmask_b32_e64 v32, v26, v32, s[0:1]
	v_fma_f32 v26, -v33, v26, v24
	v_cmp_lt_f32_e64 s[0:1], 0, v26
	v_mul_f32_e32 v19, 0x3fb8aa3b, v19
	v_mul_f32_e32 v20, 0x3fb8aa3b, v20
	v_cndmask_b32_e64 v26, v32, v33, s[0:1]
	v_mul_f32_e32 v32, 0x37800000, v26
	v_cndmask_b32_e32 v26, v26, v32, vcc
	v_cmp_class_f32_e32 vcc, v24, v189
	v_add_f32_e32 v32, v47, v3
	v_mul_f32_e32 v32, 0xbfb8aa3b, v32
	v_cndmask_b32_e32 v24, v26, v24, vcc
	v_mul_f32_e32 v26, 0x4f800000, v25
	v_cmp_gt_f32_e32 vcc, s44, v25
	v_exp_f32_e32 v32, v32
	v_mul_f32_e32 v16, v16, v24
	v_cndmask_b32_e32 v25, v25, v26, vcc
	v_sqrt_f32_e32 v26, v25
	v_mul_f32_e32 v24, v16, v27
	v_add_f32_e32 v16, 1.0, v32
	v_rcp_f32_e32 v16, v16
	v_add_u32_e32 v27, -1, v26
	v_fma_f32 v32, -v27, v26, v25
	v_cmp_ge_f32_e64 s[0:1], 0, v32
	v_add_u32_e32 v32, 1, v26
	v_mul_f32_e32 v21, 0x3fb8aa3b, v21
	v_cndmask_b32_e64 v27, v26, v27, s[0:1]
	v_fma_f32 v26, -v32, v26, v25
	v_cmp_lt_f32_e64 s[0:1], 0, v26
	v_exp_f32_e32 v18, v18
	v_exp_f32_e32 v19, v19
	v_cndmask_b32_e64 v26, v27, v32, s[0:1]
	v_exp_f32_e32 v20, v20
	v_exp_f32_e32 v21, v21
	v_mul_f32_e32 v27, 0x37800000, v26
	v_cndmask_b32_e32 v26, v26, v27, vcc
	v_cmp_class_f32_e32 vcc, v25, v189
	v_and_b32_e32 v17, 0xffff0000, v17
	v_add_f32_e32 v8, v28, v8
	v_cndmask_b32_e32 v25, v26, v25, vcc
	v_mul_f32_e32 v16, v16, v25
	v_mul_f32_e32 v25, v16, v17
	global_store_dwordx4 v[48:49], v[18:21], off offset:96
	global_store_dwordx4 v[50:51], v[22:25], off offset:96
	global_load_dwordx2 v[16:17], v[82:83], off offset:48
	v_mul_f32_e32 v8, 0xbfb8aa3b, v8
	v_exp_f32_e32 v8, v8
	s_nop 0
	v_add_f32_e32 v8, 1.0, v8
	v_rcp_f32_e32 v8, v8
	s_nop 0
	v_mul_f32_e32 v4, v4, v8
	v_add_f32_e32 v18, v4, v4
	v_cmp_nlt_f32_e32 vcc, s43, v18
	s_and_saveexec_b64 s[0:1], vcc
	s_xor_b64 s[0:1], exec, s[0:1]
	v_mul_f32_e32 v8, 0x3fb8aa3b, v18
	v_exp_f32_e32 v8, v8
	s_nop 0
	v_sub_f32_e32 v8, 1.0, v8
	s_andn2_saveexec_b64 s[0:1], s[0:1]
	v_fmamk_f32 v8, v18, 0x3c088888, v188
	v_fmaak_f32 v8, v18, v8, 0x3e2aaaab
	v_fma_f32 v8, v18, v8, 0.5
	v_fma_f32 v8, v18, v8, 1.0
	v_mul_f32_e64 v8, v8, -v18
	s_or_b64 exec, exec, s[0:1]
	v_add_f32_e32 v9, v29, v9
	v_mul_f32_e32 v9, 0xbfb8aa3b, v9
	v_exp_f32_e32 v9, v9
	s_nop 0
	v_add_f32_e32 v9, 1.0, v9
	v_rcp_f32_e32 v9, v9
	s_nop 0
	v_mul_f32_e32 v5, v5, v9
	v_add_f32_e32 v18, v5, v5
	v_cmp_nlt_f32_e32 vcc, s43, v18
	s_and_saveexec_b64 s[0:1], vcc
	s_xor_b64 s[0:1], exec, s[0:1]
	v_mul_f32_e32 v9, 0x3fb8aa3b, v18
	v_exp_f32_e32 v9, v9
	s_nop 0
	v_sub_f32_e32 v9, 1.0, v9
	s_andn2_saveexec_b64 s[0:1], s[0:1]
	v_fmamk_f32 v9, v18, 0x3c088888, v188
	v_fmaak_f32 v9, v18, v9, 0x3e2aaaab
	v_fma_f32 v9, v18, v9, 0.5
	v_fma_f32 v9, v18, v9, 1.0
	v_mul_f32_e64 v9, v9, -v18
	s_or_b64 exec, exec, s[0:1]
	v_add_f32_e32 v10, v30, v10
	v_mul_f32_e32 v10, 0xbfb8aa3b, v10
	v_exp_f32_e32 v10, v10
	s_nop 0
	v_add_f32_e32 v10, 1.0, v10
	v_rcp_f32_e32 v10, v10
	s_nop 0
	v_mul_f32_e32 v6, v6, v10
	v_add_f32_e32 v18, v6, v6
	v_cmp_nlt_f32_e32 vcc, s43, v18
	s_and_saveexec_b64 s[0:1], vcc
	s_xor_b64 s[0:1], exec, s[0:1]
	v_mul_f32_e32 v10, 0x3fb8aa3b, v18
	v_exp_f32_e32 v10, v10
	s_nop 0
	v_sub_f32_e32 v10, 1.0, v10
	s_andn2_saveexec_b64 s[0:1], s[0:1]
	v_fmamk_f32 v10, v18, 0x3c088888, v188
	v_fmaak_f32 v10, v18, v10, 0x3e2aaaab
	v_fma_f32 v10, v18, v10, 0.5
	v_fma_f32 v10, v18, v10, 1.0
	v_mul_f32_e64 v10, v10, -v18
	s_or_b64 exec, exec, s[0:1]
	v_add_f32_e32 v11, v31, v11
	v_mul_f32_e32 v11, 0xbfb8aa3b, v11
	v_exp_f32_e32 v11, v11
	s_nop 0
	v_add_f32_e32 v11, 1.0, v11
	v_rcp_f32_e32 v11, v11
	s_nop 0
	v_mul_f32_e32 v7, v7, v11
	v_add_f32_e32 v18, v7, v7
	v_cmp_nlt_f32_e32 vcc, s43, v18
	s_and_saveexec_b64 s[0:1], vcc
	s_xor_b64 s[0:1], exec, s[0:1]
	v_mul_f32_e32 v11, 0x3fb8aa3b, v18
	v_exp_f32_e32 v11, v11
	s_nop 0
	v_sub_f32_e32 v11, 1.0, v11
	s_andn2_saveexec_b64 s[0:1], s[0:1]
	s_cbranch_execz .LBB0_286
	v_fmamk_f32 v11, v18, 0x3c088888, v188
	v_fmaak_f32 v11, v18, v11, 0x3e2aaaab
	v_fma_f32 v11, v18, v11, 0.5
	v_fma_f32 v11, v18, v11, 1.0
	v_mul_f32_e64 v11, v11, -v18
	s_branch .LBB0_286
